# GEMM k-loops: prefetch loads interleaved among MFMAs right after their stage writes
# speedup vs baseline: 1.3681x; 1.0030x over previous
.LBB0_205:
	ds_read_b128 v[112:115], v237
	ds_read_b128 v[116:119], v237 offset:32
	ds_read_b128 v[120:123], v237 offset:4608
	ds_read_b128 v[124:127], v237 offset:4640
	ds_read_b128 v[130:133], v238 offset:36864
	ds_read_b128 v[134:137], v238 offset:36896
	ds_read_b128 v[138:141], v238 offset:41472
	ds_read_b128 v[142:145], v238 offset:41504
	ds_read_b128 v[146:149], v237 offset:64
	ds_read_b128 v[150:153], v237 offset:96
	ds_read_b128 v[154:157], v237 offset:4672
	ds_read_b128 v[158:161], v237 offset:4704
	ds_read_b128 v[162:165], v238 offset:36928
	ds_read_b128 v[166:169], v238 offset:36960
	ds_read_b128 v[170:173], v238 offset:41536
	ds_read_b128 v[174:177], v238 offset:41568
	s_waitcnt vmcnt(11)
	ds_write_b128 v235, v[64:67] offset:55296
	s_waitcnt vmcnt(10)
	ds_write_b128 v235, v[68:71] offset:64512
	s_waitcnt vmcnt(9)
	ds_write_b128 v239, v[80:83] offset:18432
	s_waitcnt vmcnt(8)
	ds_write_b128 v239, v[84:87] offset:27648
	s_waitcnt vmcnt(7)
	ds_write_b128 v240, v[96:99]
	s_waitcnt vmcnt(6)
	ds_write_b128 v240, v[100:103] offset:9216
	global_load_dwordx4 v[64:67], v[194:195], off offset:384
	global_load_dwordx4 v[68:71], v[198:199], off offset:384
	global_load_dwordx4 v[80:83], v[200:201], off offset:384
	global_load_dwordx4 v[84:87], v[202:203], off offset:384
	global_load_dwordx4 v[96:99], v[196:197], off offset:384
	global_load_dwordx4 v[100:103], v[204:205], off offset:384
	s_waitcnt lgkmcnt(0)
	s_barrier
	v_mfma_f32_32x32x16_bf16 v[48:63], v[112:115], v[130:133], v[48:63]
	v_mfma_f32_32x32x16_bf16 v[32:47], v[112:115], v[138:141], v[32:47]
	s_waitcnt vmcnt(11)
	ds_write_b128 v235, v[72:75]
	v_mfma_f32_32x32x16_bf16 v[16:31], v[120:123], v[130:133], v[16:31]
	global_load_dwordx4 v[72:75], v[194:195], off offset:512
	v_mfma_f32_32x32x16_bf16 v[0:15], v[120:123], v[138:141], v[0:15]
	s_waitcnt vmcnt(11)
	ds_write_b128 v235, v[76:79] offset:9216
	v_mfma_f32_32x32x16_bf16 v[48:63], v[116:119], v[134:137], v[48:63]
	global_load_dwordx4 v[76:79], v[198:199], off offset:512
	v_mfma_f32_32x32x16_bf16 v[32:47], v[116:119], v[142:145], v[32:47]
	s_waitcnt vmcnt(11)
	ds_write_b128 v235, v[88:91] offset:18432
	v_mfma_f32_32x32x16_bf16 v[16:31], v[124:127], v[134:137], v[16:31]
	global_load_dwordx4 v[88:91], v[200:201], off offset:512
	v_mfma_f32_32x32x16_bf16 v[0:15], v[124:127], v[142:145], v[0:15]
	s_waitcnt vmcnt(11)
	ds_write_b128 v235, v[92:95] offset:27648
	v_mfma_f32_32x32x16_bf16 v[48:63], v[146:149], v[162:165], v[48:63]
	global_load_dwordx4 v[92:95], v[202:203], off offset:512
	v_mfma_f32_32x32x16_bf16 v[32:47], v[146:149], v[170:173], v[32:47]
	s_waitcnt vmcnt(11)
	ds_write_b128 v235, v[104:107] offset:36864
	v_mfma_f32_32x32x16_bf16 v[16:31], v[154:157], v[162:165], v[16:31]
	global_load_dwordx4 v[104:107], v[196:197], off offset:512
	v_mfma_f32_32x32x16_bf16 v[0:15], v[154:157], v[170:173], v[0:15]
	s_waitcnt vmcnt(11)
	ds_write_b128 v235, v[108:111] offset:46080
	v_mfma_f32_32x32x16_bf16 v[48:63], v[150:153], v[166:169], v[48:63]
	global_load_dwordx4 v[108:111], v[204:205], off offset:512
	v_mfma_f32_32x32x16_bf16 v[32:47], v[150:153], v[174:177], v[32:47]
	v_mfma_f32_32x32x16_bf16 v[16:31], v[158:161], v[166:169], v[16:31]
	v_mfma_f32_32x32x16_bf16 v[0:15], v[158:161], v[174:177], v[0:15]
	s_waitcnt lgkmcnt(0)
	s_barrier
	ds_read_b128 v[162:165], v237 offset:55296
	ds_read_b128 v[130:133], v237 offset:55328
	ds_read_b128 v[170:173], v241
	ds_read_b128 v[134:137], v241 offset:32
	ds_read_b128 v[166:169], v237 offset:59904
	ds_read_b128 v[142:145], v237 offset:59936
	ds_read_b128 v[174:177], v241 offset:4608
	ds_read_b128 v[150:153], v241 offset:4640
	ds_read_b128 v[138:141], v237 offset:55360
	ds_read_b128 v[116:119], v237 offset:55392
	ds_read_b128 v[146:149], v237 offset:59968
	ds_read_b128 v[112:115], v237 offset:60000
	ds_read_b128 v[154:157], v241 offset:64
	ds_read_b128 v[120:123], v241 offset:96
	ds_read_b128 v[158:161], v241 offset:4672
	ds_read_b128 v[124:127], v241 offset:4704
	s_waitcnt lgkmcnt(0)
	s_barrier
	v_mfma_f32_32x32x16_bf16 v[48:63], v[162:165], v[170:173], v[48:63]
	v_mfma_f32_32x32x16_bf16 v[32:47], v[162:165], v[174:177], v[32:47]
	s_waitcnt vmcnt(11)
	ds_write_b128 v235, v[64:67] offset:55296
	v_mfma_f32_32x32x16_bf16 v[16:31], v[166:169], v[170:173], v[16:31]
	global_load_dwordx4 v[64:67], v[194:195], off offset:640
	v_mfma_f32_32x32x16_bf16 v[0:15], v[166:169], v[174:177], v[0:15]
	s_waitcnt vmcnt(11)
	ds_write_b128 v235, v[68:71] offset:64512
	v_mfma_f32_32x32x16_bf16 v[48:63], v[130:133], v[134:137], v[48:63]
	global_load_dwordx4 v[68:71], v[198:199], off offset:640
	v_mfma_f32_32x32x16_bf16 v[32:47], v[130:133], v[150:153], v[32:47]
	s_waitcnt vmcnt(11)
	ds_write_b128 v239, v[80:83] offset:18432
	v_mfma_f32_32x32x16_bf16 v[16:31], v[142:145], v[134:137], v[16:31]
	global_load_dwordx4 v[80:83], v[200:201], off offset:640
	v_mfma_f32_32x32x16_bf16 v[0:15], v[142:145], v[150:153], v[0:15]
	s_waitcnt vmcnt(11)
	ds_write_b128 v239, v[84:87] offset:27648
	v_mfma_f32_32x32x16_bf16 v[48:63], v[138:141], v[154:157], v[48:63]
	global_load_dwordx4 v[84:87], v[202:203], off offset:640
	v_mfma_f32_32x32x16_bf16 v[32:47], v[138:141], v[158:161], v[32:47]
	s_waitcnt vmcnt(11)
	ds_write_b128 v240, v[96:99]
	v_mfma_f32_32x32x16_bf16 v[16:31], v[146:149], v[154:157], v[16:31]
	global_load_dwordx4 v[96:99], v[196:197], off offset:640
	v_mfma_f32_32x32x16_bf16 v[0:15], v[146:149], v[158:161], v[0:15]
	s_waitcnt vmcnt(11)
	ds_write_b128 v240, v[100:103] offset:9216
	v_mfma_f32_32x32x16_bf16 v[48:63], v[116:119], v[120:123], v[48:63]
	global_load_dwordx4 v[100:103], v[204:205], off offset:640
	v_mfma_f32_32x32x16_bf16 v[32:47], v[116:119], v[124:127], v[32:47]
	v_mfma_f32_32x32x16_bf16 v[16:31], v[112:115], v[120:123], v[16:31]
	v_mfma_f32_32x32x16_bf16 v[0:15], v[112:115], v[124:127], v[0:15]
	s_waitcnt lgkmcnt(0)
	s_barrier
	ds_read_b128 v[112:115], v237
	ds_read_b128 v[116:119], v237 offset:32
	ds_read_b128 v[120:123], v237 offset:4608
	ds_read_b128 v[124:127], v237 offset:4640
	ds_read_b128 v[130:133], v238 offset:36864
	ds_read_b128 v[134:137], v238 offset:36896
	ds_read_b128 v[138:141], v238 offset:41472
	ds_read_b128 v[142:145], v238 offset:41504
	ds_read_b128 v[146:149], v237 offset:64
	ds_read_b128 v[150:153], v237 offset:96
	ds_read_b128 v[154:157], v237 offset:4672
	ds_read_b128 v[158:161], v237 offset:4704
	ds_read_b128 v[162:165], v238 offset:36928
	ds_read_b128 v[166:169], v238 offset:36960
	ds_read_b128 v[170:173], v238 offset:41536
	ds_read_b128 v[174:177], v238 offset:41568
	s_waitcnt lgkmcnt(0)
	s_barrier
	v_mfma_f32_32x32x16_bf16 v[48:63], v[112:115], v[130:133], v[48:63]
	v_mfma_f32_32x32x16_bf16 v[32:47], v[112:115], v[138:141], v[32:47]
	s_waitcnt vmcnt(11)
	ds_write_b128 v235, v[72:75]
	v_mfma_f32_32x32x16_bf16 v[16:31], v[120:123], v[130:133], v[16:31]
	global_load_dwordx4 v[72:75], v[194:195], off offset:768
	v_mfma_f32_32x32x16_bf16 v[0:15], v[120:123], v[138:141], v[0:15]
	s_waitcnt vmcnt(11)
	ds_write_b128 v235, v[76:79] offset:9216
	v_mfma_f32_32x32x16_bf16 v[48:63], v[116:119], v[134:137], v[48:63]
	global_load_dwordx4 v[76:79], v[198:199], off offset:768
	v_mfma_f32_32x32x16_bf16 v[32:47], v[116:119], v[142:145], v[32:47]
	s_waitcnt vmcnt(11)
	ds_write_b128 v235, v[88:91] offset:18432
	v_mfma_f32_32x32x16_bf16 v[16:31], v[124:127], v[134:137], v[16:31]
	global_load_dwordx4 v[88:91], v[200:201], off offset:768
	v_mfma_f32_32x32x16_bf16 v[0:15], v[124:127], v[142:145], v[0:15]
	s_waitcnt vmcnt(11)
	ds_write_b128 v235, v[92:95] offset:27648
	v_mfma_f32_32x32x16_bf16 v[48:63], v[146:149], v[162:165], v[48:63]
	global_load_dwordx4 v[92:95], v[202:203], off offset:768
	v_mfma_f32_32x32x16_bf16 v[32:47], v[146:149], v[170:173], v[32:47]
	s_waitcnt vmcnt(11)
	ds_write_b128 v235, v[104:107] offset:36864
	v_mfma_f32_32x32x16_bf16 v[16:31], v[154:157], v[162:165], v[16:31]
	global_load_dwordx4 v[104:107], v[196:197], off offset:768
	v_mfma_f32_32x32x16_bf16 v[0:15], v[154:157], v[170:173], v[0:15]
	s_waitcnt vmcnt(11)
	ds_write_b128 v235, v[108:111] offset:46080
	v_mfma_f32_32x32x16_bf16 v[48:63], v[150:153], v[166:169], v[48:63]
	global_load_dwordx4 v[108:111], v[204:205], off offset:768
	v_mfma_f32_32x32x16_bf16 v[32:47], v[150:153], v[174:177], v[32:47]
	v_mfma_f32_32x32x16_bf16 v[16:31], v[158:161], v[166:169], v[16:31]
	v_mfma_f32_32x32x16_bf16 v[0:15], v[158:161], v[174:177], v[0:15]
	s_waitcnt lgkmcnt(0)
	s_barrier
	ds_read_b128 v[162:165], v237 offset:55296
	ds_read_b128 v[130:133], v237 offset:55328
	ds_read_b128 v[170:173], v241
	ds_read_b128 v[134:137], v241 offset:32
	ds_read_b128 v[166:169], v237 offset:59904
	ds_read_b128 v[142:145], v237 offset:59936
	ds_read_b128 v[174:177], v241 offset:4608
	ds_read_b128 v[150:153], v241 offset:4640
	ds_read_b128 v[138:141], v237 offset:55360
	ds_read_b128 v[116:119], v237 offset:55392
	ds_read_b128 v[146:149], v237 offset:59968
	ds_read_b128 v[112:115], v237 offset:60000
	ds_read_b128 v[154:157], v241 offset:64
	ds_read_b128 v[120:123], v241 offset:96
	ds_read_b128 v[158:161], v241 offset:4672
	ds_read_b128 v[124:127], v241 offset:4704
	s_waitcnt lgkmcnt(0)
	s_barrier
	v_mfma_f32_32x32x16_bf16 v[48:63], v[162:165], v[170:173], v[48:63]
	v_mfma_f32_32x32x16_bf16 v[32:47], v[162:165], v[174:177], v[32:47]
	s_waitcnt vmcnt(11)
	ds_write_b128 v235, v[64:67] offset:55296
	v_mfma_f32_32x32x16_bf16 v[16:31], v[166:169], v[170:173], v[16:31]
	global_load_dwordx4 v[64:67], v[194:195], off offset:896
	v_mfma_f32_32x32x16_bf16 v[0:15], v[166:169], v[174:177], v[0:15]
	s_waitcnt vmcnt(11)
	ds_write_b128 v235, v[68:71] offset:64512
	v_mfma_f32_32x32x16_bf16 v[48:63], v[130:133], v[134:137], v[48:63]
	global_load_dwordx4 v[68:71], v[198:199], off offset:896
	v_mfma_f32_32x32x16_bf16 v[32:47], v[130:133], v[150:153], v[32:47]
	s_waitcnt vmcnt(11)
	ds_write_b128 v239, v[80:83] offset:18432
	v_mfma_f32_32x32x16_bf16 v[16:31], v[142:145], v[134:137], v[16:31]
	global_load_dwordx4 v[80:83], v[200:201], off offset:896
	v_mfma_f32_32x32x16_bf16 v[0:15], v[142:145], v[150:153], v[0:15]
	s_waitcnt vmcnt(11)
	ds_write_b128 v239, v[84:87] offset:27648
	v_mfma_f32_32x32x16_bf16 v[48:63], v[138:141], v[154:157], v[48:63]
	global_load_dwordx4 v[84:87], v[202:203], off offset:896
	v_mfma_f32_32x32x16_bf16 v[32:47], v[138:141], v[158:161], v[32:47]
	s_waitcnt vmcnt(11)
	ds_write_b128 v240, v[96:99]
	v_mfma_f32_32x32x16_bf16 v[16:31], v[146:149], v[154:157], v[16:31]
	global_load_dwordx4 v[96:99], v[196:197], off offset:896
	v_mfma_f32_32x32x16_bf16 v[0:15], v[146:149], v[158:161], v[0:15]
	s_waitcnt vmcnt(11)
	ds_write_b128 v240, v[100:103] offset:9216
	v_mfma_f32_32x32x16_bf16 v[48:63], v[116:119], v[120:123], v[48:63]
	global_load_dwordx4 v[100:103], v[204:205], off offset:896
	v_mfma_f32_32x32x16_bf16 v[32:47], v[116:119], v[124:127], v[32:47]
	v_mfma_f32_32x32x16_bf16 v[16:31], v[112:115], v[120:123], v[16:31]
	v_mfma_f32_32x32x16_bf16 v[0:15], v[112:115], v[124:127], v[0:15]
	s_waitcnt lgkmcnt(0)
	s_barrier
	ds_read_b128 v[112:115], v237
	ds_read_b128 v[116:119], v237 offset:32
	ds_read_b128 v[120:123], v237 offset:4608
	ds_read_b128 v[124:127], v237 offset:4640
	ds_read_b128 v[130:133], v238 offset:36864
	ds_read_b128 v[134:137], v238 offset:36896
	ds_read_b128 v[138:141], v238 offset:41472
	ds_read_b128 v[142:145], v238 offset:41504
	ds_read_b128 v[146:149], v237 offset:64
	ds_read_b128 v[150:153], v237 offset:96
	ds_read_b128 v[154:157], v237 offset:4672
	ds_read_b128 v[158:161], v237 offset:4704
	ds_read_b128 v[162:165], v238 offset:36928
	ds_read_b128 v[166:169], v238 offset:36960
	ds_read_b128 v[170:173], v238 offset:41536
	ds_read_b128 v[174:177], v238 offset:41568
	s_waitcnt lgkmcnt(0)
	s_barrier
	v_mfma_f32_32x32x16_bf16 v[48:63], v[112:115], v[130:133], v[48:63]
	v_mfma_f32_32x32x16_bf16 v[32:47], v[112:115], v[138:141], v[32:47]
	s_waitcnt vmcnt(11)
	ds_write_b128 v235, v[72:75]
	v_mfma_f32_32x32x16_bf16 v[16:31], v[120:123], v[130:133], v[16:31]
	global_load_dwordx4 v[72:75], v[194:195], off offset:1024
	v_mfma_f32_32x32x16_bf16 v[0:15], v[120:123], v[138:141], v[0:15]
	s_waitcnt vmcnt(11)
	ds_write_b128 v235, v[76:79] offset:9216
	v_mfma_f32_32x32x16_bf16 v[48:63], v[116:119], v[134:137], v[48:63]
	global_load_dwordx4 v[76:79], v[198:199], off offset:1024
	v_mfma_f32_32x32x16_bf16 v[32:47], v[116:119], v[142:145], v[32:47]
	s_waitcnt vmcnt(11)
	ds_write_b128 v235, v[88:91] offset:18432
	v_mfma_f32_32x32x16_bf16 v[16:31], v[124:127], v[134:137], v[16:31]
	global_load_dwordx4 v[88:91], v[200:201], off offset:1024
	v_mfma_f32_32x32x16_bf16 v[0:15], v[124:127], v[142:145], v[0:15]
	s_waitcnt vmcnt(11)
	ds_write_b128 v235, v[92:95] offset:27648
	v_mfma_f32_32x32x16_bf16 v[48:63], v[146:149], v[162:165], v[48:63]
	global_load_dwordx4 v[92:95], v[202:203], off offset:1024
	v_mfma_f32_32x32x16_bf16 v[32:47], v[146:149], v[170:173], v[32:47]
	s_waitcnt vmcnt(11)
	ds_write_b128 v235, v[104:107] offset:36864
	v_mfma_f32_32x32x16_bf16 v[16:31], v[154:157], v[162:165], v[16:31]
	global_load_dwordx4 v[104:107], v[196:197], off offset:1024
	v_mfma_f32_32x32x16_bf16 v[0:15], v[154:157], v[170:173], v[0:15]
	s_waitcnt vmcnt(11)
	ds_write_b128 v235, v[108:111] offset:46080
	v_mfma_f32_32x32x16_bf16 v[48:63], v[150:153], v[166:169], v[48:63]
	global_load_dwordx4 v[108:111], v[204:205], off offset:1024
	v_mfma_f32_32x32x16_bf16 v[32:47], v[150:153], v[174:177], v[32:47]
	v_mfma_f32_32x32x16_bf16 v[16:31], v[158:161], v[166:169], v[16:31]
	v_mfma_f32_32x32x16_bf16 v[0:15], v[158:161], v[174:177], v[0:15]
	s_waitcnt lgkmcnt(0)
	s_barrier
	ds_read_b128 v[162:165], v237 offset:55296
	ds_read_b128 v[130:133], v237 offset:55328
	ds_read_b128 v[170:173], v241
	ds_read_b128 v[134:137], v241 offset:32
	ds_read_b128 v[166:169], v237 offset:59904
	ds_read_b128 v[142:145], v237 offset:59936
	ds_read_b128 v[174:177], v241 offset:4608
	ds_read_b128 v[150:153], v241 offset:4640
	ds_read_b128 v[138:141], v237 offset:55360
	ds_read_b128 v[116:119], v237 offset:55392
	ds_read_b128 v[146:149], v237 offset:59968
	ds_read_b128 v[112:115], v237 offset:60000
	ds_read_b128 v[154:157], v241 offset:64
	ds_read_b128 v[120:123], v241 offset:96
	ds_read_b128 v[158:161], v241 offset:4672
	ds_read_b128 v[124:127], v241 offset:4704
	s_waitcnt lgkmcnt(0)
	s_barrier
	v_mfma_f32_32x32x16_bf16 v[48:63], v[162:165], v[170:173], v[48:63]
	v_mfma_f32_32x32x16_bf16 v[32:47], v[162:165], v[174:177], v[32:47]
	s_waitcnt vmcnt(11)
	ds_write_b128 v235, v[64:67] offset:55296
	v_mfma_f32_32x32x16_bf16 v[16:31], v[166:169], v[170:173], v[16:31]
	global_load_dwordx4 v[64:67], v[194:195], off offset:1152
	v_mfma_f32_32x32x16_bf16 v[0:15], v[166:169], v[174:177], v[0:15]
	s_waitcnt vmcnt(11)
	ds_write_b128 v235, v[68:71] offset:64512
	v_mfma_f32_32x32x16_bf16 v[48:63], v[130:133], v[134:137], v[48:63]
	global_load_dwordx4 v[68:71], v[198:199], off offset:1152
	v_mfma_f32_32x32x16_bf16 v[32:47], v[130:133], v[150:153], v[32:47]
	s_waitcnt vmcnt(11)
	ds_write_b128 v239, v[80:83] offset:18432
	v_mfma_f32_32x32x16_bf16 v[16:31], v[142:145], v[134:137], v[16:31]
	global_load_dwordx4 v[80:83], v[200:201], off offset:1152
	v_mfma_f32_32x32x16_bf16 v[0:15], v[142:145], v[150:153], v[0:15]
	s_waitcnt vmcnt(11)
	ds_write_b128 v239, v[84:87] offset:27648
	v_mfma_f32_32x32x16_bf16 v[48:63], v[138:141], v[154:157], v[48:63]
	global_load_dwordx4 v[84:87], v[202:203], off offset:1152
	v_mfma_f32_32x32x16_bf16 v[32:47], v[138:141], v[158:161], v[32:47]
	s_waitcnt vmcnt(11)
	ds_write_b128 v240, v[96:99]
	v_mfma_f32_32x32x16_bf16 v[16:31], v[146:149], v[154:157], v[16:31]
	global_load_dwordx4 v[96:99], v[196:197], off offset:1152
	v_mfma_f32_32x32x16_bf16 v[0:15], v[146:149], v[158:161], v[0:15]
	s_waitcnt vmcnt(11)
	ds_write_b128 v240, v[100:103] offset:9216
	v_mfma_f32_32x32x16_bf16 v[48:63], v[116:119], v[120:123], v[48:63]
	global_load_dwordx4 v[100:103], v[204:205], off offset:1152
	v_mfma_f32_32x32x16_bf16 v[32:47], v[116:119], v[124:127], v[32:47]
	v_mfma_f32_32x32x16_bf16 v[16:31], v[112:115], v[120:123], v[16:31]
	v_mfma_f32_32x32x16_bf16 v[0:15], v[112:115], v[124:127], v[0:15]
	s_waitcnt lgkmcnt(0)
	s_barrier
	ds_read_b128 v[112:115], v237
	ds_read_b128 v[116:119], v237 offset:32
	ds_read_b128 v[120:123], v237 offset:4608
	ds_read_b128 v[124:127], v237 offset:4640
	ds_read_b128 v[130:133], v238 offset:36864
	ds_read_b128 v[134:137], v238 offset:36896
	ds_read_b128 v[138:141], v238 offset:41472
	ds_read_b128 v[142:145], v238 offset:41504
	ds_read_b128 v[146:149], v237 offset:64
	ds_read_b128 v[150:153], v237 offset:96
	ds_read_b128 v[154:157], v237 offset:4672
	ds_read_b128 v[158:161], v237 offset:4704
	ds_read_b128 v[162:165], v238 offset:36928
	ds_read_b128 v[166:169], v238 offset:36960
	ds_read_b128 v[170:173], v238 offset:41536
	ds_read_b128 v[174:177], v238 offset:41568
	s_waitcnt lgkmcnt(0)
	s_barrier
	v_mfma_f32_32x32x16_bf16 v[48:63], v[112:115], v[130:133], v[48:63]
	v_mfma_f32_32x32x16_bf16 v[32:47], v[112:115], v[138:141], v[32:47]
	s_waitcnt vmcnt(11)
	ds_write_b128 v235, v[72:75]
	v_mfma_f32_32x32x16_bf16 v[16:31], v[120:123], v[130:133], v[16:31]
	global_load_dwordx4 v[72:75], v[194:195], off offset:1280
	v_mfma_f32_32x32x16_bf16 v[0:15], v[120:123], v[138:141], v[0:15]
	s_waitcnt vmcnt(11)
	ds_write_b128 v235, v[76:79] offset:9216
	v_mfma_f32_32x32x16_bf16 v[48:63], v[116:119], v[134:137], v[48:63]
	global_load_dwordx4 v[76:79], v[198:199], off offset:1280
	v_mfma_f32_32x32x16_bf16 v[32:47], v[116:119], v[142:145], v[32:47]
	s_waitcnt vmcnt(11)
	ds_write_b128 v235, v[88:91] offset:18432
	v_mfma_f32_32x32x16_bf16 v[16:31], v[124:127], v[134:137], v[16:31]
	global_load_dwordx4 v[88:91], v[200:201], off offset:1280
	v_mfma_f32_32x32x16_bf16 v[0:15], v[124:127], v[142:145], v[0:15]
	s_waitcnt vmcnt(11)
	ds_write_b128 v235, v[92:95] offset:27648
	v_mfma_f32_32x32x16_bf16 v[48:63], v[146:149], v[162:165], v[48:63]
	global_load_dwordx4 v[92:95], v[202:203], off offset:1280
	v_mfma_f32_32x32x16_bf16 v[32:47], v[146:149], v[170:173], v[32:47]
	s_waitcnt vmcnt(11)
	ds_write_b128 v235, v[104:107] offset:36864
	v_mfma_f32_32x32x16_bf16 v[16:31], v[154:157], v[162:165], v[16:31]
	global_load_dwordx4 v[104:107], v[196:197], off offset:1280
	v_mfma_f32_32x32x16_bf16 v[0:15], v[154:157], v[170:173], v[0:15]
	s_waitcnt vmcnt(11)
	ds_write_b128 v235, v[108:111] offset:46080
	v_mfma_f32_32x32x16_bf16 v[48:63], v[150:153], v[166:169], v[48:63]
	global_load_dwordx4 v[108:111], v[204:205], off offset:1280
	v_mfma_f32_32x32x16_bf16 v[32:47], v[150:153], v[174:177], v[32:47]
	v_mfma_f32_32x32x16_bf16 v[16:31], v[158:161], v[166:169], v[16:31]
	v_mfma_f32_32x32x16_bf16 v[0:15], v[158:161], v[174:177], v[0:15]
	s_waitcnt lgkmcnt(0)
	s_barrier
	ds_read_b128 v[162:165], v237 offset:55296
	ds_read_b128 v[130:133], v237 offset:55328
	ds_read_b128 v[170:173], v241
	ds_read_b128 v[134:137], v241 offset:32
	ds_read_b128 v[166:169], v237 offset:59904
	ds_read_b128 v[142:145], v237 offset:59936
	ds_read_b128 v[174:177], v241 offset:4608
	ds_read_b128 v[150:153], v241 offset:4640
	ds_read_b128 v[138:141], v237 offset:55360
	ds_read_b128 v[116:119], v237 offset:55392
	ds_read_b128 v[146:149], v237 offset:59968
	ds_read_b128 v[112:115], v237 offset:60000
	ds_read_b128 v[154:157], v241 offset:64
	ds_read_b128 v[120:123], v241 offset:96
	ds_read_b128 v[158:161], v241 offset:4672
	ds_read_b128 v[124:127], v241 offset:4704
	s_waitcnt lgkmcnt(0)
	s_barrier
	v_mfma_f32_32x32x16_bf16 v[48:63], v[162:165], v[170:173], v[48:63]
	v_mfma_f32_32x32x16_bf16 v[32:47], v[162:165], v[174:177], v[32:47]
	s_waitcnt vmcnt(11)
	ds_write_b128 v235, v[64:67] offset:55296
	v_mfma_f32_32x32x16_bf16 v[16:31], v[166:169], v[170:173], v[16:31]
	global_load_dwordx4 v[64:67], v[194:195], off offset:1408
	v_mfma_f32_32x32x16_bf16 v[0:15], v[166:169], v[174:177], v[0:15]
	s_waitcnt vmcnt(11)
	ds_write_b128 v235, v[68:71] offset:64512
	v_mfma_f32_32x32x16_bf16 v[48:63], v[130:133], v[134:137], v[48:63]
	global_load_dwordx4 v[68:71], v[198:199], off offset:1408
	v_mfma_f32_32x32x16_bf16 v[32:47], v[130:133], v[150:153], v[32:47]
	s_waitcnt vmcnt(11)
	ds_write_b128 v239, v[80:83] offset:18432
	v_mfma_f32_32x32x16_bf16 v[16:31], v[142:145], v[134:137], v[16:31]
	global_load_dwordx4 v[80:83], v[200:201], off offset:1408
	v_mfma_f32_32x32x16_bf16 v[0:15], v[142:145], v[150:153], v[0:15]
	s_waitcnt vmcnt(11)
	ds_write_b128 v239, v[84:87] offset:27648
	v_mfma_f32_32x32x16_bf16 v[48:63], v[138:141], v[154:157], v[48:63]
	global_load_dwordx4 v[84:87], v[202:203], off offset:1408
	v_mfma_f32_32x32x16_bf16 v[32:47], v[138:141], v[158:161], v[32:47]
	s_waitcnt vmcnt(11)
	ds_write_b128 v240, v[96:99]
	v_mfma_f32_32x32x16_bf16 v[16:31], v[146:149], v[154:157], v[16:31]
	global_load_dwordx4 v[96:99], v[196:197], off offset:1408
	v_mfma_f32_32x32x16_bf16 v[0:15], v[146:149], v[158:161], v[0:15]
	s_waitcnt vmcnt(11)
	ds_write_b128 v240, v[100:103] offset:9216
	v_mfma_f32_32x32x16_bf16 v[48:63], v[116:119], v[120:123], v[48:63]
	global_load_dwordx4 v[100:103], v[204:205], off offset:1408
	v_mfma_f32_32x32x16_bf16 v[32:47], v[116:119], v[124:127], v[32:47]
	v_mfma_f32_32x32x16_bf16 v[16:31], v[112:115], v[120:123], v[16:31]
	v_mfma_f32_32x32x16_bf16 v[0:15], v[112:115], v[124:127], v[0:15]
	s_waitcnt lgkmcnt(0)
	s_barrier
	ds_read_b128 v[112:115], v237
	ds_read_b128 v[116:119], v237 offset:32
	ds_read_b128 v[120:123], v237 offset:4608
	ds_read_b128 v[124:127], v237 offset:4640
	ds_read_b128 v[130:133], v238 offset:36864
	ds_read_b128 v[134:137], v238 offset:36896
	ds_read_b128 v[138:141], v238 offset:41472
	ds_read_b128 v[142:145], v238 offset:41504
	ds_read_b128 v[146:149], v237 offset:64
	ds_read_b128 v[150:153], v237 offset:96
	ds_read_b128 v[154:157], v237 offset:4672
	ds_read_b128 v[158:161], v237 offset:4704
	ds_read_b128 v[162:165], v238 offset:36928
	ds_read_b128 v[166:169], v238 offset:36960
	ds_read_b128 v[170:173], v238 offset:41536
	ds_read_b128 v[174:177], v238 offset:41568
	s_waitcnt lgkmcnt(0)
	s_barrier
	v_mfma_f32_32x32x16_bf16 v[48:63], v[112:115], v[130:133], v[48:63]
	v_mfma_f32_32x32x16_bf16 v[32:47], v[112:115], v[138:141], v[32:47]
	s_waitcnt vmcnt(11)
	ds_write_b128 v235, v[72:75]
	v_mfma_f32_32x32x16_bf16 v[16:31], v[120:123], v[130:133], v[16:31]
	global_load_dwordx4 v[72:75], v[194:195], off offset:1536
	v_mfma_f32_32x32x16_bf16 v[0:15], v[120:123], v[138:141], v[0:15]
	s_waitcnt vmcnt(11)
	ds_write_b128 v235, v[76:79] offset:9216
	v_mfma_f32_32x32x16_bf16 v[48:63], v[116:119], v[134:137], v[48:63]
	global_load_dwordx4 v[76:79], v[198:199], off offset:1536
	v_mfma_f32_32x32x16_bf16 v[32:47], v[116:119], v[142:145], v[32:47]
	s_waitcnt vmcnt(11)
	ds_write_b128 v235, v[88:91] offset:18432
	v_mfma_f32_32x32x16_bf16 v[16:31], v[124:127], v[134:137], v[16:31]
	global_load_dwordx4 v[88:91], v[200:201], off offset:1536
	v_mfma_f32_32x32x16_bf16 v[0:15], v[124:127], v[142:145], v[0:15]
	s_waitcnt vmcnt(11)
	ds_write_b128 v235, v[92:95] offset:27648
	v_mfma_f32_32x32x16_bf16 v[48:63], v[146:149], v[162:165], v[48:63]
	global_load_dwordx4 v[92:95], v[202:203], off offset:1536
	v_mfma_f32_32x32x16_bf16 v[32:47], v[146:149], v[170:173], v[32:47]
	s_waitcnt vmcnt(11)
	ds_write_b128 v235, v[104:107] offset:36864
	v_mfma_f32_32x32x16_bf16 v[16:31], v[154:157], v[162:165], v[16:31]
	global_load_dwordx4 v[104:107], v[196:197], off offset:1536
	v_mfma_f32_32x32x16_bf16 v[0:15], v[154:157], v[170:173], v[0:15]
	s_waitcnt vmcnt(11)
	ds_write_b128 v235, v[108:111] offset:46080
	v_mfma_f32_32x32x16_bf16 v[48:63], v[150:153], v[166:169], v[48:63]
	global_load_dwordx4 v[108:111], v[204:205], off offset:1536
	v_mfma_f32_32x32x16_bf16 v[32:47], v[150:153], v[174:177], v[32:47]
	v_mfma_f32_32x32x16_bf16 v[16:31], v[158:161], v[166:169], v[16:31]
	v_mfma_f32_32x32x16_bf16 v[0:15], v[158:161], v[174:177], v[0:15]
	s_waitcnt lgkmcnt(0)
	s_barrier
	ds_read_b128 v[162:165], v237 offset:55296
	ds_read_b128 v[130:133], v237 offset:55328
	ds_read_b128 v[170:173], v241
	ds_read_b128 v[134:137], v241 offset:32
	ds_read_b128 v[166:169], v237 offset:59904
	ds_read_b128 v[142:145], v237 offset:59936
	ds_read_b128 v[174:177], v241 offset:4608
	ds_read_b128 v[150:153], v241 offset:4640
	ds_read_b128 v[138:141], v237 offset:55360
	ds_read_b128 v[116:119], v237 offset:55392
	ds_read_b128 v[146:149], v237 offset:59968
	ds_read_b128 v[112:115], v237 offset:60000
	ds_read_b128 v[154:157], v241 offset:64
	ds_read_b128 v[120:123], v241 offset:96
	ds_read_b128 v[158:161], v241 offset:4672
	ds_read_b128 v[124:127], v241 offset:4704
	s_waitcnt lgkmcnt(0)
	s_barrier
	v_mfma_f32_32x32x16_bf16 v[48:63], v[162:165], v[170:173], v[48:63]
	v_mfma_f32_32x32x16_bf16 v[32:47], v[162:165], v[174:177], v[32:47]
	s_waitcnt vmcnt(11)
	ds_write_b128 v235, v[64:67] offset:55296
	v_mfma_f32_32x32x16_bf16 v[16:31], v[166:169], v[170:173], v[16:31]
	global_load_dwordx4 v[64:67], v[194:195], off offset:1664
	v_mfma_f32_32x32x16_bf16 v[0:15], v[166:169], v[174:177], v[0:15]
	s_waitcnt vmcnt(11)
	ds_write_b128 v235, v[68:71] offset:64512
	v_mfma_f32_32x32x16_bf16 v[48:63], v[130:133], v[134:137], v[48:63]
	global_load_dwordx4 v[68:71], v[198:199], off offset:1664
	v_mfma_f32_32x32x16_bf16 v[32:47], v[130:133], v[150:153], v[32:47]
	s_waitcnt vmcnt(11)
	ds_write_b128 v239, v[80:83] offset:18432
	v_mfma_f32_32x32x16_bf16 v[16:31], v[142:145], v[134:137], v[16:31]
	global_load_dwordx4 v[80:83], v[200:201], off offset:1664
	v_mfma_f32_32x32x16_bf16 v[0:15], v[142:145], v[150:153], v[0:15]
	s_waitcnt vmcnt(11)
	ds_write_b128 v239, v[84:87] offset:27648
	v_mfma_f32_32x32x16_bf16 v[48:63], v[138:141], v[154:157], v[48:63]
	global_load_dwordx4 v[84:87], v[202:203], off offset:1664
	v_mfma_f32_32x32x16_bf16 v[32:47], v[138:141], v[158:161], v[32:47]
	s_waitcnt vmcnt(11)
	ds_write_b128 v240, v[96:99]
	v_mfma_f32_32x32x16_bf16 v[16:31], v[146:149], v[154:157], v[16:31]
	global_load_dwordx4 v[96:99], v[196:197], off offset:1664
	v_mfma_f32_32x32x16_bf16 v[0:15], v[146:149], v[158:161], v[0:15]
	s_waitcnt vmcnt(11)
	ds_write_b128 v240, v[100:103] offset:9216
	v_mfma_f32_32x32x16_bf16 v[48:63], v[116:119], v[120:123], v[48:63]
	global_load_dwordx4 v[100:103], v[204:205], off offset:1664
	v_mfma_f32_32x32x16_bf16 v[32:47], v[116:119], v[124:127], v[32:47]
	v_mfma_f32_32x32x16_bf16 v[16:31], v[112:115], v[120:123], v[16:31]
	v_mfma_f32_32x32x16_bf16 v[0:15], v[112:115], v[124:127], v[0:15]
	s_waitcnt lgkmcnt(0)
	s_barrier
	ds_read_b128 v[112:115], v237
	ds_read_b128 v[116:119], v237 offset:32
	ds_read_b128 v[120:123], v237 offset:4608
	ds_read_b128 v[124:127], v237 offset:4640
	ds_read_b128 v[130:133], v238 offset:36864
	ds_read_b128 v[134:137], v238 offset:36896
	ds_read_b128 v[138:141], v238 offset:41472
	ds_read_b128 v[142:145], v238 offset:41504
	ds_read_b128 v[146:149], v237 offset:64
	ds_read_b128 v[150:153], v237 offset:96
	ds_read_b128 v[154:157], v237 offset:4672
	ds_read_b128 v[158:161], v237 offset:4704
	ds_read_b128 v[162:165], v238 offset:36928
	ds_read_b128 v[166:169], v238 offset:36960
	ds_read_b128 v[170:173], v238 offset:41536
	ds_read_b128 v[174:177], v238 offset:41568
	s_waitcnt lgkmcnt(0)
	s_barrier
	v_mfma_f32_32x32x16_bf16 v[48:63], v[112:115], v[130:133], v[48:63]
	v_mfma_f32_32x32x16_bf16 v[32:47], v[112:115], v[138:141], v[32:47]
	s_waitcnt vmcnt(11)
	ds_write_b128 v235, v[72:75]
	v_mfma_f32_32x32x16_bf16 v[16:31], v[120:123], v[130:133], v[16:31]
	global_load_dwordx4 v[72:75], v[194:195], off offset:1792
	v_mfma_f32_32x32x16_bf16 v[0:15], v[120:123], v[138:141], v[0:15]
	s_waitcnt vmcnt(11)
	ds_write_b128 v235, v[76:79] offset:9216
	v_mfma_f32_32x32x16_bf16 v[48:63], v[116:119], v[134:137], v[48:63]
	global_load_dwordx4 v[76:79], v[198:199], off offset:1792
	v_mfma_f32_32x32x16_bf16 v[32:47], v[116:119], v[142:145], v[32:47]
	s_waitcnt vmcnt(11)
	ds_write_b128 v235, v[88:91] offset:18432
	v_mfma_f32_32x32x16_bf16 v[16:31], v[124:127], v[134:137], v[16:31]
	global_load_dwordx4 v[88:91], v[200:201], off offset:1792
	v_mfma_f32_32x32x16_bf16 v[0:15], v[124:127], v[142:145], v[0:15]
	s_waitcnt vmcnt(11)
	ds_write_b128 v235, v[92:95] offset:27648
	v_mfma_f32_32x32x16_bf16 v[48:63], v[146:149], v[162:165], v[48:63]
	global_load_dwordx4 v[92:95], v[202:203], off offset:1792
	v_mfma_f32_32x32x16_bf16 v[32:47], v[146:149], v[170:173], v[32:47]
	s_waitcnt vmcnt(11)
	ds_write_b128 v235, v[104:107] offset:36864
	v_mfma_f32_32x32x16_bf16 v[16:31], v[154:157], v[162:165], v[16:31]
	global_load_dwordx4 v[104:107], v[196:197], off offset:1792
	v_mfma_f32_32x32x16_bf16 v[0:15], v[154:157], v[170:173], v[0:15]
	s_waitcnt vmcnt(11)
	ds_write_b128 v235, v[108:111] offset:46080
	v_mfma_f32_32x32x16_bf16 v[48:63], v[150:153], v[166:169], v[48:63]
	global_load_dwordx4 v[108:111], v[204:205], off offset:1792
	v_mfma_f32_32x32x16_bf16 v[32:47], v[150:153], v[174:177], v[32:47]
	v_mfma_f32_32x32x16_bf16 v[16:31], v[158:161], v[166:169], v[16:31]
	v_mfma_f32_32x32x16_bf16 v[0:15], v[158:161], v[174:177], v[0:15]
	s_waitcnt lgkmcnt(0)
	s_barrier
	ds_read_b128 v[162:165], v237 offset:55296
	ds_read_b128 v[130:133], v237 offset:55328
	ds_read_b128 v[170:173], v241
	ds_read_b128 v[134:137], v241 offset:32
	ds_read_b128 v[166:169], v237 offset:59904
	ds_read_b128 v[142:145], v237 offset:59936
	ds_read_b128 v[174:177], v241 offset:4608
	ds_read_b128 v[150:153], v241 offset:4640
	ds_read_b128 v[138:141], v237 offset:55360
	ds_read_b128 v[116:119], v237 offset:55392
	ds_read_b128 v[146:149], v237 offset:59968
	ds_read_b128 v[112:115], v237 offset:60000
	ds_read_b128 v[154:157], v241 offset:64
	ds_read_b128 v[120:123], v241 offset:96
	ds_read_b128 v[158:161], v241 offset:4672
	ds_read_b128 v[124:127], v241 offset:4704
	s_waitcnt lgkmcnt(0)
	s_barrier
	v_mfma_f32_32x32x16_bf16 v[48:63], v[162:165], v[170:173], v[48:63]
	v_mfma_f32_32x32x16_bf16 v[32:47], v[162:165], v[174:177], v[32:47]
	s_waitcnt vmcnt(11)
	ds_write_b128 v235, v[64:67] offset:55296
	v_mfma_f32_32x32x16_bf16 v[16:31], v[166:169], v[170:173], v[16:31]
	global_load_dwordx4 v[64:67], v[194:195], off offset:1920
	v_mfma_f32_32x32x16_bf16 v[0:15], v[166:169], v[174:177], v[0:15]
	s_waitcnt vmcnt(11)
	ds_write_b128 v235, v[68:71] offset:64512
	v_mfma_f32_32x32x16_bf16 v[48:63], v[130:133], v[134:137], v[48:63]
	global_load_dwordx4 v[68:71], v[198:199], off offset:1920
	v_mfma_f32_32x32x16_bf16 v[32:47], v[130:133], v[150:153], v[32:47]
	s_waitcnt vmcnt(11)
	ds_write_b128 v239, v[80:83] offset:18432
	v_mfma_f32_32x32x16_bf16 v[16:31], v[142:145], v[134:137], v[16:31]
	global_load_dwordx4 v[80:83], v[200:201], off offset:1920
	v_mfma_f32_32x32x16_bf16 v[0:15], v[142:145], v[150:153], v[0:15]
	s_waitcnt vmcnt(11)
	ds_write_b128 v239, v[84:87] offset:27648
	v_mfma_f32_32x32x16_bf16 v[48:63], v[138:141], v[154:157], v[48:63]
	global_load_dwordx4 v[84:87], v[202:203], off offset:1920
	v_mfma_f32_32x32x16_bf16 v[32:47], v[138:141], v[158:161], v[32:47]
	s_waitcnt vmcnt(11)
	ds_write_b128 v240, v[96:99]
	v_mfma_f32_32x32x16_bf16 v[16:31], v[146:149], v[154:157], v[16:31]
	global_load_dwordx4 v[96:99], v[196:197], off offset:1920
	v_mfma_f32_32x32x16_bf16 v[0:15], v[146:149], v[158:161], v[0:15]
	s_waitcnt vmcnt(11)
	ds_write_b128 v240, v[100:103] offset:9216
	v_mfma_f32_32x32x16_bf16 v[48:63], v[116:119], v[120:123], v[48:63]
	global_load_dwordx4 v[100:103], v[204:205], off offset:1920
	v_mfma_f32_32x32x16_bf16 v[32:47], v[116:119], v[124:127], v[32:47]
	v_mfma_f32_32x32x16_bf16 v[16:31], v[112:115], v[120:123], v[16:31]
	v_mfma_f32_32x32x16_bf16 v[0:15], v[112:115], v[124:127], v[0:15]
	s_waitcnt lgkmcnt(0)
	s_barrier
	ds_read_b128 v[112:115], v237
	ds_read_b128 v[116:119], v237 offset:32
	ds_read_b128 v[120:123], v237 offset:4608
	ds_read_b128 v[124:127], v237 offset:4640
	ds_read_b128 v[130:133], v238 offset:36864
	ds_read_b128 v[134:137], v238 offset:36896
	ds_read_b128 v[138:141], v238 offset:41472
	ds_read_b128 v[142:145], v238 offset:41504
	ds_read_b128 v[146:149], v237 offset:64
	ds_read_b128 v[150:153], v237 offset:96
	ds_read_b128 v[154:157], v237 offset:4672
	ds_read_b128 v[158:161], v237 offset:4704
	ds_read_b128 v[162:165], v238 offset:36928
	ds_read_b128 v[166:169], v238 offset:36960
	ds_read_b128 v[170:173], v238 offset:41536
	ds_read_b128 v[174:177], v238 offset:41568
	s_waitcnt lgkmcnt(0)
	s_barrier
	v_mfma_f32_32x32x16_bf16 v[48:63], v[112:115], v[130:133], v[48:63]
	v_mfma_f32_32x32x16_bf16 v[32:47], v[112:115], v[138:141], v[32:47]
	s_waitcnt vmcnt(11)
	ds_write_b128 v235, v[72:75]
	v_mfma_f32_32x32x16_bf16 v[16:31], v[120:123], v[130:133], v[16:31]
	v_mfma_f32_32x32x16_bf16 v[0:15], v[120:123], v[138:141], v[0:15]
	s_waitcnt vmcnt(10)
	ds_write_b128 v235, v[76:79] offset:9216
	v_mfma_f32_32x32x16_bf16 v[48:63], v[116:119], v[134:137], v[48:63]
	v_mfma_f32_32x32x16_bf16 v[32:47], v[116:119], v[142:145], v[32:47]
	s_waitcnt vmcnt(9)
	ds_write_b128 v235, v[88:91] offset:18432
	v_mfma_f32_32x32x16_bf16 v[16:31], v[124:127], v[134:137], v[16:31]
	v_mfma_f32_32x32x16_bf16 v[0:15], v[124:127], v[142:145], v[0:15]
	s_waitcnt vmcnt(8)
	ds_write_b128 v235, v[92:95] offset:27648
	v_mfma_f32_32x32x16_bf16 v[48:63], v[146:149], v[162:165], v[48:63]
	v_mfma_f32_32x32x16_bf16 v[32:47], v[146:149], v[170:173], v[32:47]
	s_waitcnt vmcnt(7)
	ds_write_b128 v235, v[104:107] offset:36864
	v_mfma_f32_32x32x16_bf16 v[16:31], v[154:157], v[162:165], v[16:31]
	v_mfma_f32_32x32x16_bf16 v[0:15], v[154:157], v[170:173], v[0:15]
	s_waitcnt vmcnt(6)
	ds_write_b128 v235, v[108:111] offset:46080
	v_mfma_f32_32x32x16_bf16 v[48:63], v[150:153], v[166:169], v[48:63]
	v_mfma_f32_32x32x16_bf16 v[32:47], v[150:153], v[174:177], v[32:47]
	v_mfma_f32_32x32x16_bf16 v[16:31], v[158:161], v[166:169], v[16:31]
	v_mfma_f32_32x32x16_bf16 v[0:15], v[158:161], v[174:177], v[0:15]
	s_waitcnt lgkmcnt(0)
	s_barrier
	ds_read_b128 v[162:165], v237 offset:55296
	ds_read_b128 v[130:133], v237 offset:55328
	ds_read_b128 v[170:173], v241
	ds_read_b128 v[134:137], v241 offset:32
	ds_read_b128 v[166:169], v237 offset:59904
	ds_read_b128 v[142:145], v237 offset:59936
	ds_read_b128 v[174:177], v241 offset:4608
	ds_read_b128 v[150:153], v241 offset:4640
	ds_read_b128 v[138:141], v237 offset:55360
	ds_read_b128 v[116:119], v237 offset:55392
	ds_read_b128 v[146:149], v237 offset:59968
	ds_read_b128 v[112:115], v237 offset:60000
	ds_read_b128 v[154:157], v241 offset:64
	ds_read_b128 v[120:123], v241 offset:96
	ds_read_b128 v[158:161], v241 offset:4672
	ds_read_b128 v[124:127], v241 offset:4704
	s_waitcnt lgkmcnt(0)
	s_barrier
	v_mfma_f32_32x32x16_bf16 v[48:63], v[162:165], v[170:173], v[48:63]
	v_mfma_f32_32x32x16_bf16 v[32:47], v[162:165], v[174:177], v[32:47]
	s_waitcnt vmcnt(5)
	ds_write_b128 v235, v[64:67] offset:55296
	v_mfma_f32_32x32x16_bf16 v[16:31], v[166:169], v[170:173], v[16:31]
	v_mfma_f32_32x32x16_bf16 v[0:15], v[166:169], v[174:177], v[0:15]
	s_waitcnt vmcnt(4)
	ds_write_b128 v235, v[68:71] offset:64512
	v_mfma_f32_32x32x16_bf16 v[48:63], v[130:133], v[134:137], v[48:63]
	v_mfma_f32_32x32x16_bf16 v[32:47], v[130:133], v[150:153], v[32:47]
	s_waitcnt vmcnt(3)
	ds_write_b128 v239, v[80:83] offset:18432
	v_mfma_f32_32x32x16_bf16 v[16:31], v[142:145], v[134:137], v[16:31]
	v_mfma_f32_32x32x16_bf16 v[0:15], v[142:145], v[150:153], v[0:15]
	s_waitcnt vmcnt(2)
	ds_write_b128 v239, v[84:87] offset:27648
	v_mfma_f32_32x32x16_bf16 v[48:63], v[138:141], v[154:157], v[48:63]
	v_mfma_f32_32x32x16_bf16 v[32:47], v[138:141], v[158:161], v[32:47]
	s_waitcnt vmcnt(1)
	ds_write_b128 v240, v[96:99]
	v_mfma_f32_32x32x16_bf16 v[16:31], v[146:149], v[154:157], v[16:31]
	v_mfma_f32_32x32x16_bf16 v[0:15], v[146:149], v[158:161], v[0:15]
	s_waitcnt vmcnt(0)
	ds_write_b128 v240, v[100:103] offset:9216
	v_mfma_f32_32x32x16_bf16 v[48:63], v[116:119], v[120:123], v[48:63]
	v_mfma_f32_32x32x16_bf16 v[32:47], v[116:119], v[124:127], v[32:47]
	v_mfma_f32_32x32x16_bf16 v[16:31], v[112:115], v[120:123], v[16:31]
	v_mfma_f32_32x32x16_bf16 v[0:15], v[112:115], v[124:127], v[0:15]
	s_waitcnt lgkmcnt(0)
	s_barrier
	ds_read_b128 v[112:115], v237
	ds_read_b128 v[116:119], v237 offset:32
	ds_read_b128 v[120:123], v237 offset:4608
	ds_read_b128 v[124:127], v237 offset:4640
	ds_read_b128 v[130:133], v238 offset:36864
	ds_read_b128 v[134:137], v238 offset:36896
	ds_read_b128 v[138:141], v238 offset:41472
	ds_read_b128 v[142:145], v238 offset:41504
	ds_read_b128 v[146:149], v237 offset:64
	ds_read_b128 v[150:153], v237 offset:96
	ds_read_b128 v[154:157], v237 offset:4672
	ds_read_b128 v[158:161], v237 offset:4704
	ds_read_b128 v[162:165], v238 offset:36928
	ds_read_b128 v[166:169], v238 offset:36960
	ds_read_b128 v[170:173], v238 offset:41536
	ds_read_b128 v[174:177], v238 offset:41568
	s_waitcnt lgkmcnt(0)
	s_barrier
	v_mfma_f32_32x32x16_bf16 v[48:63], v[112:115], v[130:133], v[48:63]
	v_mfma_f32_32x32x16_bf16 v[32:47], v[112:115], v[138:141], v[32:47]
	v_mfma_f32_32x32x16_bf16 v[16:31], v[120:123], v[130:133], v[16:31]
	v_mfma_f32_32x32x16_bf16 v[0:15], v[120:123], v[138:141], v[0:15]
	v_mfma_f32_32x32x16_bf16 v[48:63], v[116:119], v[134:137], v[48:63]
	v_mfma_f32_32x32x16_bf16 v[32:47], v[116:119], v[142:145], v[32:47]
	v_mfma_f32_32x32x16_bf16 v[16:31], v[124:127], v[134:137], v[16:31]
	v_mfma_f32_32x32x16_bf16 v[0:15], v[124:127], v[142:145], v[0:15]
	v_mfma_f32_32x32x16_bf16 v[48:63], v[146:149], v[162:165], v[48:63]
	v_mfma_f32_32x32x16_bf16 v[32:47], v[146:149], v[170:173], v[32:47]
	v_mfma_f32_32x32x16_bf16 v[16:31], v[154:157], v[162:165], v[16:31]
	v_mfma_f32_32x32x16_bf16 v[0:15], v[154:157], v[170:173], v[0:15]
	v_mfma_f32_32x32x16_bf16 v[48:63], v[150:153], v[166:169], v[48:63]
	v_mfma_f32_32x32x16_bf16 v[32:47], v[150:153], v[174:177], v[32:47]
	v_mfma_f32_32x32x16_bf16 v[16:31], v[158:161], v[166:169], v[16:31]
	v_mfma_f32_32x32x16_bf16 v[0:15], v[158:161], v[174:177], v[0:15]
	s_waitcnt lgkmcnt(0)
	s_barrier
	ds_read_b128 v[162:165], v237 offset:55296
	ds_read_b128 v[130:133], v237 offset:55328
	ds_read_b128 v[170:173], v241
	ds_read_b128 v[134:137], v241 offset:32
	ds_read_b128 v[166:169], v237 offset:59904
	ds_read_b128 v[142:145], v237 offset:59936
	ds_read_b128 v[174:177], v241 offset:4608
	ds_read_b128 v[150:153], v241 offset:4640
	ds_read_b128 v[138:141], v237 offset:55360
	ds_read_b128 v[116:119], v237 offset:55392
	ds_read_b128 v[146:149], v237 offset:59968
	ds_read_b128 v[112:115], v237 offset:60000
	ds_read_b128 v[154:157], v241 offset:64
	ds_read_b128 v[120:123], v241 offset:96
	ds_read_b128 v[158:161], v241 offset:4672
	ds_read_b128 v[124:127], v241 offset:4704
	s_waitcnt lgkmcnt(0)
	s_barrier
	v_mfma_f32_32x32x16_bf16 v[48:63], v[162:165], v[170:173], v[48:63]
	v_mfma_f32_32x32x16_bf16 v[32:47], v[162:165], v[174:177], v[32:47]
	v_mfma_f32_32x32x16_bf16 v[16:31], v[166:169], v[170:173], v[16:31]
	v_mfma_f32_32x32x16_bf16 v[0:15], v[166:169], v[174:177], v[0:15]
	v_mfma_f32_32x32x16_bf16 v[48:63], v[130:133], v[134:137], v[48:63]
	v_mfma_f32_32x32x16_bf16 v[32:47], v[130:133], v[150:153], v[32:47]
	v_mfma_f32_32x32x16_bf16 v[16:31], v[142:145], v[134:137], v[16:31]
	v_mfma_f32_32x32x16_bf16 v[0:15], v[142:145], v[150:153], v[0:15]
	v_mfma_f32_32x32x16_bf16 v[48:63], v[138:141], v[154:157], v[48:63]
	v_mfma_f32_32x32x16_bf16 v[32:47], v[138:141], v[158:161], v[32:47]
	v_mfma_f32_32x32x16_bf16 v[16:31], v[146:149], v[154:157], v[16:31]
	v_mfma_f32_32x32x16_bf16 v[0:15], v[146:149], v[158:161], v[0:15]
	v_mfma_f32_32x32x16_bf16 v[48:63], v[116:119], v[120:123], v[48:63]
	v_mfma_f32_32x32x16_bf16 v[32:47], v[116:119], v[124:127], v[32:47]
	v_mfma_f32_32x32x16_bf16 v[16:31], v[112:115], v[120:123], v[16:31]
	v_mfma_f32_32x32x16_bf16 v[0:15], v[112:115], v[124:127], v[0:15]
	s_waitcnt lgkmcnt(0)
	s_barrier
	s_branch .LBB0_207

.LBB0_211:
	s_waitcnt lgkmcnt(13)
	v_mfma_f32_32x32x16_bf16 v[48:63], v[116:119], v[124:127], v[48:63]
	s_waitcnt lgkmcnt(9)
	v_mfma_f32_32x32x16_bf16 v[32:47], v[116:119], v[154:157], v[32:47]
	v_mfma_f32_32x32x16_bf16 v[16:31], v[134:137], v[124:127], v[16:31]
	v_mfma_f32_32x32x16_bf16 v[0:15], v[134:137], v[154:157], v[0:15]
	v_mfma_f32_32x32x16_bf16 v[48:63], v[112:115], v[120:123], v[48:63]
	s_waitcnt lgkmcnt(8)
	v_mfma_f32_32x32x16_bf16 v[32:47], v[112:115], v[142:145], v[32:47]
	v_mfma_f32_32x32x16_bf16 v[16:31], v[130:133], v[120:123], v[16:31]
	v_mfma_f32_32x32x16_bf16 v[0:15], v[130:133], v[142:145], v[0:15]
	s_waitcnt lgkmcnt(3)
	v_mfma_f32_32x32x16_bf16 v[48:63], v[138:141], v[170:173], v[48:63]
	s_waitcnt lgkmcnt(1)
	v_mfma_f32_32x32x16_bf16 v[32:47], v[138:141], v[174:177], v[32:47]
	v_mfma_f32_32x32x16_bf16 v[16:31], v[158:161], v[170:173], v[16:31]
	v_mfma_f32_32x32x16_bf16 v[0:15], v[158:161], v[174:177], v[0:15]
	v_mfma_f32_32x32x16_bf16 v[48:63], v[146:149], v[162:165], v[48:63]
	s_waitcnt lgkmcnt(0)
	v_mfma_f32_32x32x16_bf16 v[32:47], v[146:149], v[166:169], v[32:47]
	v_mfma_f32_32x32x16_bf16 v[16:31], v[150:153], v[162:165], v[16:31]
	v_mfma_f32_32x32x16_bf16 v[0:15], v[150:153], v[166:169], v[0:15]
	s_waitcnt lgkmcnt(0)
	s_barrier
	ds_read_b128 v[116:119], v237 offset:55296
	ds_read_b128 v[112:115], v237 offset:55328
	ds_read_b128 v[124:127], v241
	ds_read_b128 v[120:123], v241 offset:32
	ds_read_b128 v[134:137], v237 offset:59904
	ds_read_b128 v[130:133], v237 offset:59936
	ds_read_b128 v[154:157], v241 offset:4608
	ds_read_b128 v[142:145], v241 offset:4640
	ds_read_b128 v[138:141], v237 offset:55360
	ds_read_b128 v[146:149], v237 offset:55392
	ds_read_b128 v[158:161], v237 offset:59968
	ds_read_b128 v[150:153], v237 offset:60000
	ds_read_b128 v[170:173], v241 offset:64
	ds_read_b128 v[162:165], v241 offset:96
	ds_read_b128 v[174:177], v241 offset:4672
	ds_read_b128 v[166:169], v241 offset:4704
	s_waitcnt lgkmcnt(0)
	s_barrier
	v_mfma_f32_32x32x16_bf16 v[48:63], v[116:119], v[124:127], v[48:63]
	v_mfma_f32_32x32x16_bf16 v[32:47], v[116:119], v[154:157], v[32:47]
	s_waitcnt vmcnt(11)
	ds_write_b128 v235, v[64:67]
	v_mfma_f32_32x32x16_bf16 v[16:31], v[134:137], v[124:127], v[16:31]
	global_load_dwordx4 v[64:67], v[194:195], off offset:512
	v_mfma_f32_32x32x16_bf16 v[0:15], v[134:137], v[154:157], v[0:15]
	s_waitcnt vmcnt(11)
	ds_write_b128 v235, v[68:71] offset:9216
	v_mfma_f32_32x32x16_bf16 v[48:63], v[112:115], v[120:123], v[48:63]
	global_load_dwordx4 v[68:71], v[198:199], off offset:512
	v_mfma_f32_32x32x16_bf16 v[32:47], v[112:115], v[142:145], v[32:47]
	s_waitcnt vmcnt(10)
	ds_write_b128 v235, v[84:87] offset:18432
	v_mfma_f32_32x32x16_bf16 v[16:31], v[130:133], v[120:123], v[16:31]
	global_load_dwordx4 v[84:87], v[200:201], off offset:512
	v_mfma_f32_32x32x16_bf16 v[0:15], v[130:133], v[142:145], v[0:15]
	ds_write_b128 v235, v[72:75] offset:27648
	v_mfma_f32_32x32x16_bf16 v[48:63], v[138:141], v[170:173], v[48:63]
	global_load_dwordx4 v[72:75], v[202:203], off offset:512
	v_mfma_f32_32x32x16_bf16 v[32:47], v[138:141], v[174:177], v[32:47]
	s_waitcnt vmcnt(11)
	ds_write_b128 v235, v[96:99] offset:36864
	v_mfma_f32_32x32x16_bf16 v[16:31], v[158:161], v[170:173], v[16:31]
	global_load_dwordx4 v[96:99], v[196:197], off offset:512
	v_mfma_f32_32x32x16_bf16 v[0:15], v[158:161], v[174:177], v[0:15]
	s_waitcnt vmcnt(11)
	ds_write_b128 v235, v[100:103] offset:46080
	v_mfma_f32_32x32x16_bf16 v[48:63], v[146:149], v[162:165], v[48:63]
	global_load_dwordx4 v[100:103], v[204:205], off offset:512
	v_mfma_f32_32x32x16_bf16 v[32:47], v[146:149], v[166:169], v[32:47]
	v_mfma_f32_32x32x16_bf16 v[16:31], v[150:153], v[162:165], v[16:31]
	v_mfma_f32_32x32x16_bf16 v[0:15], v[150:153], v[166:169], v[0:15]
	s_waitcnt lgkmcnt(0)
	s_barrier
	ds_read_b128 v[116:119], v237
	ds_read_b128 v[112:115], v237 offset:32
	ds_read_b128 v[124:127], v238 offset:36864
	ds_read_b128 v[120:123], v238 offset:36896
	ds_read_b128 v[134:137], v237 offset:4608
	ds_read_b128 v[130:133], v237 offset:4640
	ds_read_b128 v[154:157], v238 offset:41472
	ds_read_b128 v[142:145], v238 offset:41504
	ds_read_b128 v[138:141], v237 offset:64
	ds_read_b128 v[146:149], v237 offset:96
	ds_read_b128 v[158:161], v237 offset:4672
	ds_read_b128 v[150:153], v237 offset:4704
	ds_read_b128 v[170:173], v238 offset:36928
	ds_read_b128 v[162:165], v238 offset:36960
	ds_read_b128 v[174:177], v238 offset:41536
	ds_read_b128 v[166:169], v238 offset:41568
	s_waitcnt lgkmcnt(0)
	s_barrier
	v_mfma_f32_32x32x16_bf16 v[48:63], v[116:119], v[124:127], v[48:63]
	v_mfma_f32_32x32x16_bf16 v[32:47], v[116:119], v[154:157], v[32:47]
	s_waitcnt vmcnt(11)
	ds_write_b128 v235, v[76:79] offset:55296
	v_mfma_f32_32x32x16_bf16 v[16:31], v[134:137], v[124:127], v[16:31]
	global_load_dwordx4 v[76:79], v[194:195], off offset:640
	v_mfma_f32_32x32x16_bf16 v[0:15], v[134:137], v[154:157], v[0:15]
	s_waitcnt vmcnt(11)
	ds_write_b128 v235, v[80:83] offset:64512
	v_mfma_f32_32x32x16_bf16 v[48:63], v[112:115], v[120:123], v[48:63]
	global_load_dwordx4 v[80:83], v[198:199], off offset:640
	v_mfma_f32_32x32x16_bf16 v[32:47], v[112:115], v[142:145], v[32:47]
	s_waitcnt vmcnt(11)
	ds_write_b128 v239, v[88:91] offset:18432
	v_mfma_f32_32x32x16_bf16 v[16:31], v[130:133], v[120:123], v[16:31]
	global_load_dwordx4 v[88:91], v[200:201], off offset:640
	v_mfma_f32_32x32x16_bf16 v[0:15], v[130:133], v[142:145], v[0:15]
	s_waitcnt vmcnt(11)
	ds_write_b128 v239, v[92:95] offset:27648
	v_mfma_f32_32x32x16_bf16 v[48:63], v[138:141], v[170:173], v[48:63]
	global_load_dwordx4 v[92:95], v[202:203], off offset:640
	v_mfma_f32_32x32x16_bf16 v[32:47], v[138:141], v[174:177], v[32:47]
	s_waitcnt vmcnt(11)
	ds_write_b128 v240, v[104:107]
	v_mfma_f32_32x32x16_bf16 v[16:31], v[158:161], v[170:173], v[16:31]
	global_load_dwordx4 v[104:107], v[196:197], off offset:640
	v_mfma_f32_32x32x16_bf16 v[0:15], v[158:161], v[174:177], v[0:15]
	s_waitcnt vmcnt(11)
	ds_write_b128 v240, v[108:111] offset:9216
	v_mfma_f32_32x32x16_bf16 v[48:63], v[146:149], v[162:165], v[48:63]
	global_load_dwordx4 v[108:111], v[204:205], off offset:640
	v_mfma_f32_32x32x16_bf16 v[32:47], v[146:149], v[166:169], v[32:47]
	v_mfma_f32_32x32x16_bf16 v[16:31], v[150:153], v[162:165], v[16:31]
	v_mfma_f32_32x32x16_bf16 v[0:15], v[150:153], v[166:169], v[0:15]
	s_waitcnt lgkmcnt(0)
	s_barrier
	ds_read_b128 v[116:119], v237 offset:55296
	ds_read_b128 v[112:115], v237 offset:55328
	ds_read_b128 v[124:127], v241
	ds_read_b128 v[120:123], v241 offset:32
	ds_read_b128 v[134:137], v237 offset:59904
	ds_read_b128 v[130:133], v237 offset:59936
	ds_read_b128 v[154:157], v241 offset:4608
	ds_read_b128 v[142:145], v241 offset:4640
	ds_read_b128 v[138:141], v237 offset:55360
	ds_read_b128 v[146:149], v237 offset:55392
	ds_read_b128 v[158:161], v237 offset:59968
	ds_read_b128 v[150:153], v237 offset:60000
	ds_read_b128 v[170:173], v241 offset:64
	ds_read_b128 v[162:165], v241 offset:96
	ds_read_b128 v[174:177], v241 offset:4672
	ds_read_b128 v[166:169], v241 offset:4704
	s_waitcnt lgkmcnt(0)
	s_barrier
	v_mfma_f32_32x32x16_bf16 v[48:63], v[116:119], v[124:127], v[48:63]
	v_mfma_f32_32x32x16_bf16 v[32:47], v[116:119], v[154:157], v[32:47]
	s_waitcnt vmcnt(11)
	ds_write_b128 v235, v[64:67]
	v_mfma_f32_32x32x16_bf16 v[16:31], v[134:137], v[124:127], v[16:31]
	global_load_dwordx4 v[64:67], v[194:195], off offset:768
	v_mfma_f32_32x32x16_bf16 v[0:15], v[134:137], v[154:157], v[0:15]
	s_waitcnt vmcnt(11)
	ds_write_b128 v235, v[68:71] offset:9216
	v_mfma_f32_32x32x16_bf16 v[48:63], v[112:115], v[120:123], v[48:63]
	global_load_dwordx4 v[68:71], v[198:199], off offset:768
	v_mfma_f32_32x32x16_bf16 v[32:47], v[112:115], v[142:145], v[32:47]
	s_waitcnt vmcnt(11)
	ds_write_b128 v235, v[84:87] offset:18432
	v_mfma_f32_32x32x16_bf16 v[16:31], v[130:133], v[120:123], v[16:31]
	global_load_dwordx4 v[84:87], v[200:201], off offset:768
	v_mfma_f32_32x32x16_bf16 v[0:15], v[130:133], v[142:145], v[0:15]
	s_waitcnt vmcnt(11)
	ds_write_b128 v235, v[72:75] offset:27648
	v_mfma_f32_32x32x16_bf16 v[48:63], v[138:141], v[170:173], v[48:63]
	global_load_dwordx4 v[72:75], v[202:203], off offset:768
	v_mfma_f32_32x32x16_bf16 v[32:47], v[138:141], v[174:177], v[32:47]
	s_waitcnt vmcnt(11)
	ds_write_b128 v235, v[96:99] offset:36864
	v_mfma_f32_32x32x16_bf16 v[16:31], v[158:161], v[170:173], v[16:31]
	global_load_dwordx4 v[96:99], v[196:197], off offset:768
	v_mfma_f32_32x32x16_bf16 v[0:15], v[158:161], v[174:177], v[0:15]
	s_waitcnt vmcnt(11)
	ds_write_b128 v235, v[100:103] offset:46080
	v_mfma_f32_32x32x16_bf16 v[48:63], v[146:149], v[162:165], v[48:63]
	global_load_dwordx4 v[100:103], v[204:205], off offset:768
	v_mfma_f32_32x32x16_bf16 v[32:47], v[146:149], v[166:169], v[32:47]
	v_mfma_f32_32x32x16_bf16 v[16:31], v[150:153], v[162:165], v[16:31]
	v_mfma_f32_32x32x16_bf16 v[0:15], v[150:153], v[166:169], v[0:15]
	s_waitcnt lgkmcnt(0)
	s_barrier
	ds_read_b128 v[116:119], v237
	ds_read_b128 v[112:115], v237 offset:32
	ds_read_b128 v[124:127], v238 offset:36864
	ds_read_b128 v[120:123], v238 offset:36896
	ds_read_b128 v[134:137], v237 offset:4608
	ds_read_b128 v[130:133], v237 offset:4640
	ds_read_b128 v[154:157], v238 offset:41472
	ds_read_b128 v[142:145], v238 offset:41504
	ds_read_b128 v[138:141], v237 offset:64
	ds_read_b128 v[146:149], v237 offset:96
	ds_read_b128 v[158:161], v237 offset:4672
	ds_read_b128 v[150:153], v237 offset:4704
	ds_read_b128 v[170:173], v238 offset:36928
	ds_read_b128 v[162:165], v238 offset:36960
	ds_read_b128 v[174:177], v238 offset:41536
	ds_read_b128 v[166:169], v238 offset:41568
	s_waitcnt lgkmcnt(0)
	s_barrier
	v_mfma_f32_32x32x16_bf16 v[48:63], v[116:119], v[124:127], v[48:63]
	v_mfma_f32_32x32x16_bf16 v[32:47], v[116:119], v[154:157], v[32:47]
	s_waitcnt vmcnt(11)
	ds_write_b128 v235, v[76:79] offset:55296
	v_mfma_f32_32x32x16_bf16 v[16:31], v[134:137], v[124:127], v[16:31]
	global_load_dwordx4 v[76:79], v[194:195], off offset:896
	v_mfma_f32_32x32x16_bf16 v[0:15], v[134:137], v[154:157], v[0:15]
	s_waitcnt vmcnt(11)
	ds_write_b128 v235, v[80:83] offset:64512
	v_mfma_f32_32x32x16_bf16 v[48:63], v[112:115], v[120:123], v[48:63]
	global_load_dwordx4 v[80:83], v[198:199], off offset:896
	v_mfma_f32_32x32x16_bf16 v[32:47], v[112:115], v[142:145], v[32:47]
	s_waitcnt vmcnt(11)
	ds_write_b128 v239, v[88:91] offset:18432
	v_mfma_f32_32x32x16_bf16 v[16:31], v[130:133], v[120:123], v[16:31]
	global_load_dwordx4 v[88:91], v[200:201], off offset:896
	v_mfma_f32_32x32x16_bf16 v[0:15], v[130:133], v[142:145], v[0:15]
	s_waitcnt vmcnt(11)
	ds_write_b128 v239, v[92:95] offset:27648
	v_mfma_f32_32x32x16_bf16 v[48:63], v[138:141], v[170:173], v[48:63]
	global_load_dwordx4 v[92:95], v[202:203], off offset:896
	v_mfma_f32_32x32x16_bf16 v[32:47], v[138:141], v[174:177], v[32:47]
	s_waitcnt vmcnt(11)
	ds_write_b128 v240, v[104:107]
	v_mfma_f32_32x32x16_bf16 v[16:31], v[158:161], v[170:173], v[16:31]
	global_load_dwordx4 v[104:107], v[196:197], off offset:896
	v_mfma_f32_32x32x16_bf16 v[0:15], v[158:161], v[174:177], v[0:15]
	s_waitcnt vmcnt(11)
	ds_write_b128 v240, v[108:111] offset:9216
	v_mfma_f32_32x32x16_bf16 v[48:63], v[146:149], v[162:165], v[48:63]
	global_load_dwordx4 v[108:111], v[204:205], off offset:896
	v_mfma_f32_32x32x16_bf16 v[32:47], v[146:149], v[166:169], v[32:47]
	v_mfma_f32_32x32x16_bf16 v[16:31], v[150:153], v[162:165], v[16:31]
	v_mfma_f32_32x32x16_bf16 v[0:15], v[150:153], v[166:169], v[0:15]
	s_waitcnt lgkmcnt(0)
	s_barrier
	ds_read_b128 v[116:119], v237 offset:55296
	ds_read_b128 v[112:115], v237 offset:55328
	ds_read_b128 v[124:127], v241
	ds_read_b128 v[120:123], v241 offset:32
	ds_read_b128 v[134:137], v237 offset:59904
	ds_read_b128 v[130:133], v237 offset:59936
	ds_read_b128 v[154:157], v241 offset:4608
	ds_read_b128 v[142:145], v241 offset:4640
	ds_read_b128 v[138:141], v237 offset:55360
	ds_read_b128 v[146:149], v237 offset:55392
	ds_read_b128 v[158:161], v237 offset:59968
	ds_read_b128 v[150:153], v237 offset:60000
	ds_read_b128 v[170:173], v241 offset:64
	ds_read_b128 v[162:165], v241 offset:96
	ds_read_b128 v[174:177], v241 offset:4672
	ds_read_b128 v[166:169], v241 offset:4704
	s_waitcnt lgkmcnt(0)
	s_barrier
	v_mfma_f32_32x32x16_bf16 v[48:63], v[116:119], v[124:127], v[48:63]
	v_mfma_f32_32x32x16_bf16 v[32:47], v[116:119], v[154:157], v[32:47]
	s_waitcnt vmcnt(11)
	ds_write_b128 v235, v[64:67]
	v_mfma_f32_32x32x16_bf16 v[16:31], v[134:137], v[124:127], v[16:31]
	global_load_dwordx4 v[64:67], v[194:195], off offset:1024
	v_mfma_f32_32x32x16_bf16 v[0:15], v[134:137], v[154:157], v[0:15]
	s_waitcnt vmcnt(11)
	ds_write_b128 v235, v[68:71] offset:9216
	v_mfma_f32_32x32x16_bf16 v[48:63], v[112:115], v[120:123], v[48:63]
	global_load_dwordx4 v[68:71], v[198:199], off offset:1024
	v_mfma_f32_32x32x16_bf16 v[32:47], v[112:115], v[142:145], v[32:47]
	s_waitcnt vmcnt(11)
	ds_write_b128 v235, v[84:87] offset:18432
	v_mfma_f32_32x32x16_bf16 v[16:31], v[130:133], v[120:123], v[16:31]
	global_load_dwordx4 v[84:87], v[200:201], off offset:1024
	v_mfma_f32_32x32x16_bf16 v[0:15], v[130:133], v[142:145], v[0:15]
	s_waitcnt vmcnt(11)
	ds_write_b128 v235, v[72:75] offset:27648
	v_mfma_f32_32x32x16_bf16 v[48:63], v[138:141], v[170:173], v[48:63]
	global_load_dwordx4 v[72:75], v[202:203], off offset:1024
	v_mfma_f32_32x32x16_bf16 v[32:47], v[138:141], v[174:177], v[32:47]
	s_waitcnt vmcnt(11)
	ds_write_b128 v235, v[96:99] offset:36864
	v_mfma_f32_32x32x16_bf16 v[16:31], v[158:161], v[170:173], v[16:31]
	global_load_dwordx4 v[96:99], v[196:197], off offset:1024
	v_mfma_f32_32x32x16_bf16 v[0:15], v[158:161], v[174:177], v[0:15]
	s_waitcnt vmcnt(11)
	ds_write_b128 v235, v[100:103] offset:46080
	v_mfma_f32_32x32x16_bf16 v[48:63], v[146:149], v[162:165], v[48:63]
	global_load_dwordx4 v[100:103], v[204:205], off offset:1024
	v_mfma_f32_32x32x16_bf16 v[32:47], v[146:149], v[166:169], v[32:47]
	v_mfma_f32_32x32x16_bf16 v[16:31], v[150:153], v[162:165], v[16:31]
	v_mfma_f32_32x32x16_bf16 v[0:15], v[150:153], v[166:169], v[0:15]
	s_waitcnt lgkmcnt(0)
	s_barrier
	ds_read_b128 v[116:119], v237
	ds_read_b128 v[112:115], v237 offset:32
	ds_read_b128 v[124:127], v238 offset:36864
	ds_read_b128 v[120:123], v238 offset:36896
	ds_read_b128 v[134:137], v237 offset:4608
	ds_read_b128 v[130:133], v237 offset:4640
	ds_read_b128 v[154:157], v238 offset:41472
	ds_read_b128 v[142:145], v238 offset:41504
	ds_read_b128 v[138:141], v237 offset:64
	ds_read_b128 v[146:149], v237 offset:96
	ds_read_b128 v[158:161], v237 offset:4672
	ds_read_b128 v[150:153], v237 offset:4704
	ds_read_b128 v[170:173], v238 offset:36928
	ds_read_b128 v[162:165], v238 offset:36960
	ds_read_b128 v[174:177], v238 offset:41536
	ds_read_b128 v[166:169], v238 offset:41568
	s_waitcnt lgkmcnt(0)
	s_barrier
	v_mfma_f32_32x32x16_bf16 v[48:63], v[116:119], v[124:127], v[48:63]
	v_mfma_f32_32x32x16_bf16 v[32:47], v[116:119], v[154:157], v[32:47]
	s_waitcnt vmcnt(11)
	ds_write_b128 v235, v[76:79] offset:55296
	v_mfma_f32_32x32x16_bf16 v[16:31], v[134:137], v[124:127], v[16:31]
	global_load_dwordx4 v[76:79], v[194:195], off offset:1152
	v_mfma_f32_32x32x16_bf16 v[0:15], v[134:137], v[154:157], v[0:15]
	s_waitcnt vmcnt(11)
	ds_write_b128 v235, v[80:83] offset:64512
	v_mfma_f32_32x32x16_bf16 v[48:63], v[112:115], v[120:123], v[48:63]
	global_load_dwordx4 v[80:83], v[198:199], off offset:1152
	v_mfma_f32_32x32x16_bf16 v[32:47], v[112:115], v[142:145], v[32:47]
	s_waitcnt vmcnt(11)
	ds_write_b128 v239, v[88:91] offset:18432
	v_mfma_f32_32x32x16_bf16 v[16:31], v[130:133], v[120:123], v[16:31]
	global_load_dwordx4 v[88:91], v[200:201], off offset:1152
	v_mfma_f32_32x32x16_bf16 v[0:15], v[130:133], v[142:145], v[0:15]
	s_waitcnt vmcnt(11)
	ds_write_b128 v239, v[92:95] offset:27648
	v_mfma_f32_32x32x16_bf16 v[48:63], v[138:141], v[170:173], v[48:63]
	global_load_dwordx4 v[92:95], v[202:203], off offset:1152
	v_mfma_f32_32x32x16_bf16 v[32:47], v[138:141], v[174:177], v[32:47]
	s_waitcnt vmcnt(11)
	ds_write_b128 v240, v[104:107]
	v_mfma_f32_32x32x16_bf16 v[16:31], v[158:161], v[170:173], v[16:31]
	global_load_dwordx4 v[104:107], v[196:197], off offset:1152
	v_mfma_f32_32x32x16_bf16 v[0:15], v[158:161], v[174:177], v[0:15]
	s_waitcnt vmcnt(11)
	ds_write_b128 v240, v[108:111] offset:9216
	v_mfma_f32_32x32x16_bf16 v[48:63], v[146:149], v[162:165], v[48:63]
	global_load_dwordx4 v[108:111], v[204:205], off offset:1152
	v_mfma_f32_32x32x16_bf16 v[32:47], v[146:149], v[166:169], v[32:47]
	v_mfma_f32_32x32x16_bf16 v[16:31], v[150:153], v[162:165], v[16:31]
	v_mfma_f32_32x32x16_bf16 v[0:15], v[150:153], v[166:169], v[0:15]
	s_waitcnt lgkmcnt(0)
	s_barrier
	ds_read_b128 v[116:119], v237 offset:55296
	ds_read_b128 v[112:115], v237 offset:55328
	ds_read_b128 v[124:127], v241
	ds_read_b128 v[120:123], v241 offset:32
	ds_read_b128 v[134:137], v237 offset:59904
	ds_read_b128 v[130:133], v237 offset:59936
	ds_read_b128 v[154:157], v241 offset:4608
	ds_read_b128 v[142:145], v241 offset:4640
	ds_read_b128 v[138:141], v237 offset:55360
	ds_read_b128 v[146:149], v237 offset:55392
	ds_read_b128 v[158:161], v237 offset:59968
	ds_read_b128 v[150:153], v237 offset:60000
	ds_read_b128 v[170:173], v241 offset:64
	ds_read_b128 v[162:165], v241 offset:96
	ds_read_b128 v[174:177], v241 offset:4672
	ds_read_b128 v[166:169], v241 offset:4704
	s_waitcnt lgkmcnt(0)
	s_barrier
	v_mfma_f32_32x32x16_bf16 v[48:63], v[116:119], v[124:127], v[48:63]
	v_mfma_f32_32x32x16_bf16 v[32:47], v[116:119], v[154:157], v[32:47]
	s_waitcnt vmcnt(11)
	ds_write_b128 v235, v[64:67]
	v_mfma_f32_32x32x16_bf16 v[16:31], v[134:137], v[124:127], v[16:31]
	global_load_dwordx4 v[64:67], v[194:195], off offset:1280
	v_mfma_f32_32x32x16_bf16 v[0:15], v[134:137], v[154:157], v[0:15]
	s_waitcnt vmcnt(11)
	ds_write_b128 v235, v[68:71] offset:9216
	v_mfma_f32_32x32x16_bf16 v[48:63], v[112:115], v[120:123], v[48:63]
	global_load_dwordx4 v[68:71], v[198:199], off offset:1280
	v_mfma_f32_32x32x16_bf16 v[32:47], v[112:115], v[142:145], v[32:47]
	s_waitcnt vmcnt(11)
	ds_write_b128 v235, v[84:87] offset:18432
	v_mfma_f32_32x32x16_bf16 v[16:31], v[130:133], v[120:123], v[16:31]
	global_load_dwordx4 v[84:87], v[200:201], off offset:1280
	v_mfma_f32_32x32x16_bf16 v[0:15], v[130:133], v[142:145], v[0:15]
	s_waitcnt vmcnt(11)
	ds_write_b128 v235, v[72:75] offset:27648
	v_mfma_f32_32x32x16_bf16 v[48:63], v[138:141], v[170:173], v[48:63]
	global_load_dwordx4 v[72:75], v[202:203], off offset:1280
	v_mfma_f32_32x32x16_bf16 v[32:47], v[138:141], v[174:177], v[32:47]
	s_waitcnt vmcnt(11)
	ds_write_b128 v235, v[96:99] offset:36864
	v_mfma_f32_32x32x16_bf16 v[16:31], v[158:161], v[170:173], v[16:31]
	global_load_dwordx4 v[96:99], v[196:197], off offset:1280
	v_mfma_f32_32x32x16_bf16 v[0:15], v[158:161], v[174:177], v[0:15]
	s_waitcnt vmcnt(11)
	ds_write_b128 v235, v[100:103] offset:46080
	v_mfma_f32_32x32x16_bf16 v[48:63], v[146:149], v[162:165], v[48:63]
	global_load_dwordx4 v[100:103], v[204:205], off offset:1280
	v_mfma_f32_32x32x16_bf16 v[32:47], v[146:149], v[166:169], v[32:47]
	v_mfma_f32_32x32x16_bf16 v[16:31], v[150:153], v[162:165], v[16:31]
	v_mfma_f32_32x32x16_bf16 v[0:15], v[150:153], v[166:169], v[0:15]
	s_waitcnt lgkmcnt(0)
	s_barrier
	ds_read_b128 v[116:119], v237
	ds_read_b128 v[112:115], v237 offset:32
	ds_read_b128 v[124:127], v238 offset:36864
	ds_read_b128 v[120:123], v238 offset:36896
	ds_read_b128 v[134:137], v237 offset:4608
	ds_read_b128 v[130:133], v237 offset:4640
	ds_read_b128 v[154:157], v238 offset:41472
	ds_read_b128 v[142:145], v238 offset:41504
	ds_read_b128 v[138:141], v237 offset:64
	ds_read_b128 v[146:149], v237 offset:96
	ds_read_b128 v[158:161], v237 offset:4672
	ds_read_b128 v[150:153], v237 offset:4704
	ds_read_b128 v[170:173], v238 offset:36928
	ds_read_b128 v[162:165], v238 offset:36960
	ds_read_b128 v[174:177], v238 offset:41536
	ds_read_b128 v[166:169], v238 offset:41568
	s_waitcnt lgkmcnt(0)
	s_barrier
	v_mfma_f32_32x32x16_bf16 v[48:63], v[116:119], v[124:127], v[48:63]
	v_mfma_f32_32x32x16_bf16 v[32:47], v[116:119], v[154:157], v[32:47]
	s_waitcnt vmcnt(11)
	ds_write_b128 v235, v[76:79] offset:55296
	v_mfma_f32_32x32x16_bf16 v[16:31], v[134:137], v[124:127], v[16:31]
	global_load_dwordx4 v[76:79], v[194:195], off offset:1408
	v_mfma_f32_32x32x16_bf16 v[0:15], v[134:137], v[154:157], v[0:15]
	s_waitcnt vmcnt(11)
	ds_write_b128 v235, v[80:83] offset:64512
	v_mfma_f32_32x32x16_bf16 v[48:63], v[112:115], v[120:123], v[48:63]
	global_load_dwordx4 v[80:83], v[198:199], off offset:1408
	v_mfma_f32_32x32x16_bf16 v[32:47], v[112:115], v[142:145], v[32:47]
	s_waitcnt vmcnt(11)
	ds_write_b128 v239, v[88:91] offset:18432
	v_mfma_f32_32x32x16_bf16 v[16:31], v[130:133], v[120:123], v[16:31]
	global_load_dwordx4 v[88:91], v[200:201], off offset:1408
	v_mfma_f32_32x32x16_bf16 v[0:15], v[130:133], v[142:145], v[0:15]
	s_waitcnt vmcnt(11)
	ds_write_b128 v239, v[92:95] offset:27648
	v_mfma_f32_32x32x16_bf16 v[48:63], v[138:141], v[170:173], v[48:63]
	global_load_dwordx4 v[92:95], v[202:203], off offset:1408
	v_mfma_f32_32x32x16_bf16 v[32:47], v[138:141], v[174:177], v[32:47]
	s_waitcnt vmcnt(11)
	ds_write_b128 v240, v[104:107]
	v_mfma_f32_32x32x16_bf16 v[16:31], v[158:161], v[170:173], v[16:31]
	global_load_dwordx4 v[104:107], v[196:197], off offset:1408
	v_mfma_f32_32x32x16_bf16 v[0:15], v[158:161], v[174:177], v[0:15]
	s_waitcnt vmcnt(11)
	ds_write_b128 v240, v[108:111] offset:9216
	v_mfma_f32_32x32x16_bf16 v[48:63], v[146:149], v[162:165], v[48:63]
	global_load_dwordx4 v[108:111], v[204:205], off offset:1408
	v_mfma_f32_32x32x16_bf16 v[32:47], v[146:149], v[166:169], v[32:47]
	v_mfma_f32_32x32x16_bf16 v[16:31], v[150:153], v[162:165], v[16:31]
	v_mfma_f32_32x32x16_bf16 v[0:15], v[150:153], v[166:169], v[0:15]
	s_waitcnt lgkmcnt(0)
	s_barrier
	ds_read_b128 v[116:119], v237 offset:55296
	ds_read_b128 v[112:115], v237 offset:55328
	ds_read_b128 v[124:127], v241
	ds_read_b128 v[120:123], v241 offset:32
	ds_read_b128 v[134:137], v237 offset:59904
	ds_read_b128 v[130:133], v237 offset:59936
	ds_read_b128 v[154:157], v241 offset:4608
	ds_read_b128 v[142:145], v241 offset:4640
	ds_read_b128 v[138:141], v237 offset:55360
	ds_read_b128 v[146:149], v237 offset:55392
	ds_read_b128 v[158:161], v237 offset:59968
	ds_read_b128 v[150:153], v237 offset:60000
	ds_read_b128 v[170:173], v241 offset:64
	ds_read_b128 v[162:165], v241 offset:96
	ds_read_b128 v[174:177], v241 offset:4672
	ds_read_b128 v[166:169], v241 offset:4704
	s_waitcnt lgkmcnt(0)
	s_barrier
	v_mfma_f32_32x32x16_bf16 v[48:63], v[116:119], v[124:127], v[48:63]
	v_mfma_f32_32x32x16_bf16 v[32:47], v[116:119], v[154:157], v[32:47]
	s_waitcnt vmcnt(11)
	ds_write_b128 v235, v[64:67]
	v_mfma_f32_32x32x16_bf16 v[16:31], v[134:137], v[124:127], v[16:31]
	global_load_dwordx4 v[64:67], v[194:195], off offset:1536
	v_mfma_f32_32x32x16_bf16 v[0:15], v[134:137], v[154:157], v[0:15]
	s_waitcnt vmcnt(11)
	ds_write_b128 v235, v[68:71] offset:9216
	v_mfma_f32_32x32x16_bf16 v[48:63], v[112:115], v[120:123], v[48:63]
	global_load_dwordx4 v[68:71], v[198:199], off offset:1536
	v_mfma_f32_32x32x16_bf16 v[32:47], v[112:115], v[142:145], v[32:47]
	s_waitcnt vmcnt(11)
	ds_write_b128 v235, v[84:87] offset:18432
	v_mfma_f32_32x32x16_bf16 v[16:31], v[130:133], v[120:123], v[16:31]
	global_load_dwordx4 v[84:87], v[200:201], off offset:1536
	v_mfma_f32_32x32x16_bf16 v[0:15], v[130:133], v[142:145], v[0:15]
	s_waitcnt vmcnt(11)
	ds_write_b128 v235, v[72:75] offset:27648
	v_mfma_f32_32x32x16_bf16 v[48:63], v[138:141], v[170:173], v[48:63]
	global_load_dwordx4 v[72:75], v[202:203], off offset:1536
	v_mfma_f32_32x32x16_bf16 v[32:47], v[138:141], v[174:177], v[32:47]
	s_waitcnt vmcnt(11)
	ds_write_b128 v235, v[96:99] offset:36864
	v_mfma_f32_32x32x16_bf16 v[16:31], v[158:161], v[170:173], v[16:31]
	global_load_dwordx4 v[96:99], v[196:197], off offset:1536
	v_mfma_f32_32x32x16_bf16 v[0:15], v[158:161], v[174:177], v[0:15]
	s_waitcnt vmcnt(11)
	ds_write_b128 v235, v[100:103] offset:46080
	v_mfma_f32_32x32x16_bf16 v[48:63], v[146:149], v[162:165], v[48:63]
	global_load_dwordx4 v[100:103], v[204:205], off offset:1536
	v_mfma_f32_32x32x16_bf16 v[32:47], v[146:149], v[166:169], v[32:47]
	v_mfma_f32_32x32x16_bf16 v[16:31], v[150:153], v[162:165], v[16:31]
	v_mfma_f32_32x32x16_bf16 v[0:15], v[150:153], v[166:169], v[0:15]
	s_waitcnt lgkmcnt(0)
	s_barrier
	ds_read_b128 v[116:119], v237
	ds_read_b128 v[112:115], v237 offset:32
	ds_read_b128 v[124:127], v238 offset:36864
	ds_read_b128 v[120:123], v238 offset:36896
	ds_read_b128 v[134:137], v237 offset:4608
	ds_read_b128 v[130:133], v237 offset:4640
	ds_read_b128 v[154:157], v238 offset:41472
	ds_read_b128 v[142:145], v238 offset:41504
	ds_read_b128 v[138:141], v237 offset:64
	ds_read_b128 v[146:149], v237 offset:96
	ds_read_b128 v[158:161], v237 offset:4672
	ds_read_b128 v[150:153], v237 offset:4704
	ds_read_b128 v[170:173], v238 offset:36928
	ds_read_b128 v[162:165], v238 offset:36960
	ds_read_b128 v[174:177], v238 offset:41536
	ds_read_b128 v[166:169], v238 offset:41568
	s_waitcnt lgkmcnt(0)
	s_barrier
	v_mfma_f32_32x32x16_bf16 v[48:63], v[116:119], v[124:127], v[48:63]
	v_mfma_f32_32x32x16_bf16 v[32:47], v[116:119], v[154:157], v[32:47]
	s_waitcnt vmcnt(11)
	ds_write_b128 v235, v[76:79] offset:55296
	v_mfma_f32_32x32x16_bf16 v[16:31], v[134:137], v[124:127], v[16:31]
	global_load_dwordx4 v[76:79], v[194:195], off offset:1664
	v_mfma_f32_32x32x16_bf16 v[0:15], v[134:137], v[154:157], v[0:15]
	s_waitcnt vmcnt(11)
	ds_write_b128 v235, v[80:83] offset:64512
	v_mfma_f32_32x32x16_bf16 v[48:63], v[112:115], v[120:123], v[48:63]
	global_load_dwordx4 v[80:83], v[198:199], off offset:1664
	v_mfma_f32_32x32x16_bf16 v[32:47], v[112:115], v[142:145], v[32:47]
	s_waitcnt vmcnt(11)
	ds_write_b128 v239, v[88:91] offset:18432
	v_mfma_f32_32x32x16_bf16 v[16:31], v[130:133], v[120:123], v[16:31]
	global_load_dwordx4 v[88:91], v[200:201], off offset:1664
	v_mfma_f32_32x32x16_bf16 v[0:15], v[130:133], v[142:145], v[0:15]
	s_waitcnt vmcnt(11)
	ds_write_b128 v239, v[92:95] offset:27648
	v_mfma_f32_32x32x16_bf16 v[48:63], v[138:141], v[170:173], v[48:63]
	global_load_dwordx4 v[92:95], v[202:203], off offset:1664
	v_mfma_f32_32x32x16_bf16 v[32:47], v[138:141], v[174:177], v[32:47]
	s_waitcnt vmcnt(11)
	ds_write_b128 v240, v[104:107]
	v_mfma_f32_32x32x16_bf16 v[16:31], v[158:161], v[170:173], v[16:31]
	global_load_dwordx4 v[104:107], v[196:197], off offset:1664
	v_mfma_f32_32x32x16_bf16 v[0:15], v[158:161], v[174:177], v[0:15]
	s_waitcnt vmcnt(11)
	ds_write_b128 v240, v[108:111] offset:9216
	v_mfma_f32_32x32x16_bf16 v[48:63], v[146:149], v[162:165], v[48:63]
	global_load_dwordx4 v[108:111], v[204:205], off offset:1664
	v_mfma_f32_32x32x16_bf16 v[32:47], v[146:149], v[166:169], v[32:47]
	v_mfma_f32_32x32x16_bf16 v[16:31], v[150:153], v[162:165], v[16:31]
	v_mfma_f32_32x32x16_bf16 v[0:15], v[150:153], v[166:169], v[0:15]
	s_waitcnt lgkmcnt(0)
	s_barrier
	ds_read_b128 v[116:119], v237 offset:55296
	ds_read_b128 v[112:115], v237 offset:55328
	ds_read_b128 v[124:127], v241
	ds_read_b128 v[120:123], v241 offset:32
	ds_read_b128 v[134:137], v237 offset:59904
	ds_read_b128 v[130:133], v237 offset:59936
	ds_read_b128 v[154:157], v241 offset:4608
	ds_read_b128 v[142:145], v241 offset:4640
	ds_read_b128 v[138:141], v237 offset:55360
	ds_read_b128 v[146:149], v237 offset:55392
	ds_read_b128 v[158:161], v237 offset:59968
	ds_read_b128 v[150:153], v237 offset:60000
	ds_read_b128 v[170:173], v241 offset:64
	ds_read_b128 v[162:165], v241 offset:96
	ds_read_b128 v[174:177], v241 offset:4672
	ds_read_b128 v[166:169], v241 offset:4704
	s_waitcnt lgkmcnt(0)
	s_barrier
	v_mfma_f32_32x32x16_bf16 v[48:63], v[116:119], v[124:127], v[48:63]
	v_mfma_f32_32x32x16_bf16 v[32:47], v[116:119], v[154:157], v[32:47]
	s_waitcnt vmcnt(11)
	ds_write_b128 v235, v[64:67]
	v_mfma_f32_32x32x16_bf16 v[16:31], v[134:137], v[124:127], v[16:31]
	global_load_dwordx4 v[64:67], v[194:195], off offset:1792
	v_mfma_f32_32x32x16_bf16 v[0:15], v[134:137], v[154:157], v[0:15]
	s_waitcnt vmcnt(11)
	ds_write_b128 v235, v[68:71] offset:9216
	v_mfma_f32_32x32x16_bf16 v[48:63], v[112:115], v[120:123], v[48:63]
	global_load_dwordx4 v[68:71], v[198:199], off offset:1792
	v_mfma_f32_32x32x16_bf16 v[32:47], v[112:115], v[142:145], v[32:47]
	s_waitcnt vmcnt(11)
	ds_write_b128 v235, v[84:87] offset:18432
	v_mfma_f32_32x32x16_bf16 v[16:31], v[130:133], v[120:123], v[16:31]
	global_load_dwordx4 v[84:87], v[200:201], off offset:1792
	v_mfma_f32_32x32x16_bf16 v[0:15], v[130:133], v[142:145], v[0:15]
	s_waitcnt vmcnt(11)
	ds_write_b128 v235, v[72:75] offset:27648
	v_mfma_f32_32x32x16_bf16 v[48:63], v[138:141], v[170:173], v[48:63]
	global_load_dwordx4 v[72:75], v[202:203], off offset:1792
	v_mfma_f32_32x32x16_bf16 v[32:47], v[138:141], v[174:177], v[32:47]
	s_waitcnt vmcnt(11)
	ds_write_b128 v235, v[96:99] offset:36864
	v_mfma_f32_32x32x16_bf16 v[16:31], v[158:161], v[170:173], v[16:31]
	global_load_dwordx4 v[96:99], v[196:197], off offset:1792
	v_mfma_f32_32x32x16_bf16 v[0:15], v[158:161], v[174:177], v[0:15]
	s_waitcnt vmcnt(11)
	ds_write_b128 v235, v[100:103] offset:46080
	v_mfma_f32_32x32x16_bf16 v[48:63], v[146:149], v[162:165], v[48:63]
	global_load_dwordx4 v[100:103], v[204:205], off offset:1792
	v_mfma_f32_32x32x16_bf16 v[32:47], v[146:149], v[166:169], v[32:47]
	v_mfma_f32_32x32x16_bf16 v[16:31], v[150:153], v[162:165], v[16:31]
	v_mfma_f32_32x32x16_bf16 v[0:15], v[150:153], v[166:169], v[0:15]
	s_waitcnt lgkmcnt(0)
	s_barrier
	ds_read_b128 v[116:119], v237
	ds_read_b128 v[112:115], v237 offset:32
	ds_read_b128 v[124:127], v238 offset:36864
	ds_read_b128 v[120:123], v238 offset:36896
	ds_read_b128 v[134:137], v237 offset:4608
	ds_read_b128 v[130:133], v237 offset:4640
	ds_read_b128 v[154:157], v238 offset:41472
	ds_read_b128 v[142:145], v238 offset:41504
	ds_read_b128 v[138:141], v237 offset:64
	ds_read_b128 v[146:149], v237 offset:96
	ds_read_b128 v[158:161], v237 offset:4672
	ds_read_b128 v[150:153], v237 offset:4704
	ds_read_b128 v[170:173], v238 offset:36928
	ds_read_b128 v[162:165], v238 offset:36960
	ds_read_b128 v[174:177], v238 offset:41536
	ds_read_b128 v[166:169], v238 offset:41568
	s_waitcnt lgkmcnt(0)
	s_barrier
	v_mfma_f32_32x32x16_bf16 v[48:63], v[116:119], v[124:127], v[48:63]
	v_mfma_f32_32x32x16_bf16 v[32:47], v[116:119], v[154:157], v[32:47]
	s_waitcnt vmcnt(11)
	ds_write_b128 v235, v[76:79] offset:55296
	v_mfma_f32_32x32x16_bf16 v[16:31], v[134:137], v[124:127], v[16:31]
	global_load_dwordx4 v[76:79], v[194:195], off offset:1920
	v_mfma_f32_32x32x16_bf16 v[0:15], v[134:137], v[154:157], v[0:15]
	s_waitcnt vmcnt(11)
	ds_write_b128 v235, v[80:83] offset:64512
	v_mfma_f32_32x32x16_bf16 v[48:63], v[112:115], v[120:123], v[48:63]
	global_load_dwordx4 v[80:83], v[198:199], off offset:1920
	v_mfma_f32_32x32x16_bf16 v[32:47], v[112:115], v[142:145], v[32:47]
	s_waitcnt vmcnt(11)
	ds_write_b128 v239, v[88:91] offset:18432
	v_mfma_f32_32x32x16_bf16 v[16:31], v[130:133], v[120:123], v[16:31]
	global_load_dwordx4 v[88:91], v[200:201], off offset:1920
	v_mfma_f32_32x32x16_bf16 v[0:15], v[130:133], v[142:145], v[0:15]
	s_waitcnt vmcnt(11)
	ds_write_b128 v239, v[92:95] offset:27648
	v_mfma_f32_32x32x16_bf16 v[48:63], v[138:141], v[170:173], v[48:63]
	global_load_dwordx4 v[92:95], v[202:203], off offset:1920
	v_mfma_f32_32x32x16_bf16 v[32:47], v[138:141], v[174:177], v[32:47]
	s_waitcnt vmcnt(11)
	ds_write_b128 v240, v[104:107]
	v_mfma_f32_32x32x16_bf16 v[16:31], v[158:161], v[170:173], v[16:31]
	global_load_dwordx4 v[104:107], v[196:197], off offset:1920
	v_mfma_f32_32x32x16_bf16 v[0:15], v[158:161], v[174:177], v[0:15]
	s_waitcnt vmcnt(11)
	ds_write_b128 v240, v[108:111] offset:9216
	v_mfma_f32_32x32x16_bf16 v[48:63], v[146:149], v[162:165], v[48:63]
	global_load_dwordx4 v[108:111], v[204:205], off offset:1920
	v_mfma_f32_32x32x16_bf16 v[32:47], v[146:149], v[166:169], v[32:47]
	v_mfma_f32_32x32x16_bf16 v[16:31], v[150:153], v[162:165], v[16:31]
	v_mfma_f32_32x32x16_bf16 v[0:15], v[150:153], v[166:169], v[0:15]
	s_waitcnt lgkmcnt(0)
	s_barrier
	ds_read_b128 v[116:119], v237 offset:55296
	ds_read_b128 v[112:115], v237 offset:55328
	ds_read_b128 v[124:127], v241
	ds_read_b128 v[120:123], v241 offset:32
	ds_read_b128 v[134:137], v237 offset:59904
	ds_read_b128 v[130:133], v237 offset:59936
	ds_read_b128 v[154:157], v241 offset:4608
	ds_read_b128 v[142:145], v241 offset:4640
	ds_read_b128 v[138:141], v237 offset:55360
	ds_read_b128 v[146:149], v237 offset:55392
	ds_read_b128 v[158:161], v237 offset:59968
	ds_read_b128 v[150:153], v237 offset:60000
	ds_read_b128 v[170:173], v241 offset:64
	ds_read_b128 v[162:165], v241 offset:96
	ds_read_b128 v[174:177], v241 offset:4672
	ds_read_b128 v[166:169], v241 offset:4704
	s_waitcnt lgkmcnt(0)
	s_barrier
	v_mfma_f32_32x32x16_bf16 v[48:63], v[116:119], v[124:127], v[48:63]
	v_mfma_f32_32x32x16_bf16 v[32:47], v[116:119], v[154:157], v[32:47]
	s_waitcnt vmcnt(11)
	ds_write_b128 v235, v[64:67]
	v_mfma_f32_32x32x16_bf16 v[16:31], v[134:137], v[124:127], v[16:31]
	v_mfma_f32_32x32x16_bf16 v[0:15], v[134:137], v[154:157], v[0:15]
	s_waitcnt vmcnt(10)
	ds_write_b128 v235, v[68:71] offset:9216
	v_mfma_f32_32x32x16_bf16 v[48:63], v[112:115], v[120:123], v[48:63]
	v_mfma_f32_32x32x16_bf16 v[32:47], v[112:115], v[142:145], v[32:47]
	s_waitcnt vmcnt(9)
	ds_write_b128 v235, v[84:87] offset:18432
	v_mfma_f32_32x32x16_bf16 v[16:31], v[130:133], v[120:123], v[16:31]
	v_mfma_f32_32x32x16_bf16 v[0:15], v[130:133], v[142:145], v[0:15]
	s_waitcnt vmcnt(8)
	ds_write_b128 v235, v[72:75] offset:27648
	v_mfma_f32_32x32x16_bf16 v[48:63], v[138:141], v[170:173], v[48:63]
	v_mfma_f32_32x32x16_bf16 v[32:47], v[138:141], v[174:177], v[32:47]
	s_waitcnt vmcnt(7)
	ds_write_b128 v235, v[96:99] offset:36864
	v_mfma_f32_32x32x16_bf16 v[16:31], v[158:161], v[170:173], v[16:31]
	v_mfma_f32_32x32x16_bf16 v[0:15], v[158:161], v[174:177], v[0:15]
	s_waitcnt vmcnt(6)
	ds_write_b128 v235, v[100:103] offset:46080
	v_mfma_f32_32x32x16_bf16 v[48:63], v[146:149], v[162:165], v[48:63]
	v_mfma_f32_32x32x16_bf16 v[32:47], v[146:149], v[166:169], v[32:47]
	v_mfma_f32_32x32x16_bf16 v[16:31], v[150:153], v[162:165], v[16:31]
	v_mfma_f32_32x32x16_bf16 v[0:15], v[150:153], v[166:169], v[0:15]
	s_waitcnt lgkmcnt(0)
	s_barrier
	ds_read_b128 v[116:119], v237
	ds_read_b128 v[112:115], v237 offset:32
	ds_read_b128 v[124:127], v238 offset:36864
	ds_read_b128 v[120:123], v238 offset:36896
	ds_read_b128 v[134:137], v237 offset:4608
	ds_read_b128 v[130:133], v237 offset:4640
	ds_read_b128 v[154:157], v238 offset:41472
	ds_read_b128 v[142:145], v238 offset:41504
	ds_read_b128 v[138:141], v237 offset:64
	ds_read_b128 v[146:149], v237 offset:96
	ds_read_b128 v[158:161], v237 offset:4672
	ds_read_b128 v[150:153], v237 offset:4704
	ds_read_b128 v[170:173], v238 offset:36928
	ds_read_b128 v[162:165], v238 offset:36960
	ds_read_b128 v[174:177], v238 offset:41536
	ds_read_b128 v[166:169], v238 offset:41568
	s_waitcnt lgkmcnt(0)
	s_barrier
	v_mfma_f32_32x32x16_bf16 v[48:63], v[116:119], v[124:127], v[48:63]
	v_mfma_f32_32x32x16_bf16 v[32:47], v[116:119], v[154:157], v[32:47]
	s_waitcnt vmcnt(5)
	ds_write_b128 v235, v[76:79] offset:55296
	v_mfma_f32_32x32x16_bf16 v[16:31], v[134:137], v[124:127], v[16:31]
	v_mfma_f32_32x32x16_bf16 v[0:15], v[134:137], v[154:157], v[0:15]
	s_waitcnt vmcnt(4)
	ds_write_b128 v235, v[80:83] offset:64512
	v_mfma_f32_32x32x16_bf16 v[48:63], v[112:115], v[120:123], v[48:63]
	v_mfma_f32_32x32x16_bf16 v[32:47], v[112:115], v[142:145], v[32:47]
	s_waitcnt vmcnt(3)
	ds_write_b128 v239, v[88:91] offset:18432
	v_mfma_f32_32x32x16_bf16 v[16:31], v[130:133], v[120:123], v[16:31]
	v_mfma_f32_32x32x16_bf16 v[0:15], v[130:133], v[142:145], v[0:15]
	s_waitcnt vmcnt(2)
	ds_write_b128 v239, v[92:95] offset:27648
	v_mfma_f32_32x32x16_bf16 v[48:63], v[138:141], v[170:173], v[48:63]
	v_mfma_f32_32x32x16_bf16 v[32:47], v[138:141], v[174:177], v[32:47]
	s_waitcnt vmcnt(1)
	ds_write_b128 v240, v[104:107]
	v_mfma_f32_32x32x16_bf16 v[16:31], v[158:161], v[170:173], v[16:31]
	v_mfma_f32_32x32x16_bf16 v[0:15], v[158:161], v[174:177], v[0:15]
	s_waitcnt vmcnt(0)
	ds_write_b128 v240, v[108:111] offset:9216
	v_mfma_f32_32x32x16_bf16 v[48:63], v[146:149], v[162:165], v[48:63]
	v_mfma_f32_32x32x16_bf16 v[32:47], v[146:149], v[166:169], v[32:47]
	v_mfma_f32_32x32x16_bf16 v[16:31], v[150:153], v[162:165], v[16:31]
	v_mfma_f32_32x32x16_bf16 v[0:15], v[150:153], v[166:169], v[0:15]
	s_waitcnt lgkmcnt(0)
	s_barrier
	ds_read_b128 v[116:119], v237 offset:55296
	ds_read_b128 v[112:115], v237 offset:55328
	ds_read_b128 v[124:127], v241
	ds_read_b128 v[120:123], v241 offset:32
	ds_read_b128 v[134:137], v237 offset:59904
	ds_read_b128 v[130:133], v237 offset:59936
	ds_read_b128 v[154:157], v241 offset:4608
	ds_read_b128 v[142:145], v241 offset:4640
	ds_read_b128 v[138:141], v237 offset:55360
	ds_read_b128 v[146:149], v237 offset:55392
	ds_read_b128 v[158:161], v237 offset:59968
	ds_read_b128 v[150:153], v237 offset:60000
	ds_read_b128 v[170:173], v241 offset:64
	ds_read_b128 v[162:165], v241 offset:96
	ds_read_b128 v[174:177], v241 offset:4672
	ds_read_b128 v[166:169], v241 offset:4704
	s_waitcnt lgkmcnt(0)
	s_barrier
	v_mfma_f32_32x32x16_bf16 v[48:63], v[116:119], v[124:127], v[48:63]
	v_mfma_f32_32x32x16_bf16 v[32:47], v[116:119], v[154:157], v[32:47]
	v_mfma_f32_32x32x16_bf16 v[16:31], v[134:137], v[124:127], v[16:31]
	v_mfma_f32_32x32x16_bf16 v[0:15], v[134:137], v[154:157], v[0:15]
	v_mfma_f32_32x32x16_bf16 v[48:63], v[112:115], v[120:123], v[48:63]
	v_mfma_f32_32x32x16_bf16 v[32:47], v[112:115], v[142:145], v[32:47]
	v_mfma_f32_32x32x16_bf16 v[16:31], v[130:133], v[120:123], v[16:31]
	v_mfma_f32_32x32x16_bf16 v[0:15], v[130:133], v[142:145], v[0:15]
	v_mfma_f32_32x32x16_bf16 v[48:63], v[138:141], v[170:173], v[48:63]
	v_mfma_f32_32x32x16_bf16 v[32:47], v[138:141], v[174:177], v[32:47]
	v_mfma_f32_32x32x16_bf16 v[16:31], v[158:161], v[170:173], v[16:31]
	v_mfma_f32_32x32x16_bf16 v[0:15], v[158:161], v[174:177], v[0:15]
	v_mfma_f32_32x32x16_bf16 v[48:63], v[146:149], v[162:165], v[48:63]
	v_mfma_f32_32x32x16_bf16 v[32:47], v[146:149], v[166:169], v[32:47]
	v_mfma_f32_32x32x16_bf16 v[16:31], v[150:153], v[162:165], v[16:31]
	v_mfma_f32_32x32x16_bf16 v[0:15], v[150:153], v[166:169], v[0:15]
	s_waitcnt lgkmcnt(0)
	s_barrier
	s_waitcnt lgkmcnt(0)
	s_barrier
	s_branch .LBB0_191

.LBB0_1228:
	ds_read_b128 v[112:115], v203
	ds_read_b128 v[116:119], v203 offset:32
	ds_read_b128 v[120:123], v203 offset:4608
	ds_read_b128 v[124:127], v203 offset:4640
	ds_read_b128 v[130:133], v204 offset:36864
	ds_read_b128 v[134:137], v204 offset:36896
	ds_read_b128 v[138:141], v204 offset:41472
	ds_read_b128 v[142:145], v204 offset:41504
	ds_read_b128 v[146:149], v203 offset:64
	ds_read_b128 v[150:153], v203 offset:96
	ds_read_b128 v[154:157], v203 offset:4672
	ds_read_b128 v[158:161], v203 offset:4704
	ds_read_b128 v[162:165], v204 offset:36928
	ds_read_b128 v[166:169], v204 offset:36960
	ds_read_b128 v[170:173], v204 offset:41536
	ds_read_b128 v[174:177], v204 offset:41568
	s_waitcnt vmcnt(11)
	ds_write_b128 v201, v[64:67] offset:55296
	s_waitcnt vmcnt(10)
	ds_write_b128 v201, v[68:71] offset:64512
	s_waitcnt vmcnt(9)
	ds_write_b128 v205, v[80:83] offset:18432
	s_waitcnt vmcnt(8)
	ds_write_b128 v205, v[84:87] offset:27648
	s_waitcnt vmcnt(7)
	ds_write_b128 v234, v[96:99]
	s_waitcnt vmcnt(6)
	ds_write_b128 v234, v[100:103] offset:9216
	global_load_dwordx4 v[64:67], v[182:183], off offset:384
	global_load_dwordx4 v[68:71], v[186:187], off offset:384
	global_load_dwordx4 v[80:83], v[188:189], off offset:384
	global_load_dwordx4 v[84:87], v[190:191], off offset:384
	global_load_dwordx4 v[96:99], v[184:185], off offset:384
	global_load_dwordx4 v[100:103], v[192:193], off offset:384
	s_waitcnt lgkmcnt(0)
	s_barrier
	v_mfma_f32_32x32x16_bf16 v[48:63], v[112:115], v[130:133], v[48:63]
	v_mfma_f32_32x32x16_bf16 v[32:47], v[112:115], v[138:141], v[32:47]
	s_waitcnt vmcnt(11)
	ds_write_b128 v201, v[72:75]
	v_mfma_f32_32x32x16_bf16 v[16:31], v[120:123], v[130:133], v[16:31]
	global_load_dwordx4 v[72:75], v[182:183], off offset:512
	v_mfma_f32_32x32x16_bf16 v[0:15], v[120:123], v[138:141], v[0:15]
	s_waitcnt vmcnt(11)
	ds_write_b128 v201, v[76:79] offset:9216
	v_mfma_f32_32x32x16_bf16 v[48:63], v[116:119], v[134:137], v[48:63]
	global_load_dwordx4 v[76:79], v[186:187], off offset:512
	v_mfma_f32_32x32x16_bf16 v[32:47], v[116:119], v[142:145], v[32:47]
	s_waitcnt vmcnt(11)
	ds_write_b128 v201, v[88:91] offset:18432
	v_mfma_f32_32x32x16_bf16 v[16:31], v[124:127], v[134:137], v[16:31]
	global_load_dwordx4 v[88:91], v[188:189], off offset:512
	v_mfma_f32_32x32x16_bf16 v[0:15], v[124:127], v[142:145], v[0:15]
	s_waitcnt vmcnt(11)
	ds_write_b128 v201, v[92:95] offset:27648
	v_mfma_f32_32x32x16_bf16 v[48:63], v[146:149], v[162:165], v[48:63]
	global_load_dwordx4 v[92:95], v[190:191], off offset:512
	v_mfma_f32_32x32x16_bf16 v[32:47], v[146:149], v[170:173], v[32:47]
	s_waitcnt vmcnt(11)
	ds_write_b128 v201, v[104:107] offset:36864
	v_mfma_f32_32x32x16_bf16 v[16:31], v[154:157], v[162:165], v[16:31]
	global_load_dwordx4 v[104:107], v[184:185], off offset:512
	v_mfma_f32_32x32x16_bf16 v[0:15], v[154:157], v[170:173], v[0:15]
	s_waitcnt vmcnt(11)
	ds_write_b128 v201, v[108:111] offset:46080
	v_mfma_f32_32x32x16_bf16 v[48:63], v[150:153], v[166:169], v[48:63]
	global_load_dwordx4 v[108:111], v[192:193], off offset:512
	v_mfma_f32_32x32x16_bf16 v[32:47], v[150:153], v[174:177], v[32:47]
	v_mfma_f32_32x32x16_bf16 v[16:31], v[158:161], v[166:169], v[16:31]
	v_mfma_f32_32x32x16_bf16 v[0:15], v[158:161], v[174:177], v[0:15]
	s_waitcnt lgkmcnt(0)
	s_barrier
	ds_read_b128 v[162:165], v203 offset:55296
	ds_read_b128 v[130:133], v203 offset:55328
	ds_read_b128 v[170:173], v235
	ds_read_b128 v[134:137], v235 offset:32
	ds_read_b128 v[166:169], v203 offset:59904
	ds_read_b128 v[142:145], v203 offset:59936
	ds_read_b128 v[174:177], v235 offset:4608
	ds_read_b128 v[150:153], v235 offset:4640
	ds_read_b128 v[138:141], v203 offset:55360
	ds_read_b128 v[116:119], v203 offset:55392
	ds_read_b128 v[146:149], v203 offset:59968
	ds_read_b128 v[112:115], v203 offset:60000
	ds_read_b128 v[154:157], v235 offset:64
	ds_read_b128 v[120:123], v235 offset:96
	ds_read_b128 v[158:161], v235 offset:4672
	ds_read_b128 v[124:127], v235 offset:4704
	s_waitcnt lgkmcnt(0)
	s_barrier
	v_mfma_f32_32x32x16_bf16 v[48:63], v[162:165], v[170:173], v[48:63]
	v_mfma_f32_32x32x16_bf16 v[32:47], v[162:165], v[174:177], v[32:47]
	s_waitcnt vmcnt(11)
	ds_write_b128 v201, v[64:67] offset:55296
	v_mfma_f32_32x32x16_bf16 v[16:31], v[166:169], v[170:173], v[16:31]
	global_load_dwordx4 v[64:67], v[182:183], off offset:640
	v_mfma_f32_32x32x16_bf16 v[0:15], v[166:169], v[174:177], v[0:15]
	s_waitcnt vmcnt(11)
	ds_write_b128 v201, v[68:71] offset:64512
	v_mfma_f32_32x32x16_bf16 v[48:63], v[130:133], v[134:137], v[48:63]
	global_load_dwordx4 v[68:71], v[186:187], off offset:640
	v_mfma_f32_32x32x16_bf16 v[32:47], v[130:133], v[150:153], v[32:47]
	s_waitcnt vmcnt(11)
	ds_write_b128 v205, v[80:83] offset:18432
	v_mfma_f32_32x32x16_bf16 v[16:31], v[142:145], v[134:137], v[16:31]
	global_load_dwordx4 v[80:83], v[188:189], off offset:640
	v_mfma_f32_32x32x16_bf16 v[0:15], v[142:145], v[150:153], v[0:15]
	s_waitcnt vmcnt(11)
	ds_write_b128 v205, v[84:87] offset:27648
	v_mfma_f32_32x32x16_bf16 v[48:63], v[138:141], v[154:157], v[48:63]
	global_load_dwordx4 v[84:87], v[190:191], off offset:640
	v_mfma_f32_32x32x16_bf16 v[32:47], v[138:141], v[158:161], v[32:47]
	s_waitcnt vmcnt(11)
	ds_write_b128 v234, v[96:99]
	v_mfma_f32_32x32x16_bf16 v[16:31], v[146:149], v[154:157], v[16:31]
	global_load_dwordx4 v[96:99], v[184:185], off offset:640
	v_mfma_f32_32x32x16_bf16 v[0:15], v[146:149], v[158:161], v[0:15]
	s_waitcnt vmcnt(11)
	ds_write_b128 v234, v[100:103] offset:9216
	v_mfma_f32_32x32x16_bf16 v[48:63], v[116:119], v[120:123], v[48:63]
	global_load_dwordx4 v[100:103], v[192:193], off offset:640
	v_mfma_f32_32x32x16_bf16 v[32:47], v[116:119], v[124:127], v[32:47]
	v_mfma_f32_32x32x16_bf16 v[16:31], v[112:115], v[120:123], v[16:31]
	v_mfma_f32_32x32x16_bf16 v[0:15], v[112:115], v[124:127], v[0:15]
	s_waitcnt lgkmcnt(0)
	s_barrier
	ds_read_b128 v[112:115], v203
	ds_read_b128 v[116:119], v203 offset:32
	ds_read_b128 v[120:123], v203 offset:4608
	ds_read_b128 v[124:127], v203 offset:4640
	ds_read_b128 v[130:133], v204 offset:36864
	ds_read_b128 v[134:137], v204 offset:36896
	ds_read_b128 v[138:141], v204 offset:41472
	ds_read_b128 v[142:145], v204 offset:41504
	ds_read_b128 v[146:149], v203 offset:64
	ds_read_b128 v[150:153], v203 offset:96
	ds_read_b128 v[154:157], v203 offset:4672
	ds_read_b128 v[158:161], v203 offset:4704
	ds_read_b128 v[162:165], v204 offset:36928
	ds_read_b128 v[166:169], v204 offset:36960
	ds_read_b128 v[170:173], v204 offset:41536
	ds_read_b128 v[174:177], v204 offset:41568
	s_waitcnt lgkmcnt(0)
	s_barrier
	v_mfma_f32_32x32x16_bf16 v[48:63], v[112:115], v[130:133], v[48:63]
	v_mfma_f32_32x32x16_bf16 v[32:47], v[112:115], v[138:141], v[32:47]
	s_waitcnt vmcnt(11)
	ds_write_b128 v201, v[72:75]
	v_mfma_f32_32x32x16_bf16 v[16:31], v[120:123], v[130:133], v[16:31]
	global_load_dwordx4 v[72:75], v[182:183], off offset:768
	v_mfma_f32_32x32x16_bf16 v[0:15], v[120:123], v[138:141], v[0:15]
	s_waitcnt vmcnt(11)
	ds_write_b128 v201, v[76:79] offset:9216
	v_mfma_f32_32x32x16_bf16 v[48:63], v[116:119], v[134:137], v[48:63]
	global_load_dwordx4 v[76:79], v[186:187], off offset:768
	v_mfma_f32_32x32x16_bf16 v[32:47], v[116:119], v[142:145], v[32:47]
	s_waitcnt vmcnt(11)
	ds_write_b128 v201, v[88:91] offset:18432
	v_mfma_f32_32x32x16_bf16 v[16:31], v[124:127], v[134:137], v[16:31]
	global_load_dwordx4 v[88:91], v[188:189], off offset:768
	v_mfma_f32_32x32x16_bf16 v[0:15], v[124:127], v[142:145], v[0:15]
	s_waitcnt vmcnt(11)
	ds_write_b128 v201, v[92:95] offset:27648
	v_mfma_f32_32x32x16_bf16 v[48:63], v[146:149], v[162:165], v[48:63]
	global_load_dwordx4 v[92:95], v[190:191], off offset:768
	v_mfma_f32_32x32x16_bf16 v[32:47], v[146:149], v[170:173], v[32:47]
	s_waitcnt vmcnt(11)
	ds_write_b128 v201, v[104:107] offset:36864
	v_mfma_f32_32x32x16_bf16 v[16:31], v[154:157], v[162:165], v[16:31]
	global_load_dwordx4 v[104:107], v[184:185], off offset:768
	v_mfma_f32_32x32x16_bf16 v[0:15], v[154:157], v[170:173], v[0:15]
	s_waitcnt vmcnt(11)
	ds_write_b128 v201, v[108:111] offset:46080
	v_mfma_f32_32x32x16_bf16 v[48:63], v[150:153], v[166:169], v[48:63]
	global_load_dwordx4 v[108:111], v[192:193], off offset:768
	v_mfma_f32_32x32x16_bf16 v[32:47], v[150:153], v[174:177], v[32:47]
	v_mfma_f32_32x32x16_bf16 v[16:31], v[158:161], v[166:169], v[16:31]
	v_mfma_f32_32x32x16_bf16 v[0:15], v[158:161], v[174:177], v[0:15]
	s_waitcnt lgkmcnt(0)
	s_barrier
	ds_read_b128 v[162:165], v203 offset:55296
	ds_read_b128 v[130:133], v203 offset:55328
	ds_read_b128 v[170:173], v235
	ds_read_b128 v[134:137], v235 offset:32
	ds_read_b128 v[166:169], v203 offset:59904
	ds_read_b128 v[142:145], v203 offset:59936
	ds_read_b128 v[174:177], v235 offset:4608
	ds_read_b128 v[150:153], v235 offset:4640
	ds_read_b128 v[138:141], v203 offset:55360
	ds_read_b128 v[116:119], v203 offset:55392
	ds_read_b128 v[146:149], v203 offset:59968
	ds_read_b128 v[112:115], v203 offset:60000
	ds_read_b128 v[154:157], v235 offset:64
	ds_read_b128 v[120:123], v235 offset:96
	ds_read_b128 v[158:161], v235 offset:4672
	ds_read_b128 v[124:127], v235 offset:4704
	s_waitcnt lgkmcnt(0)
	s_barrier
	v_mfma_f32_32x32x16_bf16 v[48:63], v[162:165], v[170:173], v[48:63]
	v_mfma_f32_32x32x16_bf16 v[32:47], v[162:165], v[174:177], v[32:47]
	s_waitcnt vmcnt(11)
	ds_write_b128 v201, v[64:67] offset:55296
	v_mfma_f32_32x32x16_bf16 v[16:31], v[166:169], v[170:173], v[16:31]
	global_load_dwordx4 v[64:67], v[182:183], off offset:896
	v_mfma_f32_32x32x16_bf16 v[0:15], v[166:169], v[174:177], v[0:15]
	s_waitcnt vmcnt(11)
	ds_write_b128 v201, v[68:71] offset:64512
	v_mfma_f32_32x32x16_bf16 v[48:63], v[130:133], v[134:137], v[48:63]
	global_load_dwordx4 v[68:71], v[186:187], off offset:896
	v_mfma_f32_32x32x16_bf16 v[32:47], v[130:133], v[150:153], v[32:47]
	s_waitcnt vmcnt(11)
	ds_write_b128 v205, v[80:83] offset:18432
	v_mfma_f32_32x32x16_bf16 v[16:31], v[142:145], v[134:137], v[16:31]
	global_load_dwordx4 v[80:83], v[188:189], off offset:896
	v_mfma_f32_32x32x16_bf16 v[0:15], v[142:145], v[150:153], v[0:15]
	s_waitcnt vmcnt(11)
	ds_write_b128 v205, v[84:87] offset:27648
	v_mfma_f32_32x32x16_bf16 v[48:63], v[138:141], v[154:157], v[48:63]
	global_load_dwordx4 v[84:87], v[190:191], off offset:896
	v_mfma_f32_32x32x16_bf16 v[32:47], v[138:141], v[158:161], v[32:47]
	s_waitcnt vmcnt(11)
	ds_write_b128 v234, v[96:99]
	v_mfma_f32_32x32x16_bf16 v[16:31], v[146:149], v[154:157], v[16:31]
	global_load_dwordx4 v[96:99], v[184:185], off offset:896
	v_mfma_f32_32x32x16_bf16 v[0:15], v[146:149], v[158:161], v[0:15]
	s_waitcnt vmcnt(11)
	ds_write_b128 v234, v[100:103] offset:9216
	v_mfma_f32_32x32x16_bf16 v[48:63], v[116:119], v[120:123], v[48:63]
	global_load_dwordx4 v[100:103], v[192:193], off offset:896
	v_mfma_f32_32x32x16_bf16 v[32:47], v[116:119], v[124:127], v[32:47]
	v_mfma_f32_32x32x16_bf16 v[16:31], v[112:115], v[120:123], v[16:31]
	v_mfma_f32_32x32x16_bf16 v[0:15], v[112:115], v[124:127], v[0:15]
	s_waitcnt lgkmcnt(0)
	s_barrier
	ds_read_b128 v[112:115], v203
	ds_read_b128 v[116:119], v203 offset:32
	ds_read_b128 v[120:123], v203 offset:4608
	ds_read_b128 v[124:127], v203 offset:4640
	ds_read_b128 v[130:133], v204 offset:36864
	ds_read_b128 v[134:137], v204 offset:36896
	ds_read_b128 v[138:141], v204 offset:41472
	ds_read_b128 v[142:145], v204 offset:41504
	ds_read_b128 v[146:149], v203 offset:64
	ds_read_b128 v[150:153], v203 offset:96
	ds_read_b128 v[154:157], v203 offset:4672
	ds_read_b128 v[158:161], v203 offset:4704
	ds_read_b128 v[162:165], v204 offset:36928
	ds_read_b128 v[166:169], v204 offset:36960
	ds_read_b128 v[170:173], v204 offset:41536
	ds_read_b128 v[174:177], v204 offset:41568
	s_waitcnt lgkmcnt(0)
	s_barrier
	v_mfma_f32_32x32x16_bf16 v[48:63], v[112:115], v[130:133], v[48:63]
	v_mfma_f32_32x32x16_bf16 v[32:47], v[112:115], v[138:141], v[32:47]
	s_waitcnt vmcnt(11)
	ds_write_b128 v201, v[72:75]
	v_mfma_f32_32x32x16_bf16 v[16:31], v[120:123], v[130:133], v[16:31]
	global_load_dwordx4 v[72:75], v[182:183], off offset:1024
	v_mfma_f32_32x32x16_bf16 v[0:15], v[120:123], v[138:141], v[0:15]
	s_waitcnt vmcnt(11)
	ds_write_b128 v201, v[76:79] offset:9216
	v_mfma_f32_32x32x16_bf16 v[48:63], v[116:119], v[134:137], v[48:63]
	global_load_dwordx4 v[76:79], v[186:187], off offset:1024
	v_mfma_f32_32x32x16_bf16 v[32:47], v[116:119], v[142:145], v[32:47]
	s_waitcnt vmcnt(11)
	ds_write_b128 v201, v[88:91] offset:18432
	v_mfma_f32_32x32x16_bf16 v[16:31], v[124:127], v[134:137], v[16:31]
	global_load_dwordx4 v[88:91], v[188:189], off offset:1024
	v_mfma_f32_32x32x16_bf16 v[0:15], v[124:127], v[142:145], v[0:15]
	s_waitcnt vmcnt(11)
	ds_write_b128 v201, v[92:95] offset:27648
	v_mfma_f32_32x32x16_bf16 v[48:63], v[146:149], v[162:165], v[48:63]
	global_load_dwordx4 v[92:95], v[190:191], off offset:1024
	v_mfma_f32_32x32x16_bf16 v[32:47], v[146:149], v[170:173], v[32:47]
	s_waitcnt vmcnt(11)
	ds_write_b128 v201, v[104:107] offset:36864
	v_mfma_f32_32x32x16_bf16 v[16:31], v[154:157], v[162:165], v[16:31]
	global_load_dwordx4 v[104:107], v[184:185], off offset:1024
	v_mfma_f32_32x32x16_bf16 v[0:15], v[154:157], v[170:173], v[0:15]
	s_waitcnt vmcnt(11)
	ds_write_b128 v201, v[108:111] offset:46080
	v_mfma_f32_32x32x16_bf16 v[48:63], v[150:153], v[166:169], v[48:63]
	global_load_dwordx4 v[108:111], v[192:193], off offset:1024
	v_mfma_f32_32x32x16_bf16 v[32:47], v[150:153], v[174:177], v[32:47]
	v_mfma_f32_32x32x16_bf16 v[16:31], v[158:161], v[166:169], v[16:31]
	v_mfma_f32_32x32x16_bf16 v[0:15], v[158:161], v[174:177], v[0:15]
	s_waitcnt lgkmcnt(0)
	s_barrier
	ds_read_b128 v[162:165], v203 offset:55296
	ds_read_b128 v[130:133], v203 offset:55328
	ds_read_b128 v[170:173], v235
	ds_read_b128 v[134:137], v235 offset:32
	ds_read_b128 v[166:169], v203 offset:59904
	ds_read_b128 v[142:145], v203 offset:59936
	ds_read_b128 v[174:177], v235 offset:4608
	ds_read_b128 v[150:153], v235 offset:4640
	ds_read_b128 v[138:141], v203 offset:55360
	ds_read_b128 v[116:119], v203 offset:55392
	ds_read_b128 v[146:149], v203 offset:59968
	ds_read_b128 v[112:115], v203 offset:60000
	ds_read_b128 v[154:157], v235 offset:64
	ds_read_b128 v[120:123], v235 offset:96
	ds_read_b128 v[158:161], v235 offset:4672
	ds_read_b128 v[124:127], v235 offset:4704
	s_waitcnt lgkmcnt(0)
	s_barrier
	v_mfma_f32_32x32x16_bf16 v[48:63], v[162:165], v[170:173], v[48:63]
	v_mfma_f32_32x32x16_bf16 v[32:47], v[162:165], v[174:177], v[32:47]
	s_waitcnt vmcnt(11)
	ds_write_b128 v201, v[64:67] offset:55296
	v_mfma_f32_32x32x16_bf16 v[16:31], v[166:169], v[170:173], v[16:31]
	global_load_dwordx4 v[64:67], v[182:183], off offset:1152
	v_mfma_f32_32x32x16_bf16 v[0:15], v[166:169], v[174:177], v[0:15]
	s_waitcnt vmcnt(11)
	ds_write_b128 v201, v[68:71] offset:64512
	v_mfma_f32_32x32x16_bf16 v[48:63], v[130:133], v[134:137], v[48:63]
	global_load_dwordx4 v[68:71], v[186:187], off offset:1152
	v_mfma_f32_32x32x16_bf16 v[32:47], v[130:133], v[150:153], v[32:47]
	s_waitcnt vmcnt(11)
	ds_write_b128 v205, v[80:83] offset:18432
	v_mfma_f32_32x32x16_bf16 v[16:31], v[142:145], v[134:137], v[16:31]
	global_load_dwordx4 v[80:83], v[188:189], off offset:1152
	v_mfma_f32_32x32x16_bf16 v[0:15], v[142:145], v[150:153], v[0:15]
	s_waitcnt vmcnt(11)
	ds_write_b128 v205, v[84:87] offset:27648
	v_mfma_f32_32x32x16_bf16 v[48:63], v[138:141], v[154:157], v[48:63]
	global_load_dwordx4 v[84:87], v[190:191], off offset:1152
	v_mfma_f32_32x32x16_bf16 v[32:47], v[138:141], v[158:161], v[32:47]
	s_waitcnt vmcnt(11)
	ds_write_b128 v234, v[96:99]
	v_mfma_f32_32x32x16_bf16 v[16:31], v[146:149], v[154:157], v[16:31]
	global_load_dwordx4 v[96:99], v[184:185], off offset:1152
	v_mfma_f32_32x32x16_bf16 v[0:15], v[146:149], v[158:161], v[0:15]
	s_waitcnt vmcnt(11)
	ds_write_b128 v234, v[100:103] offset:9216
	v_mfma_f32_32x32x16_bf16 v[48:63], v[116:119], v[120:123], v[48:63]
	global_load_dwordx4 v[100:103], v[192:193], off offset:1152
	v_mfma_f32_32x32x16_bf16 v[32:47], v[116:119], v[124:127], v[32:47]
	v_mfma_f32_32x32x16_bf16 v[16:31], v[112:115], v[120:123], v[16:31]
	v_mfma_f32_32x32x16_bf16 v[0:15], v[112:115], v[124:127], v[0:15]
	s_waitcnt lgkmcnt(0)
	s_barrier
	ds_read_b128 v[112:115], v203
	ds_read_b128 v[116:119], v203 offset:32
	ds_read_b128 v[120:123], v203 offset:4608
	ds_read_b128 v[124:127], v203 offset:4640
	ds_read_b128 v[130:133], v204 offset:36864
	ds_read_b128 v[134:137], v204 offset:36896
	ds_read_b128 v[138:141], v204 offset:41472
	ds_read_b128 v[142:145], v204 offset:41504
	ds_read_b128 v[146:149], v203 offset:64
	ds_read_b128 v[150:153], v203 offset:96
	ds_read_b128 v[154:157], v203 offset:4672
	ds_read_b128 v[158:161], v203 offset:4704
	ds_read_b128 v[162:165], v204 offset:36928
	ds_read_b128 v[166:169], v204 offset:36960
	ds_read_b128 v[170:173], v204 offset:41536
	ds_read_b128 v[174:177], v204 offset:41568
	s_waitcnt lgkmcnt(0)
	s_barrier
	v_mfma_f32_32x32x16_bf16 v[48:63], v[112:115], v[130:133], v[48:63]
	v_mfma_f32_32x32x16_bf16 v[32:47], v[112:115], v[138:141], v[32:47]
	s_waitcnt vmcnt(11)
	ds_write_b128 v201, v[72:75]
	v_mfma_f32_32x32x16_bf16 v[16:31], v[120:123], v[130:133], v[16:31]
	global_load_dwordx4 v[72:75], v[182:183], off offset:1280
	v_mfma_f32_32x32x16_bf16 v[0:15], v[120:123], v[138:141], v[0:15]
	s_waitcnt vmcnt(11)
	ds_write_b128 v201, v[76:79] offset:9216
	v_mfma_f32_32x32x16_bf16 v[48:63], v[116:119], v[134:137], v[48:63]
	global_load_dwordx4 v[76:79], v[186:187], off offset:1280
	v_mfma_f32_32x32x16_bf16 v[32:47], v[116:119], v[142:145], v[32:47]
	s_waitcnt vmcnt(11)
	ds_write_b128 v201, v[88:91] offset:18432
	v_mfma_f32_32x32x16_bf16 v[16:31], v[124:127], v[134:137], v[16:31]
	global_load_dwordx4 v[88:91], v[188:189], off offset:1280
	v_mfma_f32_32x32x16_bf16 v[0:15], v[124:127], v[142:145], v[0:15]
	s_waitcnt vmcnt(11)
	ds_write_b128 v201, v[92:95] offset:27648
	v_mfma_f32_32x32x16_bf16 v[48:63], v[146:149], v[162:165], v[48:63]
	global_load_dwordx4 v[92:95], v[190:191], off offset:1280
	v_mfma_f32_32x32x16_bf16 v[32:47], v[146:149], v[170:173], v[32:47]
	s_waitcnt vmcnt(11)
	ds_write_b128 v201, v[104:107] offset:36864
	v_mfma_f32_32x32x16_bf16 v[16:31], v[154:157], v[162:165], v[16:31]
	global_load_dwordx4 v[104:107], v[184:185], off offset:1280
	v_mfma_f32_32x32x16_bf16 v[0:15], v[154:157], v[170:173], v[0:15]
	s_waitcnt vmcnt(11)
	ds_write_b128 v201, v[108:111] offset:46080
	v_mfma_f32_32x32x16_bf16 v[48:63], v[150:153], v[166:169], v[48:63]
	global_load_dwordx4 v[108:111], v[192:193], off offset:1280
	v_mfma_f32_32x32x16_bf16 v[32:47], v[150:153], v[174:177], v[32:47]
	v_mfma_f32_32x32x16_bf16 v[16:31], v[158:161], v[166:169], v[16:31]
	v_mfma_f32_32x32x16_bf16 v[0:15], v[158:161], v[174:177], v[0:15]
	s_waitcnt lgkmcnt(0)
	s_barrier
	ds_read_b128 v[162:165], v203 offset:55296
	ds_read_b128 v[130:133], v203 offset:55328
	ds_read_b128 v[170:173], v235
	ds_read_b128 v[134:137], v235 offset:32
	ds_read_b128 v[166:169], v203 offset:59904
	ds_read_b128 v[142:145], v203 offset:59936
	ds_read_b128 v[174:177], v235 offset:4608
	ds_read_b128 v[150:153], v235 offset:4640
	ds_read_b128 v[138:141], v203 offset:55360
	ds_read_b128 v[116:119], v203 offset:55392
	ds_read_b128 v[146:149], v203 offset:59968
	ds_read_b128 v[112:115], v203 offset:60000
	ds_read_b128 v[154:157], v235 offset:64
	ds_read_b128 v[120:123], v235 offset:96
	ds_read_b128 v[158:161], v235 offset:4672
	ds_read_b128 v[124:127], v235 offset:4704
	s_waitcnt lgkmcnt(0)
	s_barrier
	v_mfma_f32_32x32x16_bf16 v[48:63], v[162:165], v[170:173], v[48:63]
	v_mfma_f32_32x32x16_bf16 v[32:47], v[162:165], v[174:177], v[32:47]
	s_waitcnt vmcnt(11)
	ds_write_b128 v201, v[64:67] offset:55296
	v_mfma_f32_32x32x16_bf16 v[16:31], v[166:169], v[170:173], v[16:31]
	global_load_dwordx4 v[64:67], v[182:183], off offset:1408
	v_mfma_f32_32x32x16_bf16 v[0:15], v[166:169], v[174:177], v[0:15]
	s_waitcnt vmcnt(11)
	ds_write_b128 v201, v[68:71] offset:64512
	v_mfma_f32_32x32x16_bf16 v[48:63], v[130:133], v[134:137], v[48:63]
	global_load_dwordx4 v[68:71], v[186:187], off offset:1408
	v_mfma_f32_32x32x16_bf16 v[32:47], v[130:133], v[150:153], v[32:47]
	s_waitcnt vmcnt(11)
	ds_write_b128 v205, v[80:83] offset:18432
	v_mfma_f32_32x32x16_bf16 v[16:31], v[142:145], v[134:137], v[16:31]
	global_load_dwordx4 v[80:83], v[188:189], off offset:1408
	v_mfma_f32_32x32x16_bf16 v[0:15], v[142:145], v[150:153], v[0:15]
	s_waitcnt vmcnt(11)
	ds_write_b128 v205, v[84:87] offset:27648
	v_mfma_f32_32x32x16_bf16 v[48:63], v[138:141], v[154:157], v[48:63]
	global_load_dwordx4 v[84:87], v[190:191], off offset:1408
	v_mfma_f32_32x32x16_bf16 v[32:47], v[138:141], v[158:161], v[32:47]
	s_waitcnt vmcnt(11)
	ds_write_b128 v234, v[96:99]
	v_mfma_f32_32x32x16_bf16 v[16:31], v[146:149], v[154:157], v[16:31]
	global_load_dwordx4 v[96:99], v[184:185], off offset:1408
	v_mfma_f32_32x32x16_bf16 v[0:15], v[146:149], v[158:161], v[0:15]
	s_waitcnt vmcnt(11)
	ds_write_b128 v234, v[100:103] offset:9216
	v_mfma_f32_32x32x16_bf16 v[48:63], v[116:119], v[120:123], v[48:63]
	global_load_dwordx4 v[100:103], v[192:193], off offset:1408
	v_mfma_f32_32x32x16_bf16 v[32:47], v[116:119], v[124:127], v[32:47]
	v_mfma_f32_32x32x16_bf16 v[16:31], v[112:115], v[120:123], v[16:31]
	v_mfma_f32_32x32x16_bf16 v[0:15], v[112:115], v[124:127], v[0:15]
	s_waitcnt lgkmcnt(0)
	s_barrier
	ds_read_b128 v[112:115], v203
	ds_read_b128 v[116:119], v203 offset:32
	ds_read_b128 v[120:123], v203 offset:4608
	ds_read_b128 v[124:127], v203 offset:4640
	ds_read_b128 v[130:133], v204 offset:36864
	ds_read_b128 v[134:137], v204 offset:36896
	ds_read_b128 v[138:141], v204 offset:41472
	ds_read_b128 v[142:145], v204 offset:41504
	ds_read_b128 v[146:149], v203 offset:64
	ds_read_b128 v[150:153], v203 offset:96
	ds_read_b128 v[154:157], v203 offset:4672
	ds_read_b128 v[158:161], v203 offset:4704
	ds_read_b128 v[162:165], v204 offset:36928
	ds_read_b128 v[166:169], v204 offset:36960
	ds_read_b128 v[170:173], v204 offset:41536
	ds_read_b128 v[174:177], v204 offset:41568
	s_waitcnt lgkmcnt(0)
	s_barrier
	v_mfma_f32_32x32x16_bf16 v[48:63], v[112:115], v[130:133], v[48:63]
	v_mfma_f32_32x32x16_bf16 v[32:47], v[112:115], v[138:141], v[32:47]
	s_waitcnt vmcnt(11)
	ds_write_b128 v201, v[72:75]
	v_mfma_f32_32x32x16_bf16 v[16:31], v[120:123], v[130:133], v[16:31]
	global_load_dwordx4 v[72:75], v[182:183], off offset:1536
	v_mfma_f32_32x32x16_bf16 v[0:15], v[120:123], v[138:141], v[0:15]
	s_waitcnt vmcnt(11)
	ds_write_b128 v201, v[76:79] offset:9216
	v_mfma_f32_32x32x16_bf16 v[48:63], v[116:119], v[134:137], v[48:63]
	global_load_dwordx4 v[76:79], v[186:187], off offset:1536
	v_mfma_f32_32x32x16_bf16 v[32:47], v[116:119], v[142:145], v[32:47]
	s_waitcnt vmcnt(11)
	ds_write_b128 v201, v[88:91] offset:18432
	v_mfma_f32_32x32x16_bf16 v[16:31], v[124:127], v[134:137], v[16:31]
	global_load_dwordx4 v[88:91], v[188:189], off offset:1536
	v_mfma_f32_32x32x16_bf16 v[0:15], v[124:127], v[142:145], v[0:15]
	s_waitcnt vmcnt(11)
	ds_write_b128 v201, v[92:95] offset:27648
	v_mfma_f32_32x32x16_bf16 v[48:63], v[146:149], v[162:165], v[48:63]
	global_load_dwordx4 v[92:95], v[190:191], off offset:1536
	v_mfma_f32_32x32x16_bf16 v[32:47], v[146:149], v[170:173], v[32:47]
	s_waitcnt vmcnt(11)
	ds_write_b128 v201, v[104:107] offset:36864
	v_mfma_f32_32x32x16_bf16 v[16:31], v[154:157], v[162:165], v[16:31]
	global_load_dwordx4 v[104:107], v[184:185], off offset:1536
	v_mfma_f32_32x32x16_bf16 v[0:15], v[154:157], v[170:173], v[0:15]
	s_waitcnt vmcnt(11)
	ds_write_b128 v201, v[108:111] offset:46080
	v_mfma_f32_32x32x16_bf16 v[48:63], v[150:153], v[166:169], v[48:63]
	global_load_dwordx4 v[108:111], v[192:193], off offset:1536
	v_mfma_f32_32x32x16_bf16 v[32:47], v[150:153], v[174:177], v[32:47]
	v_mfma_f32_32x32x16_bf16 v[16:31], v[158:161], v[166:169], v[16:31]
	v_mfma_f32_32x32x16_bf16 v[0:15], v[158:161], v[174:177], v[0:15]
	s_waitcnt lgkmcnt(0)
	s_barrier
	ds_read_b128 v[162:165], v203 offset:55296
	ds_read_b128 v[130:133], v203 offset:55328
	ds_read_b128 v[170:173], v235
	ds_read_b128 v[134:137], v235 offset:32
	ds_read_b128 v[166:169], v203 offset:59904
	ds_read_b128 v[142:145], v203 offset:59936
	ds_read_b128 v[174:177], v235 offset:4608
	ds_read_b128 v[150:153], v235 offset:4640
	ds_read_b128 v[138:141], v203 offset:55360
	ds_read_b128 v[116:119], v203 offset:55392
	ds_read_b128 v[146:149], v203 offset:59968
	ds_read_b128 v[112:115], v203 offset:60000
	ds_read_b128 v[154:157], v235 offset:64
	ds_read_b128 v[120:123], v235 offset:96
	ds_read_b128 v[158:161], v235 offset:4672
	ds_read_b128 v[124:127], v235 offset:4704
	s_waitcnt lgkmcnt(0)
	s_barrier
	v_mfma_f32_32x32x16_bf16 v[48:63], v[162:165], v[170:173], v[48:63]
	v_mfma_f32_32x32x16_bf16 v[32:47], v[162:165], v[174:177], v[32:47]
	s_waitcnt vmcnt(11)
	ds_write_b128 v201, v[64:67] offset:55296
	v_mfma_f32_32x32x16_bf16 v[16:31], v[166:169], v[170:173], v[16:31]
	global_load_dwordx4 v[64:67], v[182:183], off offset:1664
	v_mfma_f32_32x32x16_bf16 v[0:15], v[166:169], v[174:177], v[0:15]
	s_waitcnt vmcnt(11)
	ds_write_b128 v201, v[68:71] offset:64512
	v_mfma_f32_32x32x16_bf16 v[48:63], v[130:133], v[134:137], v[48:63]
	global_load_dwordx4 v[68:71], v[186:187], off offset:1664
	v_mfma_f32_32x32x16_bf16 v[32:47], v[130:133], v[150:153], v[32:47]
	s_waitcnt vmcnt(11)
	ds_write_b128 v205, v[80:83] offset:18432
	v_mfma_f32_32x32x16_bf16 v[16:31], v[142:145], v[134:137], v[16:31]
	global_load_dwordx4 v[80:83], v[188:189], off offset:1664
	v_mfma_f32_32x32x16_bf16 v[0:15], v[142:145], v[150:153], v[0:15]
	s_waitcnt vmcnt(11)
	ds_write_b128 v205, v[84:87] offset:27648
	v_mfma_f32_32x32x16_bf16 v[48:63], v[138:141], v[154:157], v[48:63]
	global_load_dwordx4 v[84:87], v[190:191], off offset:1664
	v_mfma_f32_32x32x16_bf16 v[32:47], v[138:141], v[158:161], v[32:47]
	s_waitcnt vmcnt(11)
	ds_write_b128 v234, v[96:99]
	v_mfma_f32_32x32x16_bf16 v[16:31], v[146:149], v[154:157], v[16:31]
	global_load_dwordx4 v[96:99], v[184:185], off offset:1664
	v_mfma_f32_32x32x16_bf16 v[0:15], v[146:149], v[158:161], v[0:15]
	s_waitcnt vmcnt(11)
	ds_write_b128 v234, v[100:103] offset:9216
	v_mfma_f32_32x32x16_bf16 v[48:63], v[116:119], v[120:123], v[48:63]
	global_load_dwordx4 v[100:103], v[192:193], off offset:1664
	v_mfma_f32_32x32x16_bf16 v[32:47], v[116:119], v[124:127], v[32:47]
	v_mfma_f32_32x32x16_bf16 v[16:31], v[112:115], v[120:123], v[16:31]
	v_mfma_f32_32x32x16_bf16 v[0:15], v[112:115], v[124:127], v[0:15]
	s_waitcnt lgkmcnt(0)
	s_barrier
	ds_read_b128 v[112:115], v203
	ds_read_b128 v[116:119], v203 offset:32
	ds_read_b128 v[120:123], v203 offset:4608
	ds_read_b128 v[124:127], v203 offset:4640
	ds_read_b128 v[130:133], v204 offset:36864
	ds_read_b128 v[134:137], v204 offset:36896
	ds_read_b128 v[138:141], v204 offset:41472
	ds_read_b128 v[142:145], v204 offset:41504
	ds_read_b128 v[146:149], v203 offset:64
	ds_read_b128 v[150:153], v203 offset:96
	ds_read_b128 v[154:157], v203 offset:4672
	ds_read_b128 v[158:161], v203 offset:4704
	ds_read_b128 v[162:165], v204 offset:36928
	ds_read_b128 v[166:169], v204 offset:36960
	ds_read_b128 v[170:173], v204 offset:41536
	ds_read_b128 v[174:177], v204 offset:41568
	s_waitcnt lgkmcnt(0)
	s_barrier
	v_mfma_f32_32x32x16_bf16 v[48:63], v[112:115], v[130:133], v[48:63]
	v_mfma_f32_32x32x16_bf16 v[32:47], v[112:115], v[138:141], v[32:47]
	s_waitcnt vmcnt(11)
	ds_write_b128 v201, v[72:75]
	v_mfma_f32_32x32x16_bf16 v[16:31], v[120:123], v[130:133], v[16:31]
	global_load_dwordx4 v[72:75], v[182:183], off offset:1792
	v_mfma_f32_32x32x16_bf16 v[0:15], v[120:123], v[138:141], v[0:15]
	s_waitcnt vmcnt(11)
	ds_write_b128 v201, v[76:79] offset:9216
	v_mfma_f32_32x32x16_bf16 v[48:63], v[116:119], v[134:137], v[48:63]
	global_load_dwordx4 v[76:79], v[186:187], off offset:1792
	v_mfma_f32_32x32x16_bf16 v[32:47], v[116:119], v[142:145], v[32:47]
	s_waitcnt vmcnt(11)
	ds_write_b128 v201, v[88:91] offset:18432
	v_mfma_f32_32x32x16_bf16 v[16:31], v[124:127], v[134:137], v[16:31]
	global_load_dwordx4 v[88:91], v[188:189], off offset:1792
	v_mfma_f32_32x32x16_bf16 v[0:15], v[124:127], v[142:145], v[0:15]
	s_waitcnt vmcnt(11)
	ds_write_b128 v201, v[92:95] offset:27648
	v_mfma_f32_32x32x16_bf16 v[48:63], v[146:149], v[162:165], v[48:63]
	global_load_dwordx4 v[92:95], v[190:191], off offset:1792
	v_mfma_f32_32x32x16_bf16 v[32:47], v[146:149], v[170:173], v[32:47]
	s_waitcnt vmcnt(11)
	ds_write_b128 v201, v[104:107] offset:36864
	v_mfma_f32_32x32x16_bf16 v[16:31], v[154:157], v[162:165], v[16:31]
	global_load_dwordx4 v[104:107], v[184:185], off offset:1792
	v_mfma_f32_32x32x16_bf16 v[0:15], v[154:157], v[170:173], v[0:15]
	s_waitcnt vmcnt(11)
	ds_write_b128 v201, v[108:111] offset:46080
	v_mfma_f32_32x32x16_bf16 v[48:63], v[150:153], v[166:169], v[48:63]
	global_load_dwordx4 v[108:111], v[192:193], off offset:1792
	v_mfma_f32_32x32x16_bf16 v[32:47], v[150:153], v[174:177], v[32:47]
	v_mfma_f32_32x32x16_bf16 v[16:31], v[158:161], v[166:169], v[16:31]
	v_mfma_f32_32x32x16_bf16 v[0:15], v[158:161], v[174:177], v[0:15]
	s_waitcnt lgkmcnt(0)
	s_barrier
	ds_read_b128 v[162:165], v203 offset:55296
	ds_read_b128 v[130:133], v203 offset:55328
	ds_read_b128 v[170:173], v235
	ds_read_b128 v[134:137], v235 offset:32
	ds_read_b128 v[166:169], v203 offset:59904
	ds_read_b128 v[142:145], v203 offset:59936
	ds_read_b128 v[174:177], v235 offset:4608
	ds_read_b128 v[150:153], v235 offset:4640
	ds_read_b128 v[138:141], v203 offset:55360
	ds_read_b128 v[116:119], v203 offset:55392
	ds_read_b128 v[146:149], v203 offset:59968
	ds_read_b128 v[112:115], v203 offset:60000
	ds_read_b128 v[154:157], v235 offset:64
	ds_read_b128 v[120:123], v235 offset:96
	ds_read_b128 v[158:161], v235 offset:4672
	ds_read_b128 v[124:127], v235 offset:4704
	s_waitcnt lgkmcnt(0)
	s_barrier
	v_mfma_f32_32x32x16_bf16 v[48:63], v[162:165], v[170:173], v[48:63]
	v_mfma_f32_32x32x16_bf16 v[32:47], v[162:165], v[174:177], v[32:47]
	s_waitcnt vmcnt(11)
	ds_write_b128 v201, v[64:67] offset:55296
	v_mfma_f32_32x32x16_bf16 v[16:31], v[166:169], v[170:173], v[16:31]
	global_load_dwordx4 v[64:67], v[182:183], off offset:1920
	v_mfma_f32_32x32x16_bf16 v[0:15], v[166:169], v[174:177], v[0:15]
	s_waitcnt vmcnt(11)
	ds_write_b128 v201, v[68:71] offset:64512
	v_mfma_f32_32x32x16_bf16 v[48:63], v[130:133], v[134:137], v[48:63]
	global_load_dwordx4 v[68:71], v[186:187], off offset:1920
	v_mfma_f32_32x32x16_bf16 v[32:47], v[130:133], v[150:153], v[32:47]
	s_waitcnt vmcnt(11)
	ds_write_b128 v205, v[80:83] offset:18432
	v_mfma_f32_32x32x16_bf16 v[16:31], v[142:145], v[134:137], v[16:31]
	global_load_dwordx4 v[80:83], v[188:189], off offset:1920
	v_mfma_f32_32x32x16_bf16 v[0:15], v[142:145], v[150:153], v[0:15]
	s_waitcnt vmcnt(11)
	ds_write_b128 v205, v[84:87] offset:27648
	v_mfma_f32_32x32x16_bf16 v[48:63], v[138:141], v[154:157], v[48:63]
	global_load_dwordx4 v[84:87], v[190:191], off offset:1920
	v_mfma_f32_32x32x16_bf16 v[32:47], v[138:141], v[158:161], v[32:47]
	s_waitcnt vmcnt(11)
	ds_write_b128 v234, v[96:99]
	v_mfma_f32_32x32x16_bf16 v[16:31], v[146:149], v[154:157], v[16:31]
	global_load_dwordx4 v[96:99], v[184:185], off offset:1920
	v_mfma_f32_32x32x16_bf16 v[0:15], v[146:149], v[158:161], v[0:15]
	s_waitcnt vmcnt(11)
	ds_write_b128 v234, v[100:103] offset:9216
	v_mfma_f32_32x32x16_bf16 v[48:63], v[116:119], v[120:123], v[48:63]
	global_load_dwordx4 v[100:103], v[192:193], off offset:1920
	v_mfma_f32_32x32x16_bf16 v[32:47], v[116:119], v[124:127], v[32:47]
	v_mfma_f32_32x32x16_bf16 v[16:31], v[112:115], v[120:123], v[16:31]
	v_mfma_f32_32x32x16_bf16 v[0:15], v[112:115], v[124:127], v[0:15]
	s_waitcnt lgkmcnt(0)
	s_barrier
	ds_read_b128 v[112:115], v203
	ds_read_b128 v[116:119], v203 offset:32
	ds_read_b128 v[120:123], v203 offset:4608
	ds_read_b128 v[124:127], v203 offset:4640
	ds_read_b128 v[130:133], v204 offset:36864
	ds_read_b128 v[134:137], v204 offset:36896
	ds_read_b128 v[138:141], v204 offset:41472
	ds_read_b128 v[142:145], v204 offset:41504
	ds_read_b128 v[146:149], v203 offset:64
	ds_read_b128 v[150:153], v203 offset:96
	ds_read_b128 v[154:157], v203 offset:4672
	ds_read_b128 v[158:161], v203 offset:4704
	ds_read_b128 v[162:165], v204 offset:36928
	ds_read_b128 v[166:169], v204 offset:36960
	ds_read_b128 v[170:173], v204 offset:41536
	ds_read_b128 v[174:177], v204 offset:41568
	s_waitcnt lgkmcnt(0)
	s_barrier
	v_mfma_f32_32x32x16_bf16 v[48:63], v[112:115], v[130:133], v[48:63]
	v_mfma_f32_32x32x16_bf16 v[32:47], v[112:115], v[138:141], v[32:47]
	s_waitcnt vmcnt(11)
	ds_write_b128 v201, v[72:75]
	v_mfma_f32_32x32x16_bf16 v[16:31], v[120:123], v[130:133], v[16:31]
	v_mfma_f32_32x32x16_bf16 v[0:15], v[120:123], v[138:141], v[0:15]
	s_waitcnt vmcnt(10)
	ds_write_b128 v201, v[76:79] offset:9216
	v_mfma_f32_32x32x16_bf16 v[48:63], v[116:119], v[134:137], v[48:63]
	v_mfma_f32_32x32x16_bf16 v[32:47], v[116:119], v[142:145], v[32:47]
	s_waitcnt vmcnt(9)
	ds_write_b128 v201, v[88:91] offset:18432
	v_mfma_f32_32x32x16_bf16 v[16:31], v[124:127], v[134:137], v[16:31]
	v_mfma_f32_32x32x16_bf16 v[0:15], v[124:127], v[142:145], v[0:15]
	s_waitcnt vmcnt(8)
	ds_write_b128 v201, v[92:95] offset:27648
	v_mfma_f32_32x32x16_bf16 v[48:63], v[146:149], v[162:165], v[48:63]
	v_mfma_f32_32x32x16_bf16 v[32:47], v[146:149], v[170:173], v[32:47]
	s_waitcnt vmcnt(7)
	ds_write_b128 v201, v[104:107] offset:36864
	v_mfma_f32_32x32x16_bf16 v[16:31], v[154:157], v[162:165], v[16:31]
	v_mfma_f32_32x32x16_bf16 v[0:15], v[154:157], v[170:173], v[0:15]
	s_waitcnt vmcnt(6)
	ds_write_b128 v201, v[108:111] offset:46080
	v_mfma_f32_32x32x16_bf16 v[48:63], v[150:153], v[166:169], v[48:63]
	v_mfma_f32_32x32x16_bf16 v[32:47], v[150:153], v[174:177], v[32:47]
	v_mfma_f32_32x32x16_bf16 v[16:31], v[158:161], v[166:169], v[16:31]
	v_mfma_f32_32x32x16_bf16 v[0:15], v[158:161], v[174:177], v[0:15]
	s_waitcnt lgkmcnt(0)
	s_barrier
	ds_read_b128 v[162:165], v203 offset:55296
	ds_read_b128 v[130:133], v203 offset:55328
	ds_read_b128 v[170:173], v235
	ds_read_b128 v[134:137], v235 offset:32
	ds_read_b128 v[166:169], v203 offset:59904
	ds_read_b128 v[142:145], v203 offset:59936
	ds_read_b128 v[174:177], v235 offset:4608
	ds_read_b128 v[150:153], v235 offset:4640
	ds_read_b128 v[138:141], v203 offset:55360
	ds_read_b128 v[116:119], v203 offset:55392
	ds_read_b128 v[146:149], v203 offset:59968
	ds_read_b128 v[112:115], v203 offset:60000
	ds_read_b128 v[154:157], v235 offset:64
	ds_read_b128 v[120:123], v235 offset:96
	ds_read_b128 v[158:161], v235 offset:4672
	ds_read_b128 v[124:127], v235 offset:4704
	s_waitcnt lgkmcnt(0)
	s_barrier
	v_mfma_f32_32x32x16_bf16 v[48:63], v[162:165], v[170:173], v[48:63]
	v_mfma_f32_32x32x16_bf16 v[32:47], v[162:165], v[174:177], v[32:47]
	s_waitcnt vmcnt(5)
	ds_write_b128 v201, v[64:67] offset:55296
	v_mfma_f32_32x32x16_bf16 v[16:31], v[166:169], v[170:173], v[16:31]
	v_mfma_f32_32x32x16_bf16 v[0:15], v[166:169], v[174:177], v[0:15]
	s_waitcnt vmcnt(4)
	ds_write_b128 v201, v[68:71] offset:64512
	v_mfma_f32_32x32x16_bf16 v[48:63], v[130:133], v[134:137], v[48:63]
	v_mfma_f32_32x32x16_bf16 v[32:47], v[130:133], v[150:153], v[32:47]
	s_waitcnt vmcnt(3)
	ds_write_b128 v205, v[80:83] offset:18432
	v_mfma_f32_32x32x16_bf16 v[16:31], v[142:145], v[134:137], v[16:31]
	v_mfma_f32_32x32x16_bf16 v[0:15], v[142:145], v[150:153], v[0:15]
	s_waitcnt vmcnt(2)
	ds_write_b128 v205, v[84:87] offset:27648
	v_mfma_f32_32x32x16_bf16 v[48:63], v[138:141], v[154:157], v[48:63]
	v_mfma_f32_32x32x16_bf16 v[32:47], v[138:141], v[158:161], v[32:47]
	s_waitcnt vmcnt(1)
	ds_write_b128 v234, v[96:99]
	v_mfma_f32_32x32x16_bf16 v[16:31], v[146:149], v[154:157], v[16:31]
	v_mfma_f32_32x32x16_bf16 v[0:15], v[146:149], v[158:161], v[0:15]
	s_waitcnt vmcnt(0)
	ds_write_b128 v234, v[100:103] offset:9216
	v_mfma_f32_32x32x16_bf16 v[48:63], v[116:119], v[120:123], v[48:63]
	v_mfma_f32_32x32x16_bf16 v[32:47], v[116:119], v[124:127], v[32:47]
	v_mfma_f32_32x32x16_bf16 v[16:31], v[112:115], v[120:123], v[16:31]
	v_mfma_f32_32x32x16_bf16 v[0:15], v[112:115], v[124:127], v[0:15]
	s_waitcnt lgkmcnt(0)
	s_barrier
	ds_read_b128 v[112:115], v203
	ds_read_b128 v[116:119], v203 offset:32
	ds_read_b128 v[120:123], v203 offset:4608
	ds_read_b128 v[124:127], v203 offset:4640
	ds_read_b128 v[130:133], v204 offset:36864
	ds_read_b128 v[134:137], v204 offset:36896
	ds_read_b128 v[138:141], v204 offset:41472
	ds_read_b128 v[142:145], v204 offset:41504
	ds_read_b128 v[146:149], v203 offset:64
	ds_read_b128 v[150:153], v203 offset:96
	ds_read_b128 v[154:157], v203 offset:4672
	ds_read_b128 v[158:161], v203 offset:4704
	ds_read_b128 v[162:165], v204 offset:36928
	ds_read_b128 v[166:169], v204 offset:36960
	ds_read_b128 v[170:173], v204 offset:41536
	ds_read_b128 v[174:177], v204 offset:41568
	s_waitcnt lgkmcnt(0)
	s_barrier
	v_mfma_f32_32x32x16_bf16 v[48:63], v[112:115], v[130:133], v[48:63]
	v_mfma_f32_32x32x16_bf16 v[32:47], v[112:115], v[138:141], v[32:47]
	v_mfma_f32_32x32x16_bf16 v[16:31], v[120:123], v[130:133], v[16:31]
	v_mfma_f32_32x32x16_bf16 v[0:15], v[120:123], v[138:141], v[0:15]
	v_mfma_f32_32x32x16_bf16 v[48:63], v[116:119], v[134:137], v[48:63]
	v_mfma_f32_32x32x16_bf16 v[32:47], v[116:119], v[142:145], v[32:47]
	v_mfma_f32_32x32x16_bf16 v[16:31], v[124:127], v[134:137], v[16:31]
	v_mfma_f32_32x32x16_bf16 v[0:15], v[124:127], v[142:145], v[0:15]
	v_mfma_f32_32x32x16_bf16 v[48:63], v[146:149], v[162:165], v[48:63]
	v_mfma_f32_32x32x16_bf16 v[32:47], v[146:149], v[170:173], v[32:47]
	v_mfma_f32_32x32x16_bf16 v[16:31], v[154:157], v[162:165], v[16:31]
	v_mfma_f32_32x32x16_bf16 v[0:15], v[154:157], v[170:173], v[0:15]
	v_mfma_f32_32x32x16_bf16 v[48:63], v[150:153], v[166:169], v[48:63]
	v_mfma_f32_32x32x16_bf16 v[32:47], v[150:153], v[174:177], v[32:47]
	v_mfma_f32_32x32x16_bf16 v[16:31], v[158:161], v[166:169], v[16:31]
	v_mfma_f32_32x32x16_bf16 v[0:15], v[158:161], v[174:177], v[0:15]
	s_waitcnt lgkmcnt(0)
	s_barrier
	ds_read_b128 v[162:165], v203 offset:55296
	ds_read_b128 v[130:133], v203 offset:55328
	ds_read_b128 v[170:173], v235
	ds_read_b128 v[134:137], v235 offset:32
	ds_read_b128 v[166:169], v203 offset:59904
	ds_read_b128 v[142:145], v203 offset:59936
	ds_read_b128 v[174:177], v235 offset:4608
	ds_read_b128 v[150:153], v235 offset:4640
	ds_read_b128 v[138:141], v203 offset:55360
	ds_read_b128 v[116:119], v203 offset:55392
	ds_read_b128 v[146:149], v203 offset:59968
	ds_read_b128 v[112:115], v203 offset:60000
	ds_read_b128 v[154:157], v235 offset:64
	ds_read_b128 v[120:123], v235 offset:96
	ds_read_b128 v[158:161], v235 offset:4672
	ds_read_b128 v[124:127], v235 offset:4704
	s_waitcnt lgkmcnt(0)
	s_barrier
	v_mfma_f32_32x32x16_bf16 v[48:63], v[162:165], v[170:173], v[48:63]
	v_mfma_f32_32x32x16_bf16 v[32:47], v[162:165], v[174:177], v[32:47]
	v_mfma_f32_32x32x16_bf16 v[16:31], v[166:169], v[170:173], v[16:31]
	v_mfma_f32_32x32x16_bf16 v[0:15], v[166:169], v[174:177], v[0:15]
	v_mfma_f32_32x32x16_bf16 v[48:63], v[130:133], v[134:137], v[48:63]
	v_mfma_f32_32x32x16_bf16 v[32:47], v[130:133], v[150:153], v[32:47]
	v_mfma_f32_32x32x16_bf16 v[16:31], v[142:145], v[134:137], v[16:31]
	v_mfma_f32_32x32x16_bf16 v[0:15], v[142:145], v[150:153], v[0:15]
	v_mfma_f32_32x32x16_bf16 v[48:63], v[138:141], v[154:157], v[48:63]
	v_mfma_f32_32x32x16_bf16 v[32:47], v[138:141], v[158:161], v[32:47]
	v_mfma_f32_32x32x16_bf16 v[16:31], v[146:149], v[154:157], v[16:31]
	v_mfma_f32_32x32x16_bf16 v[0:15], v[146:149], v[158:161], v[0:15]
	v_mfma_f32_32x32x16_bf16 v[48:63], v[116:119], v[120:123], v[48:63]
	v_mfma_f32_32x32x16_bf16 v[32:47], v[116:119], v[124:127], v[32:47]
	v_mfma_f32_32x32x16_bf16 v[16:31], v[112:115], v[120:123], v[16:31]
	v_mfma_f32_32x32x16_bf16 v[0:15], v[112:115], v[124:127], v[0:15]
	s_waitcnt lgkmcnt(0)
	s_barrier
	s_branch .LBB0_1230

.LBB0_1234:
	s_waitcnt lgkmcnt(13)
	v_mfma_f32_32x32x16_bf16 v[48:63], v[116:119], v[124:127], v[48:63]
	s_waitcnt lgkmcnt(9)
	v_mfma_f32_32x32x16_bf16 v[32:47], v[116:119], v[154:157], v[32:47]
	v_mfma_f32_32x32x16_bf16 v[16:31], v[134:137], v[124:127], v[16:31]
	v_mfma_f32_32x32x16_bf16 v[0:15], v[134:137], v[154:157], v[0:15]
	v_mfma_f32_32x32x16_bf16 v[48:63], v[112:115], v[120:123], v[48:63]
	s_waitcnt lgkmcnt(8)
	v_mfma_f32_32x32x16_bf16 v[32:47], v[112:115], v[142:145], v[32:47]
	v_mfma_f32_32x32x16_bf16 v[16:31], v[130:133], v[120:123], v[16:31]
	v_mfma_f32_32x32x16_bf16 v[0:15], v[130:133], v[142:145], v[0:15]
	s_waitcnt lgkmcnt(3)
	v_mfma_f32_32x32x16_bf16 v[48:63], v[138:141], v[170:173], v[48:63]
	s_waitcnt lgkmcnt(1)
	v_mfma_f32_32x32x16_bf16 v[32:47], v[138:141], v[174:177], v[32:47]
	v_mfma_f32_32x32x16_bf16 v[16:31], v[158:161], v[170:173], v[16:31]
	v_mfma_f32_32x32x16_bf16 v[0:15], v[158:161], v[174:177], v[0:15]
	v_mfma_f32_32x32x16_bf16 v[48:63], v[146:149], v[162:165], v[48:63]
	s_waitcnt lgkmcnt(0)
	v_mfma_f32_32x32x16_bf16 v[32:47], v[146:149], v[166:169], v[32:47]
	v_mfma_f32_32x32x16_bf16 v[16:31], v[150:153], v[162:165], v[16:31]
	v_mfma_f32_32x32x16_bf16 v[0:15], v[150:153], v[166:169], v[0:15]
	s_waitcnt lgkmcnt(0)
	s_barrier
	ds_read_b128 v[116:119], v203 offset:55296
	ds_read_b128 v[112:115], v203 offset:55328
	ds_read_b128 v[124:127], v235
	ds_read_b128 v[120:123], v235 offset:32
	ds_read_b128 v[134:137], v203 offset:59904
	ds_read_b128 v[130:133], v203 offset:59936
	ds_read_b128 v[154:157], v235 offset:4608
	ds_read_b128 v[142:145], v235 offset:4640
	ds_read_b128 v[138:141], v203 offset:55360
	ds_read_b128 v[146:149], v203 offset:55392
	ds_read_b128 v[158:161], v203 offset:59968
	ds_read_b128 v[150:153], v203 offset:60000
	ds_read_b128 v[170:173], v235 offset:64
	ds_read_b128 v[162:165], v235 offset:96
	ds_read_b128 v[174:177], v235 offset:4672
	ds_read_b128 v[166:169], v235 offset:4704
	s_waitcnt lgkmcnt(0)
	s_barrier
	v_mfma_f32_32x32x16_bf16 v[48:63], v[116:119], v[124:127], v[48:63]
	v_mfma_f32_32x32x16_bf16 v[32:47], v[116:119], v[154:157], v[32:47]
	s_waitcnt vmcnt(11)
	ds_write_b128 v201, v[64:67]
	v_mfma_f32_32x32x16_bf16 v[16:31], v[134:137], v[124:127], v[16:31]
	global_load_dwordx4 v[64:67], v[182:183], off offset:512
	v_mfma_f32_32x32x16_bf16 v[0:15], v[134:137], v[154:157], v[0:15]
	s_waitcnt vmcnt(11)
	ds_write_b128 v201, v[68:71] offset:9216
	v_mfma_f32_32x32x16_bf16 v[48:63], v[112:115], v[120:123], v[48:63]
	global_load_dwordx4 v[68:71], v[186:187], off offset:512
	v_mfma_f32_32x32x16_bf16 v[32:47], v[112:115], v[142:145], v[32:47]
	s_waitcnt vmcnt(10)
	ds_write_b128 v201, v[84:87] offset:18432
	v_mfma_f32_32x32x16_bf16 v[16:31], v[130:133], v[120:123], v[16:31]
	global_load_dwordx4 v[84:87], v[188:189], off offset:512
	v_mfma_f32_32x32x16_bf16 v[0:15], v[130:133], v[142:145], v[0:15]
	ds_write_b128 v201, v[72:75] offset:27648
	v_mfma_f32_32x32x16_bf16 v[48:63], v[138:141], v[170:173], v[48:63]
	global_load_dwordx4 v[72:75], v[190:191], off offset:512
	v_mfma_f32_32x32x16_bf16 v[32:47], v[138:141], v[174:177], v[32:47]
	s_waitcnt vmcnt(11)
	ds_write_b128 v201, v[96:99] offset:36864
	v_mfma_f32_32x32x16_bf16 v[16:31], v[158:161], v[170:173], v[16:31]
	global_load_dwordx4 v[96:99], v[184:185], off offset:512
	v_mfma_f32_32x32x16_bf16 v[0:15], v[158:161], v[174:177], v[0:15]
	s_waitcnt vmcnt(11)
	ds_write_b128 v201, v[100:103] offset:46080
	v_mfma_f32_32x32x16_bf16 v[48:63], v[146:149], v[162:165], v[48:63]
	global_load_dwordx4 v[100:103], v[192:193], off offset:512
	v_mfma_f32_32x32x16_bf16 v[32:47], v[146:149], v[166:169], v[32:47]
	v_mfma_f32_32x32x16_bf16 v[16:31], v[150:153], v[162:165], v[16:31]
	v_mfma_f32_32x32x16_bf16 v[0:15], v[150:153], v[166:169], v[0:15]
	s_waitcnt lgkmcnt(0)
	s_barrier
	ds_read_b128 v[116:119], v203
	ds_read_b128 v[112:115], v203 offset:32
	ds_read_b128 v[124:127], v204 offset:36864
	ds_read_b128 v[120:123], v204 offset:36896
	ds_read_b128 v[134:137], v203 offset:4608
	ds_read_b128 v[130:133], v203 offset:4640
	ds_read_b128 v[154:157], v204 offset:41472
	ds_read_b128 v[142:145], v204 offset:41504
	ds_read_b128 v[138:141], v203 offset:64
	ds_read_b128 v[146:149], v203 offset:96
	ds_read_b128 v[158:161], v203 offset:4672
	ds_read_b128 v[150:153], v203 offset:4704
	ds_read_b128 v[170:173], v204 offset:36928
	ds_read_b128 v[162:165], v204 offset:36960
	ds_read_b128 v[174:177], v204 offset:41536
	ds_read_b128 v[166:169], v204 offset:41568
	s_waitcnt lgkmcnt(0)
	s_barrier
	v_mfma_f32_32x32x16_bf16 v[48:63], v[116:119], v[124:127], v[48:63]
	v_mfma_f32_32x32x16_bf16 v[32:47], v[116:119], v[154:157], v[32:47]
	s_waitcnt vmcnt(11)
	ds_write_b128 v201, v[76:79] offset:55296
	v_mfma_f32_32x32x16_bf16 v[16:31], v[134:137], v[124:127], v[16:31]
	global_load_dwordx4 v[76:79], v[182:183], off offset:640
	v_mfma_f32_32x32x16_bf16 v[0:15], v[134:137], v[154:157], v[0:15]
	s_waitcnt vmcnt(11)
	ds_write_b128 v201, v[80:83] offset:64512
	v_mfma_f32_32x32x16_bf16 v[48:63], v[112:115], v[120:123], v[48:63]
	global_load_dwordx4 v[80:83], v[186:187], off offset:640
	v_mfma_f32_32x32x16_bf16 v[32:47], v[112:115], v[142:145], v[32:47]
	s_waitcnt vmcnt(11)
	ds_write_b128 v205, v[88:91] offset:18432
	v_mfma_f32_32x32x16_bf16 v[16:31], v[130:133], v[120:123], v[16:31]
	global_load_dwordx4 v[88:91], v[188:189], off offset:640
	v_mfma_f32_32x32x16_bf16 v[0:15], v[130:133], v[142:145], v[0:15]
	s_waitcnt vmcnt(11)
	ds_write_b128 v205, v[92:95] offset:27648
	v_mfma_f32_32x32x16_bf16 v[48:63], v[138:141], v[170:173], v[48:63]
	global_load_dwordx4 v[92:95], v[190:191], off offset:640
	v_mfma_f32_32x32x16_bf16 v[32:47], v[138:141], v[174:177], v[32:47]
	s_waitcnt vmcnt(11)
	ds_write_b128 v234, v[104:107]
	v_mfma_f32_32x32x16_bf16 v[16:31], v[158:161], v[170:173], v[16:31]
	global_load_dwordx4 v[104:107], v[184:185], off offset:640
	v_mfma_f32_32x32x16_bf16 v[0:15], v[158:161], v[174:177], v[0:15]
	s_waitcnt vmcnt(11)
	ds_write_b128 v234, v[108:111] offset:9216
	v_mfma_f32_32x32x16_bf16 v[48:63], v[146:149], v[162:165], v[48:63]
	global_load_dwordx4 v[108:111], v[192:193], off offset:640
	v_mfma_f32_32x32x16_bf16 v[32:47], v[146:149], v[166:169], v[32:47]
	v_mfma_f32_32x32x16_bf16 v[16:31], v[150:153], v[162:165], v[16:31]
	v_mfma_f32_32x32x16_bf16 v[0:15], v[150:153], v[166:169], v[0:15]
	s_waitcnt lgkmcnt(0)
	s_barrier
	ds_read_b128 v[116:119], v203 offset:55296
	ds_read_b128 v[112:115], v203 offset:55328
	ds_read_b128 v[124:127], v235
	ds_read_b128 v[120:123], v235 offset:32
	ds_read_b128 v[134:137], v203 offset:59904
	ds_read_b128 v[130:133], v203 offset:59936
	ds_read_b128 v[154:157], v235 offset:4608
	ds_read_b128 v[142:145], v235 offset:4640
	ds_read_b128 v[138:141], v203 offset:55360
	ds_read_b128 v[146:149], v203 offset:55392
	ds_read_b128 v[158:161], v203 offset:59968
	ds_read_b128 v[150:153], v203 offset:60000
	ds_read_b128 v[170:173], v235 offset:64
	ds_read_b128 v[162:165], v235 offset:96
	ds_read_b128 v[174:177], v235 offset:4672
	ds_read_b128 v[166:169], v235 offset:4704
	s_waitcnt lgkmcnt(0)
	s_barrier
	v_mfma_f32_32x32x16_bf16 v[48:63], v[116:119], v[124:127], v[48:63]
	v_mfma_f32_32x32x16_bf16 v[32:47], v[116:119], v[154:157], v[32:47]
	s_waitcnt vmcnt(11)
	ds_write_b128 v201, v[64:67]
	v_mfma_f32_32x32x16_bf16 v[16:31], v[134:137], v[124:127], v[16:31]
	global_load_dwordx4 v[64:67], v[182:183], off offset:768
	v_mfma_f32_32x32x16_bf16 v[0:15], v[134:137], v[154:157], v[0:15]
	s_waitcnt vmcnt(11)
	ds_write_b128 v201, v[68:71] offset:9216
	v_mfma_f32_32x32x16_bf16 v[48:63], v[112:115], v[120:123], v[48:63]
	global_load_dwordx4 v[68:71], v[186:187], off offset:768
	v_mfma_f32_32x32x16_bf16 v[32:47], v[112:115], v[142:145], v[32:47]
	s_waitcnt vmcnt(11)
	ds_write_b128 v201, v[84:87] offset:18432
	v_mfma_f32_32x32x16_bf16 v[16:31], v[130:133], v[120:123], v[16:31]
	global_load_dwordx4 v[84:87], v[188:189], off offset:768
	v_mfma_f32_32x32x16_bf16 v[0:15], v[130:133], v[142:145], v[0:15]
	s_waitcnt vmcnt(11)
	ds_write_b128 v201, v[72:75] offset:27648
	v_mfma_f32_32x32x16_bf16 v[48:63], v[138:141], v[170:173], v[48:63]
	global_load_dwordx4 v[72:75], v[190:191], off offset:768
	v_mfma_f32_32x32x16_bf16 v[32:47], v[138:141], v[174:177], v[32:47]
	s_waitcnt vmcnt(11)
	ds_write_b128 v201, v[96:99] offset:36864
	v_mfma_f32_32x32x16_bf16 v[16:31], v[158:161], v[170:173], v[16:31]
	global_load_dwordx4 v[96:99], v[184:185], off offset:768
	v_mfma_f32_32x32x16_bf16 v[0:15], v[158:161], v[174:177], v[0:15]
	s_waitcnt vmcnt(11)
	ds_write_b128 v201, v[100:103] offset:46080
	v_mfma_f32_32x32x16_bf16 v[48:63], v[146:149], v[162:165], v[48:63]
	global_load_dwordx4 v[100:103], v[192:193], off offset:768
	v_mfma_f32_32x32x16_bf16 v[32:47], v[146:149], v[166:169], v[32:47]
	v_mfma_f32_32x32x16_bf16 v[16:31], v[150:153], v[162:165], v[16:31]
	v_mfma_f32_32x32x16_bf16 v[0:15], v[150:153], v[166:169], v[0:15]
	s_waitcnt lgkmcnt(0)
	s_barrier
	ds_read_b128 v[116:119], v203
	ds_read_b128 v[112:115], v203 offset:32
	ds_read_b128 v[124:127], v204 offset:36864
	ds_read_b128 v[120:123], v204 offset:36896
	ds_read_b128 v[134:137], v203 offset:4608
	ds_read_b128 v[130:133], v203 offset:4640
	ds_read_b128 v[154:157], v204 offset:41472
	ds_read_b128 v[142:145], v204 offset:41504
	ds_read_b128 v[138:141], v203 offset:64
	ds_read_b128 v[146:149], v203 offset:96
	ds_read_b128 v[158:161], v203 offset:4672
	ds_read_b128 v[150:153], v203 offset:4704
	ds_read_b128 v[170:173], v204 offset:36928
	ds_read_b128 v[162:165], v204 offset:36960
	ds_read_b128 v[174:177], v204 offset:41536
	ds_read_b128 v[166:169], v204 offset:41568
	s_waitcnt lgkmcnt(0)
	s_barrier
	v_mfma_f32_32x32x16_bf16 v[48:63], v[116:119], v[124:127], v[48:63]
	v_mfma_f32_32x32x16_bf16 v[32:47], v[116:119], v[154:157], v[32:47]
	s_waitcnt vmcnt(11)
	ds_write_b128 v201, v[76:79] offset:55296
	v_mfma_f32_32x32x16_bf16 v[16:31], v[134:137], v[124:127], v[16:31]
	global_load_dwordx4 v[76:79], v[182:183], off offset:896
	v_mfma_f32_32x32x16_bf16 v[0:15], v[134:137], v[154:157], v[0:15]
	s_waitcnt vmcnt(11)
	ds_write_b128 v201, v[80:83] offset:64512
	v_mfma_f32_32x32x16_bf16 v[48:63], v[112:115], v[120:123], v[48:63]
	global_load_dwordx4 v[80:83], v[186:187], off offset:896
	v_mfma_f32_32x32x16_bf16 v[32:47], v[112:115], v[142:145], v[32:47]
	s_waitcnt vmcnt(11)
	ds_write_b128 v205, v[88:91] offset:18432
	v_mfma_f32_32x32x16_bf16 v[16:31], v[130:133], v[120:123], v[16:31]
	global_load_dwordx4 v[88:91], v[188:189], off offset:896
	v_mfma_f32_32x32x16_bf16 v[0:15], v[130:133], v[142:145], v[0:15]
	s_waitcnt vmcnt(11)
	ds_write_b128 v205, v[92:95] offset:27648
	v_mfma_f32_32x32x16_bf16 v[48:63], v[138:141], v[170:173], v[48:63]
	global_load_dwordx4 v[92:95], v[190:191], off offset:896
	v_mfma_f32_32x32x16_bf16 v[32:47], v[138:141], v[174:177], v[32:47]
	s_waitcnt vmcnt(11)
	ds_write_b128 v234, v[104:107]
	v_mfma_f32_32x32x16_bf16 v[16:31], v[158:161], v[170:173], v[16:31]
	global_load_dwordx4 v[104:107], v[184:185], off offset:896
	v_mfma_f32_32x32x16_bf16 v[0:15], v[158:161], v[174:177], v[0:15]
	s_waitcnt vmcnt(11)
	ds_write_b128 v234, v[108:111] offset:9216
	v_mfma_f32_32x32x16_bf16 v[48:63], v[146:149], v[162:165], v[48:63]
	global_load_dwordx4 v[108:111], v[192:193], off offset:896
	v_mfma_f32_32x32x16_bf16 v[32:47], v[146:149], v[166:169], v[32:47]
	v_mfma_f32_32x32x16_bf16 v[16:31], v[150:153], v[162:165], v[16:31]
	v_mfma_f32_32x32x16_bf16 v[0:15], v[150:153], v[166:169], v[0:15]
	s_waitcnt lgkmcnt(0)
	s_barrier
	ds_read_b128 v[116:119], v203 offset:55296
	ds_read_b128 v[112:115], v203 offset:55328
	ds_read_b128 v[124:127], v235
	ds_read_b128 v[120:123], v235 offset:32
	ds_read_b128 v[134:137], v203 offset:59904
	ds_read_b128 v[130:133], v203 offset:59936
	ds_read_b128 v[154:157], v235 offset:4608
	ds_read_b128 v[142:145], v235 offset:4640
	ds_read_b128 v[138:141], v203 offset:55360
	ds_read_b128 v[146:149], v203 offset:55392
	ds_read_b128 v[158:161], v203 offset:59968
	ds_read_b128 v[150:153], v203 offset:60000
	ds_read_b128 v[170:173], v235 offset:64
	ds_read_b128 v[162:165], v235 offset:96
	ds_read_b128 v[174:177], v235 offset:4672
	ds_read_b128 v[166:169], v235 offset:4704
	s_waitcnt lgkmcnt(0)
	s_barrier
	v_mfma_f32_32x32x16_bf16 v[48:63], v[116:119], v[124:127], v[48:63]
	v_mfma_f32_32x32x16_bf16 v[32:47], v[116:119], v[154:157], v[32:47]
	s_waitcnt vmcnt(11)
	ds_write_b128 v201, v[64:67]
	v_mfma_f32_32x32x16_bf16 v[16:31], v[134:137], v[124:127], v[16:31]
	global_load_dwordx4 v[64:67], v[182:183], off offset:1024
	v_mfma_f32_32x32x16_bf16 v[0:15], v[134:137], v[154:157], v[0:15]
	s_waitcnt vmcnt(11)
	ds_write_b128 v201, v[68:71] offset:9216
	v_mfma_f32_32x32x16_bf16 v[48:63], v[112:115], v[120:123], v[48:63]
	global_load_dwordx4 v[68:71], v[186:187], off offset:1024
	v_mfma_f32_32x32x16_bf16 v[32:47], v[112:115], v[142:145], v[32:47]
	s_waitcnt vmcnt(11)
	ds_write_b128 v201, v[84:87] offset:18432
	v_mfma_f32_32x32x16_bf16 v[16:31], v[130:133], v[120:123], v[16:31]
	global_load_dwordx4 v[84:87], v[188:189], off offset:1024
	v_mfma_f32_32x32x16_bf16 v[0:15], v[130:133], v[142:145], v[0:15]
	s_waitcnt vmcnt(11)
	ds_write_b128 v201, v[72:75] offset:27648
	v_mfma_f32_32x32x16_bf16 v[48:63], v[138:141], v[170:173], v[48:63]
	global_load_dwordx4 v[72:75], v[190:191], off offset:1024
	v_mfma_f32_32x32x16_bf16 v[32:47], v[138:141], v[174:177], v[32:47]
	s_waitcnt vmcnt(11)
	ds_write_b128 v201, v[96:99] offset:36864
	v_mfma_f32_32x32x16_bf16 v[16:31], v[158:161], v[170:173], v[16:31]
	global_load_dwordx4 v[96:99], v[184:185], off offset:1024
	v_mfma_f32_32x32x16_bf16 v[0:15], v[158:161], v[174:177], v[0:15]
	s_waitcnt vmcnt(11)
	ds_write_b128 v201, v[100:103] offset:46080
	v_mfma_f32_32x32x16_bf16 v[48:63], v[146:149], v[162:165], v[48:63]
	global_load_dwordx4 v[100:103], v[192:193], off offset:1024
	v_mfma_f32_32x32x16_bf16 v[32:47], v[146:149], v[166:169], v[32:47]
	v_mfma_f32_32x32x16_bf16 v[16:31], v[150:153], v[162:165], v[16:31]
	v_mfma_f32_32x32x16_bf16 v[0:15], v[150:153], v[166:169], v[0:15]
	s_waitcnt lgkmcnt(0)
	s_barrier
	ds_read_b128 v[116:119], v203
	ds_read_b128 v[112:115], v203 offset:32
	ds_read_b128 v[124:127], v204 offset:36864
	ds_read_b128 v[120:123], v204 offset:36896
	ds_read_b128 v[134:137], v203 offset:4608
	ds_read_b128 v[130:133], v203 offset:4640
	ds_read_b128 v[154:157], v204 offset:41472
	ds_read_b128 v[142:145], v204 offset:41504
	ds_read_b128 v[138:141], v203 offset:64
	ds_read_b128 v[146:149], v203 offset:96
	ds_read_b128 v[158:161], v203 offset:4672
	ds_read_b128 v[150:153], v203 offset:4704
	ds_read_b128 v[170:173], v204 offset:36928
	ds_read_b128 v[162:165], v204 offset:36960
	ds_read_b128 v[174:177], v204 offset:41536
	ds_read_b128 v[166:169], v204 offset:41568
	s_waitcnt lgkmcnt(0)
	s_barrier
	v_mfma_f32_32x32x16_bf16 v[48:63], v[116:119], v[124:127], v[48:63]
	v_mfma_f32_32x32x16_bf16 v[32:47], v[116:119], v[154:157], v[32:47]
	s_waitcnt vmcnt(11)
	ds_write_b128 v201, v[76:79] offset:55296
	v_mfma_f32_32x32x16_bf16 v[16:31], v[134:137], v[124:127], v[16:31]
	global_load_dwordx4 v[76:79], v[182:183], off offset:1152
	v_mfma_f32_32x32x16_bf16 v[0:15], v[134:137], v[154:157], v[0:15]
	s_waitcnt vmcnt(11)
	ds_write_b128 v201, v[80:83] offset:64512
	v_mfma_f32_32x32x16_bf16 v[48:63], v[112:115], v[120:123], v[48:63]
	global_load_dwordx4 v[80:83], v[186:187], off offset:1152
	v_mfma_f32_32x32x16_bf16 v[32:47], v[112:115], v[142:145], v[32:47]
	s_waitcnt vmcnt(11)
	ds_write_b128 v205, v[88:91] offset:18432
	v_mfma_f32_32x32x16_bf16 v[16:31], v[130:133], v[120:123], v[16:31]
	global_load_dwordx4 v[88:91], v[188:189], off offset:1152
	v_mfma_f32_32x32x16_bf16 v[0:15], v[130:133], v[142:145], v[0:15]
	s_waitcnt vmcnt(11)
	ds_write_b128 v205, v[92:95] offset:27648
	v_mfma_f32_32x32x16_bf16 v[48:63], v[138:141], v[170:173], v[48:63]
	global_load_dwordx4 v[92:95], v[190:191], off offset:1152
	v_mfma_f32_32x32x16_bf16 v[32:47], v[138:141], v[174:177], v[32:47]
	s_waitcnt vmcnt(11)
	ds_write_b128 v234, v[104:107]
	v_mfma_f32_32x32x16_bf16 v[16:31], v[158:161], v[170:173], v[16:31]
	global_load_dwordx4 v[104:107], v[184:185], off offset:1152
	v_mfma_f32_32x32x16_bf16 v[0:15], v[158:161], v[174:177], v[0:15]
	s_waitcnt vmcnt(11)
	ds_write_b128 v234, v[108:111] offset:9216
	v_mfma_f32_32x32x16_bf16 v[48:63], v[146:149], v[162:165], v[48:63]
	global_load_dwordx4 v[108:111], v[192:193], off offset:1152
	v_mfma_f32_32x32x16_bf16 v[32:47], v[146:149], v[166:169], v[32:47]
	v_mfma_f32_32x32x16_bf16 v[16:31], v[150:153], v[162:165], v[16:31]
	v_mfma_f32_32x32x16_bf16 v[0:15], v[150:153], v[166:169], v[0:15]
	s_waitcnt lgkmcnt(0)
	s_barrier
	ds_read_b128 v[116:119], v203 offset:55296
	ds_read_b128 v[112:115], v203 offset:55328
	ds_read_b128 v[124:127], v235
	ds_read_b128 v[120:123], v235 offset:32
	ds_read_b128 v[134:137], v203 offset:59904
	ds_read_b128 v[130:133], v203 offset:59936
	ds_read_b128 v[154:157], v235 offset:4608
	ds_read_b128 v[142:145], v235 offset:4640
	ds_read_b128 v[138:141], v203 offset:55360
	ds_read_b128 v[146:149], v203 offset:55392
	ds_read_b128 v[158:161], v203 offset:59968
	ds_read_b128 v[150:153], v203 offset:60000
	ds_read_b128 v[170:173], v235 offset:64
	ds_read_b128 v[162:165], v235 offset:96
	ds_read_b128 v[174:177], v235 offset:4672
	ds_read_b128 v[166:169], v235 offset:4704
	s_waitcnt lgkmcnt(0)
	s_barrier
	v_mfma_f32_32x32x16_bf16 v[48:63], v[116:119], v[124:127], v[48:63]
	v_mfma_f32_32x32x16_bf16 v[32:47], v[116:119], v[154:157], v[32:47]
	s_waitcnt vmcnt(11)
	ds_write_b128 v201, v[64:67]
	v_mfma_f32_32x32x16_bf16 v[16:31], v[134:137], v[124:127], v[16:31]
	global_load_dwordx4 v[64:67], v[182:183], off offset:1280
	v_mfma_f32_32x32x16_bf16 v[0:15], v[134:137], v[154:157], v[0:15]
	s_waitcnt vmcnt(11)
	ds_write_b128 v201, v[68:71] offset:9216
	v_mfma_f32_32x32x16_bf16 v[48:63], v[112:115], v[120:123], v[48:63]
	global_load_dwordx4 v[68:71], v[186:187], off offset:1280
	v_mfma_f32_32x32x16_bf16 v[32:47], v[112:115], v[142:145], v[32:47]
	s_waitcnt vmcnt(11)
	ds_write_b128 v201, v[84:87] offset:18432
	v_mfma_f32_32x32x16_bf16 v[16:31], v[130:133], v[120:123], v[16:31]
	global_load_dwordx4 v[84:87], v[188:189], off offset:1280
	v_mfma_f32_32x32x16_bf16 v[0:15], v[130:133], v[142:145], v[0:15]
	s_waitcnt vmcnt(11)
	ds_write_b128 v201, v[72:75] offset:27648
	v_mfma_f32_32x32x16_bf16 v[48:63], v[138:141], v[170:173], v[48:63]
	global_load_dwordx4 v[72:75], v[190:191], off offset:1280
	v_mfma_f32_32x32x16_bf16 v[32:47], v[138:141], v[174:177], v[32:47]
	s_waitcnt vmcnt(11)
	ds_write_b128 v201, v[96:99] offset:36864
	v_mfma_f32_32x32x16_bf16 v[16:31], v[158:161], v[170:173], v[16:31]
	global_load_dwordx4 v[96:99], v[184:185], off offset:1280
	v_mfma_f32_32x32x16_bf16 v[0:15], v[158:161], v[174:177], v[0:15]
	s_waitcnt vmcnt(11)
	ds_write_b128 v201, v[100:103] offset:46080
	v_mfma_f32_32x32x16_bf16 v[48:63], v[146:149], v[162:165], v[48:63]
	global_load_dwordx4 v[100:103], v[192:193], off offset:1280
	v_mfma_f32_32x32x16_bf16 v[32:47], v[146:149], v[166:169], v[32:47]
	v_mfma_f32_32x32x16_bf16 v[16:31], v[150:153], v[162:165], v[16:31]
	v_mfma_f32_32x32x16_bf16 v[0:15], v[150:153], v[166:169], v[0:15]
	s_waitcnt lgkmcnt(0)
	s_barrier
	ds_read_b128 v[116:119], v203
	ds_read_b128 v[112:115], v203 offset:32
	ds_read_b128 v[124:127], v204 offset:36864
	ds_read_b128 v[120:123], v204 offset:36896
	ds_read_b128 v[134:137], v203 offset:4608
	ds_read_b128 v[130:133], v203 offset:4640
	ds_read_b128 v[154:157], v204 offset:41472
	ds_read_b128 v[142:145], v204 offset:41504
	ds_read_b128 v[138:141], v203 offset:64
	ds_read_b128 v[146:149], v203 offset:96
	ds_read_b128 v[158:161], v203 offset:4672
	ds_read_b128 v[150:153], v203 offset:4704
	ds_read_b128 v[170:173], v204 offset:36928
	ds_read_b128 v[162:165], v204 offset:36960
	ds_read_b128 v[174:177], v204 offset:41536
	ds_read_b128 v[166:169], v204 offset:41568
	s_waitcnt lgkmcnt(0)
	s_barrier
	v_mfma_f32_32x32x16_bf16 v[48:63], v[116:119], v[124:127], v[48:63]
	v_mfma_f32_32x32x16_bf16 v[32:47], v[116:119], v[154:157], v[32:47]
	s_waitcnt vmcnt(11)
	ds_write_b128 v201, v[76:79] offset:55296
	v_mfma_f32_32x32x16_bf16 v[16:31], v[134:137], v[124:127], v[16:31]
	global_load_dwordx4 v[76:79], v[182:183], off offset:1408
	v_mfma_f32_32x32x16_bf16 v[0:15], v[134:137], v[154:157], v[0:15]
	s_waitcnt vmcnt(11)
	ds_write_b128 v201, v[80:83] offset:64512
	v_mfma_f32_32x32x16_bf16 v[48:63], v[112:115], v[120:123], v[48:63]
	global_load_dwordx4 v[80:83], v[186:187], off offset:1408
	v_mfma_f32_32x32x16_bf16 v[32:47], v[112:115], v[142:145], v[32:47]
	s_waitcnt vmcnt(11)
	ds_write_b128 v205, v[88:91] offset:18432
	v_mfma_f32_32x32x16_bf16 v[16:31], v[130:133], v[120:123], v[16:31]
	global_load_dwordx4 v[88:91], v[188:189], off offset:1408
	v_mfma_f32_32x32x16_bf16 v[0:15], v[130:133], v[142:145], v[0:15]
	s_waitcnt vmcnt(11)
	ds_write_b128 v205, v[92:95] offset:27648
	v_mfma_f32_32x32x16_bf16 v[48:63], v[138:141], v[170:173], v[48:63]
	global_load_dwordx4 v[92:95], v[190:191], off offset:1408
	v_mfma_f32_32x32x16_bf16 v[32:47], v[138:141], v[174:177], v[32:47]
	s_waitcnt vmcnt(11)
	ds_write_b128 v234, v[104:107]
	v_mfma_f32_32x32x16_bf16 v[16:31], v[158:161], v[170:173], v[16:31]
	global_load_dwordx4 v[104:107], v[184:185], off offset:1408
	v_mfma_f32_32x32x16_bf16 v[0:15], v[158:161], v[174:177], v[0:15]
	s_waitcnt vmcnt(11)
	ds_write_b128 v234, v[108:111] offset:9216
	v_mfma_f32_32x32x16_bf16 v[48:63], v[146:149], v[162:165], v[48:63]
	global_load_dwordx4 v[108:111], v[192:193], off offset:1408
	v_mfma_f32_32x32x16_bf16 v[32:47], v[146:149], v[166:169], v[32:47]
	v_mfma_f32_32x32x16_bf16 v[16:31], v[150:153], v[162:165], v[16:31]
	v_mfma_f32_32x32x16_bf16 v[0:15], v[150:153], v[166:169], v[0:15]
	s_waitcnt lgkmcnt(0)
	s_barrier
	ds_read_b128 v[116:119], v203 offset:55296
	ds_read_b128 v[112:115], v203 offset:55328
	ds_read_b128 v[124:127], v235
	ds_read_b128 v[120:123], v235 offset:32
	ds_read_b128 v[134:137], v203 offset:59904
	ds_read_b128 v[130:133], v203 offset:59936
	ds_read_b128 v[154:157], v235 offset:4608
	ds_read_b128 v[142:145], v235 offset:4640
	ds_read_b128 v[138:141], v203 offset:55360
	ds_read_b128 v[146:149], v203 offset:55392
	ds_read_b128 v[158:161], v203 offset:59968
	ds_read_b128 v[150:153], v203 offset:60000
	ds_read_b128 v[170:173], v235 offset:64
	ds_read_b128 v[162:165], v235 offset:96
	ds_read_b128 v[174:177], v235 offset:4672
	ds_read_b128 v[166:169], v235 offset:4704
	s_waitcnt lgkmcnt(0)
	s_barrier
	v_mfma_f32_32x32x16_bf16 v[48:63], v[116:119], v[124:127], v[48:63]
	v_mfma_f32_32x32x16_bf16 v[32:47], v[116:119], v[154:157], v[32:47]
	s_waitcnt vmcnt(11)
	ds_write_b128 v201, v[64:67]
	v_mfma_f32_32x32x16_bf16 v[16:31], v[134:137], v[124:127], v[16:31]
	global_load_dwordx4 v[64:67], v[182:183], off offset:1536
	v_mfma_f32_32x32x16_bf16 v[0:15], v[134:137], v[154:157], v[0:15]
	s_waitcnt vmcnt(11)
	ds_write_b128 v201, v[68:71] offset:9216
	v_mfma_f32_32x32x16_bf16 v[48:63], v[112:115], v[120:123], v[48:63]
	global_load_dwordx4 v[68:71], v[186:187], off offset:1536
	v_mfma_f32_32x32x16_bf16 v[32:47], v[112:115], v[142:145], v[32:47]
	s_waitcnt vmcnt(11)
	ds_write_b128 v201, v[84:87] offset:18432
	v_mfma_f32_32x32x16_bf16 v[16:31], v[130:133], v[120:123], v[16:31]
	global_load_dwordx4 v[84:87], v[188:189], off offset:1536
	v_mfma_f32_32x32x16_bf16 v[0:15], v[130:133], v[142:145], v[0:15]
	s_waitcnt vmcnt(11)
	ds_write_b128 v201, v[72:75] offset:27648
	v_mfma_f32_32x32x16_bf16 v[48:63], v[138:141], v[170:173], v[48:63]
	global_load_dwordx4 v[72:75], v[190:191], off offset:1536
	v_mfma_f32_32x32x16_bf16 v[32:47], v[138:141], v[174:177], v[32:47]
	s_waitcnt vmcnt(11)
	ds_write_b128 v201, v[96:99] offset:36864
	v_mfma_f32_32x32x16_bf16 v[16:31], v[158:161], v[170:173], v[16:31]
	global_load_dwordx4 v[96:99], v[184:185], off offset:1536
	v_mfma_f32_32x32x16_bf16 v[0:15], v[158:161], v[174:177], v[0:15]
	s_waitcnt vmcnt(11)
	ds_write_b128 v201, v[100:103] offset:46080
	v_mfma_f32_32x32x16_bf16 v[48:63], v[146:149], v[162:165], v[48:63]
	global_load_dwordx4 v[100:103], v[192:193], off offset:1536
	v_mfma_f32_32x32x16_bf16 v[32:47], v[146:149], v[166:169], v[32:47]
	v_mfma_f32_32x32x16_bf16 v[16:31], v[150:153], v[162:165], v[16:31]
	v_mfma_f32_32x32x16_bf16 v[0:15], v[150:153], v[166:169], v[0:15]
	s_waitcnt lgkmcnt(0)
	s_barrier
	ds_read_b128 v[116:119], v203
	ds_read_b128 v[112:115], v203 offset:32
	ds_read_b128 v[124:127], v204 offset:36864
	ds_read_b128 v[120:123], v204 offset:36896
	ds_read_b128 v[134:137], v203 offset:4608
	ds_read_b128 v[130:133], v203 offset:4640
	ds_read_b128 v[154:157], v204 offset:41472
	ds_read_b128 v[142:145], v204 offset:41504
	ds_read_b128 v[138:141], v203 offset:64
	ds_read_b128 v[146:149], v203 offset:96
	ds_read_b128 v[158:161], v203 offset:4672
	ds_read_b128 v[150:153], v203 offset:4704
	ds_read_b128 v[170:173], v204 offset:36928
	ds_read_b128 v[162:165], v204 offset:36960
	ds_read_b128 v[174:177], v204 offset:41536
	ds_read_b128 v[166:169], v204 offset:41568
	s_waitcnt lgkmcnt(0)
	s_barrier
	v_mfma_f32_32x32x16_bf16 v[48:63], v[116:119], v[124:127], v[48:63]
	v_mfma_f32_32x32x16_bf16 v[32:47], v[116:119], v[154:157], v[32:47]
	s_waitcnt vmcnt(11)
	ds_write_b128 v201, v[76:79] offset:55296
	v_mfma_f32_32x32x16_bf16 v[16:31], v[134:137], v[124:127], v[16:31]
	global_load_dwordx4 v[76:79], v[182:183], off offset:1664
	v_mfma_f32_32x32x16_bf16 v[0:15], v[134:137], v[154:157], v[0:15]
	s_waitcnt vmcnt(11)
	ds_write_b128 v201, v[80:83] offset:64512
	v_mfma_f32_32x32x16_bf16 v[48:63], v[112:115], v[120:123], v[48:63]
	global_load_dwordx4 v[80:83], v[186:187], off offset:1664
	v_mfma_f32_32x32x16_bf16 v[32:47], v[112:115], v[142:145], v[32:47]
	s_waitcnt vmcnt(11)
	ds_write_b128 v205, v[88:91] offset:18432
	v_mfma_f32_32x32x16_bf16 v[16:31], v[130:133], v[120:123], v[16:31]
	global_load_dwordx4 v[88:91], v[188:189], off offset:1664
	v_mfma_f32_32x32x16_bf16 v[0:15], v[130:133], v[142:145], v[0:15]
	s_waitcnt vmcnt(11)
	ds_write_b128 v205, v[92:95] offset:27648
	v_mfma_f32_32x32x16_bf16 v[48:63], v[138:141], v[170:173], v[48:63]
	global_load_dwordx4 v[92:95], v[190:191], off offset:1664
	v_mfma_f32_32x32x16_bf16 v[32:47], v[138:141], v[174:177], v[32:47]
	s_waitcnt vmcnt(11)
	ds_write_b128 v234, v[104:107]
	v_mfma_f32_32x32x16_bf16 v[16:31], v[158:161], v[170:173], v[16:31]
	global_load_dwordx4 v[104:107], v[184:185], off offset:1664
	v_mfma_f32_32x32x16_bf16 v[0:15], v[158:161], v[174:177], v[0:15]
	s_waitcnt vmcnt(11)
	ds_write_b128 v234, v[108:111] offset:9216
	v_mfma_f32_32x32x16_bf16 v[48:63], v[146:149], v[162:165], v[48:63]
	global_load_dwordx4 v[108:111], v[192:193], off offset:1664
	v_mfma_f32_32x32x16_bf16 v[32:47], v[146:149], v[166:169], v[32:47]
	v_mfma_f32_32x32x16_bf16 v[16:31], v[150:153], v[162:165], v[16:31]
	v_mfma_f32_32x32x16_bf16 v[0:15], v[150:153], v[166:169], v[0:15]
	s_waitcnt lgkmcnt(0)
	s_barrier
	ds_read_b128 v[116:119], v203 offset:55296
	ds_read_b128 v[112:115], v203 offset:55328
	ds_read_b128 v[124:127], v235
	ds_read_b128 v[120:123], v235 offset:32
	ds_read_b128 v[134:137], v203 offset:59904
	ds_read_b128 v[130:133], v203 offset:59936
	ds_read_b128 v[154:157], v235 offset:4608
	ds_read_b128 v[142:145], v235 offset:4640
	ds_read_b128 v[138:141], v203 offset:55360
	ds_read_b128 v[146:149], v203 offset:55392
	ds_read_b128 v[158:161], v203 offset:59968
	ds_read_b128 v[150:153], v203 offset:60000
	ds_read_b128 v[170:173], v235 offset:64
	ds_read_b128 v[162:165], v235 offset:96
	ds_read_b128 v[174:177], v235 offset:4672
	ds_read_b128 v[166:169], v235 offset:4704
	s_waitcnt lgkmcnt(0)
	s_barrier
	v_mfma_f32_32x32x16_bf16 v[48:63], v[116:119], v[124:127], v[48:63]
	v_mfma_f32_32x32x16_bf16 v[32:47], v[116:119], v[154:157], v[32:47]
	s_waitcnt vmcnt(11)
	ds_write_b128 v201, v[64:67]
	v_mfma_f32_32x32x16_bf16 v[16:31], v[134:137], v[124:127], v[16:31]
	global_load_dwordx4 v[64:67], v[182:183], off offset:1792
	v_mfma_f32_32x32x16_bf16 v[0:15], v[134:137], v[154:157], v[0:15]
	s_waitcnt vmcnt(11)
	ds_write_b128 v201, v[68:71] offset:9216
	v_mfma_f32_32x32x16_bf16 v[48:63], v[112:115], v[120:123], v[48:63]
	global_load_dwordx4 v[68:71], v[186:187], off offset:1792
	v_mfma_f32_32x32x16_bf16 v[32:47], v[112:115], v[142:145], v[32:47]
	s_waitcnt vmcnt(11)
	ds_write_b128 v201, v[84:87] offset:18432
	v_mfma_f32_32x32x16_bf16 v[16:31], v[130:133], v[120:123], v[16:31]
	global_load_dwordx4 v[84:87], v[188:189], off offset:1792
	v_mfma_f32_32x32x16_bf16 v[0:15], v[130:133], v[142:145], v[0:15]
	s_waitcnt vmcnt(11)
	ds_write_b128 v201, v[72:75] offset:27648
	v_mfma_f32_32x32x16_bf16 v[48:63], v[138:141], v[170:173], v[48:63]
	global_load_dwordx4 v[72:75], v[190:191], off offset:1792
	v_mfma_f32_32x32x16_bf16 v[32:47], v[138:141], v[174:177], v[32:47]
	s_waitcnt vmcnt(11)
	ds_write_b128 v201, v[96:99] offset:36864
	v_mfma_f32_32x32x16_bf16 v[16:31], v[158:161], v[170:173], v[16:31]
	global_load_dwordx4 v[96:99], v[184:185], off offset:1792
	v_mfma_f32_32x32x16_bf16 v[0:15], v[158:161], v[174:177], v[0:15]
	s_waitcnt vmcnt(11)
	ds_write_b128 v201, v[100:103] offset:46080
	v_mfma_f32_32x32x16_bf16 v[48:63], v[146:149], v[162:165], v[48:63]
	global_load_dwordx4 v[100:103], v[192:193], off offset:1792
	v_mfma_f32_32x32x16_bf16 v[32:47], v[146:149], v[166:169], v[32:47]
	v_mfma_f32_32x32x16_bf16 v[16:31], v[150:153], v[162:165], v[16:31]
	v_mfma_f32_32x32x16_bf16 v[0:15], v[150:153], v[166:169], v[0:15]
	s_waitcnt lgkmcnt(0)
	s_barrier
	ds_read_b128 v[116:119], v203
	ds_read_b128 v[112:115], v203 offset:32
	ds_read_b128 v[124:127], v204 offset:36864
	ds_read_b128 v[120:123], v204 offset:36896
	ds_read_b128 v[134:137], v203 offset:4608
	ds_read_b128 v[130:133], v203 offset:4640
	ds_read_b128 v[154:157], v204 offset:41472
	ds_read_b128 v[142:145], v204 offset:41504
	ds_read_b128 v[138:141], v203 offset:64
	ds_read_b128 v[146:149], v203 offset:96
	ds_read_b128 v[158:161], v203 offset:4672
	ds_read_b128 v[150:153], v203 offset:4704
	ds_read_b128 v[170:173], v204 offset:36928
	ds_read_b128 v[162:165], v204 offset:36960
	ds_read_b128 v[174:177], v204 offset:41536
	ds_read_b128 v[166:169], v204 offset:41568
	s_waitcnt lgkmcnt(0)
	s_barrier
	v_mfma_f32_32x32x16_bf16 v[48:63], v[116:119], v[124:127], v[48:63]
	v_mfma_f32_32x32x16_bf16 v[32:47], v[116:119], v[154:157], v[32:47]
	s_waitcnt vmcnt(11)
	ds_write_b128 v201, v[76:79] offset:55296
	v_mfma_f32_32x32x16_bf16 v[16:31], v[134:137], v[124:127], v[16:31]
	global_load_dwordx4 v[76:79], v[182:183], off offset:1920
	v_mfma_f32_32x32x16_bf16 v[0:15], v[134:137], v[154:157], v[0:15]
	s_waitcnt vmcnt(11)
	ds_write_b128 v201, v[80:83] offset:64512
	v_mfma_f32_32x32x16_bf16 v[48:63], v[112:115], v[120:123], v[48:63]
	global_load_dwordx4 v[80:83], v[186:187], off offset:1920
	v_mfma_f32_32x32x16_bf16 v[32:47], v[112:115], v[142:145], v[32:47]
	s_waitcnt vmcnt(11)
	ds_write_b128 v205, v[88:91] offset:18432
	v_mfma_f32_32x32x16_bf16 v[16:31], v[130:133], v[120:123], v[16:31]
	global_load_dwordx4 v[88:91], v[188:189], off offset:1920
	v_mfma_f32_32x32x16_bf16 v[0:15], v[130:133], v[142:145], v[0:15]
	s_waitcnt vmcnt(11)
	ds_write_b128 v205, v[92:95] offset:27648
	v_mfma_f32_32x32x16_bf16 v[48:63], v[138:141], v[170:173], v[48:63]
	global_load_dwordx4 v[92:95], v[190:191], off offset:1920
	v_mfma_f32_32x32x16_bf16 v[32:47], v[138:141], v[174:177], v[32:47]
	s_waitcnt vmcnt(11)
	ds_write_b128 v234, v[104:107]
	v_mfma_f32_32x32x16_bf16 v[16:31], v[158:161], v[170:173], v[16:31]
	global_load_dwordx4 v[104:107], v[184:185], off offset:1920
	v_mfma_f32_32x32x16_bf16 v[0:15], v[158:161], v[174:177], v[0:15]
	s_waitcnt vmcnt(11)
	ds_write_b128 v234, v[108:111] offset:9216
	v_mfma_f32_32x32x16_bf16 v[48:63], v[146:149], v[162:165], v[48:63]
	global_load_dwordx4 v[108:111], v[192:193], off offset:1920
	v_mfma_f32_32x32x16_bf16 v[32:47], v[146:149], v[166:169], v[32:47]
	v_mfma_f32_32x32x16_bf16 v[16:31], v[150:153], v[162:165], v[16:31]
	v_mfma_f32_32x32x16_bf16 v[0:15], v[150:153], v[166:169], v[0:15]
	s_waitcnt lgkmcnt(0)
	s_barrier
	ds_read_b128 v[116:119], v203 offset:55296
	ds_read_b128 v[112:115], v203 offset:55328
	ds_read_b128 v[124:127], v235
	ds_read_b128 v[120:123], v235 offset:32
	ds_read_b128 v[134:137], v203 offset:59904
	ds_read_b128 v[130:133], v203 offset:59936
	ds_read_b128 v[154:157], v235 offset:4608
	ds_read_b128 v[142:145], v235 offset:4640
	ds_read_b128 v[138:141], v203 offset:55360
	ds_read_b128 v[146:149], v203 offset:55392
	ds_read_b128 v[158:161], v203 offset:59968
	ds_read_b128 v[150:153], v203 offset:60000
	ds_read_b128 v[170:173], v235 offset:64
	ds_read_b128 v[162:165], v235 offset:96
	ds_read_b128 v[174:177], v235 offset:4672
	ds_read_b128 v[166:169], v235 offset:4704
	s_waitcnt lgkmcnt(0)
	s_barrier
	v_mfma_f32_32x32x16_bf16 v[48:63], v[116:119], v[124:127], v[48:63]
	v_mfma_f32_32x32x16_bf16 v[32:47], v[116:119], v[154:157], v[32:47]
	s_waitcnt vmcnt(11)
	ds_write_b128 v201, v[64:67]
	v_mfma_f32_32x32x16_bf16 v[16:31], v[134:137], v[124:127], v[16:31]
	v_mfma_f32_32x32x16_bf16 v[0:15], v[134:137], v[154:157], v[0:15]
	s_waitcnt vmcnt(10)
	ds_write_b128 v201, v[68:71] offset:9216
	v_mfma_f32_32x32x16_bf16 v[48:63], v[112:115], v[120:123], v[48:63]
	v_mfma_f32_32x32x16_bf16 v[32:47], v[112:115], v[142:145], v[32:47]
	s_waitcnt vmcnt(9)
	ds_write_b128 v201, v[84:87] offset:18432
	v_mfma_f32_32x32x16_bf16 v[16:31], v[130:133], v[120:123], v[16:31]
	v_mfma_f32_32x32x16_bf16 v[0:15], v[130:133], v[142:145], v[0:15]
	s_waitcnt vmcnt(8)
	ds_write_b128 v201, v[72:75] offset:27648
	v_mfma_f32_32x32x16_bf16 v[48:63], v[138:141], v[170:173], v[48:63]
	v_mfma_f32_32x32x16_bf16 v[32:47], v[138:141], v[174:177], v[32:47]
	s_waitcnt vmcnt(7)
	ds_write_b128 v201, v[96:99] offset:36864
	v_mfma_f32_32x32x16_bf16 v[16:31], v[158:161], v[170:173], v[16:31]
	v_mfma_f32_32x32x16_bf16 v[0:15], v[158:161], v[174:177], v[0:15]
	s_waitcnt vmcnt(6)
	ds_write_b128 v201, v[100:103] offset:46080
	v_mfma_f32_32x32x16_bf16 v[48:63], v[146:149], v[162:165], v[48:63]
	v_mfma_f32_32x32x16_bf16 v[32:47], v[146:149], v[166:169], v[32:47]
	v_mfma_f32_32x32x16_bf16 v[16:31], v[150:153], v[162:165], v[16:31]
	v_mfma_f32_32x32x16_bf16 v[0:15], v[150:153], v[166:169], v[0:15]
	s_waitcnt lgkmcnt(0)
	s_barrier
	ds_read_b128 v[116:119], v203
	ds_read_b128 v[112:115], v203 offset:32
	ds_read_b128 v[124:127], v204 offset:36864
	ds_read_b128 v[120:123], v204 offset:36896
	ds_read_b128 v[134:137], v203 offset:4608
	ds_read_b128 v[130:133], v203 offset:4640
	ds_read_b128 v[154:157], v204 offset:41472
	ds_read_b128 v[142:145], v204 offset:41504
	ds_read_b128 v[138:141], v203 offset:64
	ds_read_b128 v[146:149], v203 offset:96
	ds_read_b128 v[158:161], v203 offset:4672
	ds_read_b128 v[150:153], v203 offset:4704
	ds_read_b128 v[170:173], v204 offset:36928
	ds_read_b128 v[162:165], v204 offset:36960
	ds_read_b128 v[174:177], v204 offset:41536
	ds_read_b128 v[166:169], v204 offset:41568
	s_waitcnt lgkmcnt(0)
	s_barrier
	v_mfma_f32_32x32x16_bf16 v[48:63], v[116:119], v[124:127], v[48:63]
	v_mfma_f32_32x32x16_bf16 v[32:47], v[116:119], v[154:157], v[32:47]
	s_waitcnt vmcnt(5)
	ds_write_b128 v201, v[76:79] offset:55296
	v_mfma_f32_32x32x16_bf16 v[16:31], v[134:137], v[124:127], v[16:31]
	v_mfma_f32_32x32x16_bf16 v[0:15], v[134:137], v[154:157], v[0:15]
	s_waitcnt vmcnt(4)
	ds_write_b128 v201, v[80:83] offset:64512
	v_mfma_f32_32x32x16_bf16 v[48:63], v[112:115], v[120:123], v[48:63]
	v_mfma_f32_32x32x16_bf16 v[32:47], v[112:115], v[142:145], v[32:47]
	s_waitcnt vmcnt(3)
	ds_write_b128 v205, v[88:91] offset:18432
	v_mfma_f32_32x32x16_bf16 v[16:31], v[130:133], v[120:123], v[16:31]
	v_mfma_f32_32x32x16_bf16 v[0:15], v[130:133], v[142:145], v[0:15]
	s_waitcnt vmcnt(2)
	ds_write_b128 v205, v[92:95] offset:27648
	v_mfma_f32_32x32x16_bf16 v[48:63], v[138:141], v[170:173], v[48:63]
	v_mfma_f32_32x32x16_bf16 v[32:47], v[138:141], v[174:177], v[32:47]
	s_waitcnt vmcnt(1)
	ds_write_b128 v234, v[104:107]
	v_mfma_f32_32x32x16_bf16 v[16:31], v[158:161], v[170:173], v[16:31]
	v_mfma_f32_32x32x16_bf16 v[0:15], v[158:161], v[174:177], v[0:15]
	s_waitcnt vmcnt(0)
	ds_write_b128 v234, v[108:111] offset:9216
	v_mfma_f32_32x32x16_bf16 v[48:63], v[146:149], v[162:165], v[48:63]
	v_mfma_f32_32x32x16_bf16 v[32:47], v[146:149], v[166:169], v[32:47]
	v_mfma_f32_32x32x16_bf16 v[16:31], v[150:153], v[162:165], v[16:31]
	v_mfma_f32_32x32x16_bf16 v[0:15], v[150:153], v[166:169], v[0:15]
	s_waitcnt lgkmcnt(0)
	s_barrier
	ds_read_b128 v[116:119], v203 offset:55296
	ds_read_b128 v[112:115], v203 offset:55328
	ds_read_b128 v[124:127], v235
	ds_read_b128 v[120:123], v235 offset:32
	ds_read_b128 v[134:137], v203 offset:59904
	ds_read_b128 v[130:133], v203 offset:59936
	ds_read_b128 v[154:157], v235 offset:4608
	ds_read_b128 v[142:145], v235 offset:4640
	ds_read_b128 v[138:141], v203 offset:55360
	ds_read_b128 v[146:149], v203 offset:55392
	ds_read_b128 v[158:161], v203 offset:59968
	ds_read_b128 v[150:153], v203 offset:60000
	ds_read_b128 v[170:173], v235 offset:64
	ds_read_b128 v[162:165], v235 offset:96
	ds_read_b128 v[174:177], v235 offset:4672
	ds_read_b128 v[166:169], v235 offset:4704
	s_waitcnt lgkmcnt(0)
	s_barrier
	v_mfma_f32_32x32x16_bf16 v[48:63], v[116:119], v[124:127], v[48:63]
	v_mfma_f32_32x32x16_bf16 v[32:47], v[116:119], v[154:157], v[32:47]
	v_mfma_f32_32x32x16_bf16 v[16:31], v[134:137], v[124:127], v[16:31]
	v_mfma_f32_32x32x16_bf16 v[0:15], v[134:137], v[154:157], v[0:15]
	v_mfma_f32_32x32x16_bf16 v[48:63], v[112:115], v[120:123], v[48:63]
	v_mfma_f32_32x32x16_bf16 v[32:47], v[112:115], v[142:145], v[32:47]
	v_mfma_f32_32x32x16_bf16 v[16:31], v[130:133], v[120:123], v[16:31]
	v_mfma_f32_32x32x16_bf16 v[0:15], v[130:133], v[142:145], v[0:15]
	v_mfma_f32_32x32x16_bf16 v[48:63], v[138:141], v[170:173], v[48:63]
	v_mfma_f32_32x32x16_bf16 v[32:47], v[138:141], v[174:177], v[32:47]
	v_mfma_f32_32x32x16_bf16 v[16:31], v[158:161], v[170:173], v[16:31]
	v_mfma_f32_32x32x16_bf16 v[0:15], v[158:161], v[174:177], v[0:15]
	v_mfma_f32_32x32x16_bf16 v[48:63], v[146:149], v[162:165], v[48:63]
	v_mfma_f32_32x32x16_bf16 v[32:47], v[146:149], v[166:169], v[32:47]
	v_mfma_f32_32x32x16_bf16 v[16:31], v[150:153], v[162:165], v[16:31]
	v_mfma_f32_32x32x16_bf16 v[0:15], v[150:153], v[166:169], v[0:15]
	s_waitcnt lgkmcnt(0)
	s_barrier
	s_waitcnt lgkmcnt(0)
	s_barrier
	s_branch .LBB0_1240
